# rg_phase item loops: next-item prefetch no longer waited at the item head; drained before the item's final stores
# baseline (speedup 1.0000x reference)
.LBB0_266:
	s_waitcnt vmcnt(0)
	v_mov_b32_e32 v68, 0
	s_mov_b32 s10, s94
	s_mov_b32 s11, s3
	s_mov_b32 s69, s97
	v_mov_b32_e32 v69, v68
	v_mov_b32_e32 v70, v68
	v_mov_b32_e32 v71, v68
	v_mov_b32_e32 v72, v68
	v_mov_b32_e32 v73, v68
	v_mov_b32_e32 v74, v68
	v_mov_b32_e32 v75, v68
	v_mov_b32_e32 v100, v68
	v_mov_b32_e32 v101, v68
	v_mov_b32_e32 v102, v68
	v_mov_b32_e32 v103, v68
	v_mov_b32_e32 v104, v68
	v_mov_b32_e32 v105, v68
	v_mov_b32_e32 v106, v68
	v_mov_b32_e32 v107, v68
	s_branch .LBB0_269

.LBB0_279:
	v_cndmask_b32_e64 v0, 0, 1, s[30:31]
	v_cmp_ne_u32_e64 s[6:7], 1, v0
	s_andn2_b64 vcc, exec, s[30:31]
	s_cbranch_vccnz .LBB0_281
	s_waitcnt vmcnt(4)
	v_mov_b32_e32 v82, v204
	s_and_b32 s2, s69, 7
	s_lshl_b32 s26, s2, 8
	v_lshlrev_b32_e32 v0, 5, v82
	v_and_b32_e32 v0, 0xe0, v0
	v_or_b32_e32 v0, s26, v0
	v_lshl_add_u64 v[2:3], s[12:13], 0, v[0:1]
	v_add_co_u32_e32 v2, vcc, s1, v2
	v_ashrrev_i32_e32 v60, 7, v82
	global_load_dwordx4 v[4:7], v0, s[12:13] offset:2064
	global_load_dwordx4 v[8:11], v0, s[12:13] offset:2048
	v_addc_co_u32_e32 v3, vcc, 0, v3, vcc
	global_load_dwordx4 v[12:15], v0, s[38:39]
	global_load_dwordx4 v[16:19], v0, s[48:49]
	global_load_dwordx4 v[20:23], v[2:3], off offset:16
	global_load_dwordx4 v[36:39], v[2:3], off offset:2064
	global_load_dwordx4 v[28:31], v0, s[12:13] offset:16
	global_load_dwordx4 v[44:47], v0, s[14:15] offset:16
	global_load_dwordx4 v[32:35], v0, s[12:13]
	global_load_dwordx4 v[48:51], v0, s[14:15]
	v_lshl_or_b32 v2, v60, 3, s2
	v_lshlrev_b32_e32 v60, 11, v60
	v_lshrrev_b32_e32 v0, 1, v82
	v_ashrrev_i32_e32 v3, 31, v2
	v_and_b32_e32 v76, 0x800, v60
	v_mov_b32_e32 v77, v1
	s_waitcnt vmcnt(13)
	v_and_b32_e32 v84, 32, v0
	v_lshlrev_b64 v[2:3], 13, v[2:3]
	v_lshl_add_u64 v[60:61], s[36:37], 0, v[76:77]
	v_lshl_add_u64 v[2:3], s[50:51], 0, v[2:3]
	v_and_b32_e32 v0, 48, v82
	v_lshl_add_u64 v[78:79], v[60:61], 0, s[26:27]
	v_and_or_b32 v60, v82, 15, v84
	v_lshl_add_u64 v[2:3], v[2:3], 0, v[0:1]
	v_lshlrev_b32_e32 v80, 7, v60
	v_mov_b32_e32 v81, v1
	v_lshl_add_u64 v[64:65], v[2:3], 0, v[80:81]
	v_mov_b32_e32 v81, s25
	v_mov_b32_e32 v83, s19
	v_cmp_gt_u32_e32 vcc, s45, v82
	v_mov_b32_e32 v82, s18
	v_lshl_or_b32 v0, v84, 2, v0
	v_cndmask_b32_e32 v83, v81, v83, vcc
	v_mov_b32_e32 v81, s24
	v_cndmask_b32_e32 v82, v81, v82, vcc
	v_lshl_add_u64 v[76:77], v[82:83], 0, v[76:77]
	v_lshl_add_u64 v[76:77], v[76:77], 0, s[26:27]
	s_waitcnt vmcnt(12)
	v_lshl_add_u64 v[88:89], v[76:77], 0, v[0:1]
	s_waitcnt vmcnt(10)
	v_lshl_add_u64 v[96:97], v[78:79], 0, v[0:1]
	v_or_b32_e32 v0, 0x800, v80
	v_lshl_add_u64 v[2:3], v[2:3], 0, v[0:1]
	global_load_dwordx4 v[60:63], v[64:65], off
	s_nop 0
	global_load_dwordx4 v[64:67], v[64:65], off offset:64
	s_nop 0
	global_load_dwordx4 v[76:79], v[2:3], off
	global_load_dwordx4 v[80:83], v[2:3], off offset:64
	global_load_dwordx4 v[84:87], v[88:89], off
	s_nop 0
	global_load_dwordx4 v[88:91], v[88:89], off offset:64
	s_nop 0
	global_load_dwordx4 v[92:95], v[96:97], off
	s_nop 0
	global_load_dwordx4 v[96:99], v[96:97], off offset:64
	s_waitcnt vmcnt(0)
.LBB0_281:
	v_mov_b32_e32 v0, v204
	s_nop 0
	v_and_b32_e32 v3, 0xffff0000, v40
	v_lshlrev_b32_e32 v2, 3, v0
	v_and_b32_e32 v116, 56, v2
	v_lshlrev_b32_e32 v2, 16, v40
	v_pk_fma_f32 v[2:3], v[32:33], v[2:3], v[48:49]
	v_lshlrev_b32_e32 v108, 16, v24
	v_and_b32_e32 v109, 0xffff0000, v24
	v_pk_fma_f32 v[2:3], v[8:9], v[108:109], v[2:3]
	v_lshlrev_b32_e32 v108, 16, v52
	v_and_b32_e32 v109, 0xffff0000, v52
	v_pk_fma_f32 v[2:3], v[12:13], v[108:109], v[2:3]
	v_lshlrev_b32_e32 v108, 16, v56
	v_and_b32_e32 v109, 0xffff0000, v56
	v_pk_fma_f32 v[108:109], v[16:17], v[108:109], v[2:3]
	v_lshlrev_b32_e32 v2, 16, v42
	v_and_b32_e32 v3, 0xffff0000, v42
	v_pk_fma_f32 v[2:3], v[28:29], v[2:3], v[44:45]
	v_lshlrev_b32_e32 v110, 16, v26
	v_and_b32_e32 v111, 0xffff0000, v26
	v_pk_fma_f32 v[2:3], v[4:5], v[110:111], v[2:3]
	v_lshlrev_b32_e32 v110, 16, v54
	v_and_b32_e32 v111, 0xffff0000, v54
	v_pk_fma_f32 v[2:3], v[20:21], v[110:111], v[2:3]
	v_lshlrev_b32_e32 v110, 16, v58
	v_and_b32_e32 v111, 0xffff0000, v58
	v_pk_fma_f32 v[112:113], v[36:37], v[110:111], v[2:3]
	v_lshlrev_b32_e32 v2, 16, v41
	v_and_b32_e32 v3, 0xffff0000, v41
	v_pk_fma_f32 v[2:3], v[34:35], v[2:3], v[50:51]
	v_lshlrev_b32_e32 v110, 16, v25
	v_and_b32_e32 v111, 0xffff0000, v25
	v_pk_fma_f32 v[2:3], v[10:11], v[110:111], v[2:3]
	v_lshlrev_b32_e32 v110, 16, v53
	v_and_b32_e32 v111, 0xffff0000, v53
	v_pk_fma_f32 v[2:3], v[14:15], v[110:111], v[2:3]
	v_lshlrev_b32_e32 v110, 16, v57
	v_and_b32_e32 v111, 0xffff0000, v57
	v_pk_fma_f32 v[110:111], v[18:19], v[110:111], v[2:3]
	v_lshlrev_b32_e32 v2, 16, v43
	v_and_b32_e32 v3, 0xffff0000, v43
	v_pk_fma_f32 v[2:3], v[30:31], v[2:3], v[46:47]
	v_lshlrev_b32_e32 v114, 16, v27
	v_and_b32_e32 v115, 0xffff0000, v27
	v_pk_fma_f32 v[2:3], v[6:7], v[114:115], v[2:3]
	v_lshlrev_b32_e32 v114, 16, v55
	v_and_b32_e32 v115, 0xffff0000, v55
	v_pk_fma_f32 v[2:3], v[22:23], v[114:115], v[2:3]
	v_lshlrev_b32_e32 v114, 16, v59
	v_and_b32_e32 v115, 0xffff0000, v59
	v_pk_fma_f32 v[114:115], v[38:39], v[114:115], v[2:3]
	v_ashrrev_i32_e32 v3, 3, v0
	v_lshl_add_u32 v117, v3, 8, 0
	v_lshl_add_u32 v118, v116, 2, v117
	ds_write_b128 v118, v[108:111]
	ds_write_b128 v118, v[112:115] offset:16
	v_cvt_pk_bf16_f32 v108, v108, v109
	v_cvt_pk_bf16_f32 v109, v110, v111
	v_cvt_pk_bf16_f32 v110, v112, v113
	v_mul_lo_u32 v3, v3, s67
	v_lshlrev_b32_e32 v112, 1, v116
	v_and_b32_e32 v127, 15, v0
	v_cvt_pk_bf16_f32 v111, v114, v115
	v_add3_u32 v3, v117, v3, v112
	v_and_b32_e32 v2, 48, v0
	ds_write_b128 v3, v[108:111] offset:16384
	v_mul_u32_u24_e32 v3, 0x90, v127
	v_add3_u32 v3, 0, v2, v3
	s_waitcnt lgkmcnt(0)
	s_barrier
	ds_read_b128 v[108:111], v3 offset:16384
	ds_read_b128 v[112:115], v3 offset:16448
	ds_read_b128 v[120:123], v3 offset:18688
	ds_read_b128 v[128:131], v3 offset:18752
	s_waitcnt lgkmcnt(1)
	v_mfma_f32_16x16x32_bf16 v[132:135], v[60:63], v[120:123], 0
	s_add_i32 s2, 0, 0xe400
	v_cmp_gt_u32_e32 vcc, s45, v0
	v_lshlrev_b32_e32 v127, 8, v127
	v_mfma_f32_16x16x32_bf16 v[136:139], v[76:79], v[120:123], 0
	ds_read_b128 v[120:123], v3 offset:20992
	ds_read_b128 v[140:143], v3 offset:21056
	v_mfma_f32_16x16x32_bf16 v[116:119], v[60:63], v[108:111], 0
	v_mfma_f32_16x16x32_bf16 v[108:111], v[76:79], v[108:111], 0
	s_waitcnt lgkmcnt(1)
	v_mfma_f32_16x16x32_bf16 v[144:147], v[60:63], v[120:123], 0
	v_mfma_f32_16x16x32_bf16 v[148:151], v[76:79], v[120:123], 0
	ds_read_b128 v[120:123], v3 offset:23296
	ds_read_b128 v[154:157], v3 offset:23360
	v_mov_b32_e32 v3, s2
	v_mfma_f32_16x16x32_bf16 v[166:169], v[64:67], v[112:115], v[116:119]
	s_waitcnt lgkmcnt(1)
	v_mfma_f32_16x16x32_bf16 v[158:161], v[60:63], v[120:123], 0
	v_mfma_f32_16x16x32_bf16 v[162:165], v[76:79], v[120:123], 0
	v_mfma_f32_16x16x32_bf16 v[120:123], v[80:83], v[112:115], v[108:111]
	v_mfma_f32_16x16x32_bf16 v[132:135], v[64:67], v[128:131], v[132:135]
	v_mfma_f32_16x16x32_bf16 v[116:119], v[80:83], v[128:131], v[136:139]
	s_nop 5
	v_add_f32_e32 v122, v90, v122
	v_mul_f32_e32 v122, 0xbfb8aa3b, v122
	v_exp_f32_e32 v122, v122
	v_mfma_f32_16x16x32_bf16 v[128:131], v[64:67], v[140:143], v[144:147]
	v_add_f32_e32 v123, v91, v123
	v_mul_f32_e32 v123, 0xbfb8aa3b, v123
	v_exp_f32_e32 v123, v123
	v_mfma_f32_16x16x32_bf16 v[112:115], v[80:83], v[140:143], v[148:151]
	v_mov_b32_e32 v140, s73
	v_cndmask_b32_e32 v3, v3, v140, vcc
	v_lshlrev_b32_e32 v140, 7, v0
	v_and_b32_e32 v140, 0x4000, v140
	v_add3_u32 v3, v3, v140, v127
	v_add_f32_e32 v140, v84, v166
	v_mul_f32_e32 v140, 0xbfb8aa3b, v140
	v_add_f32_e32 v141, v85, v167
	v_exp_f32_e32 v140, v140
	v_mul_f32_e32 v141, 0xbfb8aa3b, v141
	v_exp_f32_e32 v141, v141
	v_lshlrev_b32_e32 v127, 1, v0
	v_and_b32_e32 v127, 0x80, v127
	v_add_f32_e32 v140, 1.0, v140
	v_rcp_f32_e32 v140, v140
	v_add3_u32 v2, v3, v127, v2
	v_add_f32_e32 v3, 1.0, v141
	v_add_f32_e32 v141, v86, v168
	v_mul_f32_e32 v141, 0xbfb8aa3b, v141
	v_rcp_f32_e32 v3, v3
	v_exp_f32_e32 v141, v141
	v_add_f32_e32 v142, v87, v169
	v_mul_f32_e32 v142, 0xbfb8aa3b, v142
	v_mul_f32_e32 v127, 0xc1000000, v140
	v_exp_f32_e32 v142, v142
	v_mul_f32_e32 v127, v92, v127
	v_cndmask_b32_e32 v140, v140, v127, vcc
	v_mul_f32_e32 v127, 0xc1000000, v3
	v_add_f32_e32 v141, 1.0, v141
	v_mul_f32_e32 v127, v93, v127
	v_rcp_f32_e32 v143, v141
	v_cndmask_b32_e32 v141, v3, v127, vcc
	v_add_f32_e32 v3, 1.0, v142
	v_rcp_f32_e32 v3, v3
	v_mul_f32_e32 v127, 0xc1000000, v143
	v_mul_f32_e32 v127, v94, v127
	v_cndmask_b32_e32 v142, v143, v127, vcc
	v_mul_f32_e32 v127, 0xc1000000, v3
	v_mul_f32_e32 v127, v95, v127
	v_cndmask_b32_e32 v143, v3, v127, vcc
	v_add_f32_e32 v3, v84, v132
	v_mul_f32_e32 v3, 0xbfb8aa3b, v3
	v_exp_f32_e32 v3, v3
	v_add_f32_e32 v127, v85, v133
	v_mul_f32_e32 v127, 0xbfb8aa3b, v127
	v_exp_f32_e32 v127, v127
	v_add_f32_e32 v3, 1.0, v3
	v_rcp_f32_e32 v3, v3
	v_add_f32_e32 v133, v86, v134
	v_add_f32_e32 v127, 1.0, v127
	v_mul_f32_e32 v133, 0xbfb8aa3b, v133
	v_rcp_f32_e32 v127, v127
	v_exp_f32_e32 v133, v133
	v_add_f32_e32 v134, v87, v135
	v_mul_f32_e32 v134, 0xbfb8aa3b, v134
	v_mul_f32_e32 v132, 0xc1000000, v3
	v_exp_f32_e32 v134, v134
	v_mul_f32_e32 v132, v92, v132
	v_cndmask_b32_e32 v132, v3, v132, vcc
	v_mul_f32_e32 v3, 0xc1000000, v127
	v_add_f32_e32 v133, 1.0, v133
	v_mul_f32_e32 v3, v93, v3
	v_rcp_f32_e32 v135, v133
	v_cndmask_b32_e32 v133, v127, v3, vcc
	v_add_f32_e32 v3, 1.0, v134
	v_rcp_f32_e32 v3, v3
	v_mul_f32_e32 v127, 0xc1000000, v135
	v_mul_f32_e32 v127, v94, v127
	v_cndmask_b32_e32 v134, v135, v127, vcc
	v_mul_f32_e32 v127, 0xc1000000, v3
	v_mul_f32_e32 v127, v95, v127
	v_cndmask_b32_e32 v135, v3, v127, vcc
	v_add_f32_e32 v3, v84, v128
	v_mul_f32_e32 v3, 0xbfb8aa3b, v3
	v_exp_f32_e32 v3, v3
	v_add_f32_e32 v127, v85, v129
	v_mul_f32_e32 v127, 0xbfb8aa3b, v127
	v_exp_f32_e32 v127, v127
	v_add_f32_e32 v3, 1.0, v3
	v_rcp_f32_e32 v3, v3
	v_add_f32_e32 v129, v86, v130
	v_add_f32_e32 v127, 1.0, v127
	v_mul_f32_e32 v129, 0xbfb8aa3b, v129
	v_rcp_f32_e32 v127, v127
	v_exp_f32_e32 v129, v129
	v_add_f32_e32 v130, v87, v131
	v_mul_f32_e32 v130, 0xbfb8aa3b, v130
	v_mul_f32_e32 v128, 0xc1000000, v3
	v_exp_f32_e32 v130, v130
	v_mul_f32_e32 v128, v92, v128
	v_cndmask_b32_e32 v128, v3, v128, vcc
	v_mul_f32_e32 v3, 0xc1000000, v127
	v_add_f32_e32 v129, 1.0, v129
	v_mul_f32_e32 v3, v93, v3
	v_rcp_f32_e32 v131, v129
	v_cndmask_b32_e32 v129, v127, v3, vcc
	v_add_f32_e32 v3, 1.0, v130
	v_rcp_f32_e32 v3, v3
	s_waitcnt lgkmcnt(0)
	v_mfma_f32_16x16x32_bf16 v[136:139], v[64:67], v[154:157], v[158:161]
	v_mul_f32_e32 v127, 0xc1000000, v131
	v_mul_f32_e32 v127, v94, v127
	v_cndmask_b32_e32 v130, v131, v127, vcc
	v_mul_f32_e32 v127, 0xc1000000, v3
	v_mul_f32_e32 v127, v95, v127
	v_cndmask_b32_e32 v131, v3, v127, vcc
	s_nop 1
	v_add_f32_e32 v3, v84, v136
	v_mul_f32_e32 v3, 0xbfb8aa3b, v3
	v_exp_f32_e32 v3, v3
	v_add_f32_e32 v127, v85, v137
	v_mul_f32_e32 v127, 0xbfb8aa3b, v127
	v_exp_f32_e32 v127, v127
	v_add_f32_e32 v3, 1.0, v3
	v_rcp_f32_e32 v3, v3
	ds_write_b128 v2, v[128:131] offset:8192
	v_add_f32_e32 v129, v86, v138
	v_add_f32_e32 v127, 1.0, v127
	v_mul_f32_e32 v129, 0xbfb8aa3b, v129
	v_rcp_f32_e32 v127, v127
	v_exp_f32_e32 v129, v129
	v_add_f32_e32 v130, v87, v139
	v_mul_f32_e32 v130, 0xbfb8aa3b, v130
	v_mul_f32_e32 v128, 0xc1000000, v3
	v_exp_f32_e32 v130, v130
	v_mul_f32_e32 v128, v92, v128
	v_cndmask_b32_e32 v128, v3, v128, vcc
	v_mul_f32_e32 v3, 0xc1000000, v127
	v_add_f32_e32 v129, 1.0, v129
	v_mul_f32_e32 v3, v93, v3
	v_rcp_f32_e32 v131, v129
	v_cndmask_b32_e32 v129, v127, v3, vcc
	v_add_f32_e32 v3, 1.0, v130
	v_rcp_f32_e32 v3, v3
	v_mul_f32_e32 v127, 0xc1000000, v131
	v_mul_f32_e32 v127, v94, v127
	v_cndmask_b32_e32 v130, v131, v127, vcc
	v_mul_f32_e32 v127, 0xc1000000, v3
	v_mul_f32_e32 v127, v95, v127
	v_cndmask_b32_e32 v131, v3, v127, vcc
	v_add_f32_e32 v3, v88, v120
	v_mul_f32_e32 v3, 0xbfb8aa3b, v3
	v_exp_f32_e32 v3, v3
	v_add_f32_e32 v120, v89, v121
	v_mul_f32_e32 v120, 0xbfb8aa3b, v120
	v_exp_f32_e32 v120, v120
	v_add_f32_e32 v3, 1.0, v3
	v_rcp_f32_e32 v3, v3
	v_add_f32_e32 v122, 1.0, v122
	v_add_f32_e32 v120, 1.0, v120
	v_rcp_f32_e32 v121, v120
	v_mul_f32_e32 v120, 0xc1000000, v3
	v_mul_f32_e32 v120, v96, v120
	v_cndmask_b32_e32 v120, v3, v120, vcc
	v_mul_f32_e32 v3, 0xc1000000, v121
	v_mul_f32_e32 v3, v97, v3
	v_rcp_f32_e32 v122, v122
	v_cndmask_b32_e32 v121, v121, v3, vcc
	v_add_f32_e32 v3, 1.0, v123
	v_rcp_f32_e32 v3, v3
	v_mul_f32_e32 v123, 0xc1000000, v122
	v_mul_f32_e32 v123, v98, v123
	v_cndmask_b32_e32 v122, v122, v123, vcc
	v_mul_f32_e32 v123, 0xc1000000, v3
	v_mul_f32_e32 v123, v99, v123
	v_cndmask_b32_e32 v123, v3, v123, vcc
	v_add_f32_e32 v3, v88, v116
	v_mul_f32_e32 v3, 0xbfb8aa3b, v3
	v_exp_f32_e32 v3, v3
	v_add_f32_e32 v116, v89, v117
	v_mul_f32_e32 v116, 0xbfb8aa3b, v116
	v_exp_f32_e32 v116, v116
	v_add_f32_e32 v3, 1.0, v3
	v_rcp_f32_e32 v3, v3
	v_add_f32_e32 v118, v90, v118
	v_add_f32_e32 v116, 1.0, v116
	v_mul_f32_e32 v118, 0xbfb8aa3b, v118
	v_rcp_f32_e32 v117, v116
	v_exp_f32_e32 v118, v118
	v_add_f32_e32 v119, v91, v119
	v_mul_f32_e32 v119, 0xbfb8aa3b, v119
	v_mul_f32_e32 v116, 0xc1000000, v3
	v_exp_f32_e32 v119, v119
	v_mul_f32_e32 v116, v96, v116
	v_cndmask_b32_e32 v116, v3, v116, vcc
	v_mul_f32_e32 v3, 0xc1000000, v117
	v_add_f32_e32 v118, 1.0, v118
	v_mul_f32_e32 v3, v97, v3
	v_rcp_f32_e32 v118, v118
	v_cndmask_b32_e32 v117, v117, v3, vcc
	v_add_f32_e32 v3, 1.0, v119
	v_rcp_f32_e32 v3, v3
	v_mul_f32_e32 v119, 0xc1000000, v118
	v_mul_f32_e32 v119, v98, v119
	v_cndmask_b32_e32 v118, v118, v119, vcc
	v_mul_f32_e32 v119, 0xc1000000, v3
	v_mul_f32_e32 v119, v99, v119
	v_cndmask_b32_e32 v119, v3, v119, vcc
	v_add_f32_e32 v3, v88, v112
	v_mul_f32_e32 v3, 0xbfb8aa3b, v3
	v_exp_f32_e32 v3, v3
	v_add_f32_e32 v112, v89, v113
	v_mul_f32_e32 v112, 0xbfb8aa3b, v112
	v_exp_f32_e32 v112, v112
	v_add_f32_e32 v3, 1.0, v3
	v_rcp_f32_e32 v3, v3
	v_add_f32_e32 v114, v90, v114
	v_add_f32_e32 v112, 1.0, v112
	v_mul_f32_e32 v114, 0xbfb8aa3b, v114
	v_rcp_f32_e32 v113, v112
	v_exp_f32_e32 v114, v114
	v_add_f32_e32 v115, v91, v115
	v_mul_f32_e32 v115, 0xbfb8aa3b, v115
	v_mul_f32_e32 v112, 0xc1000000, v3
	v_exp_f32_e32 v115, v115
	v_mul_f32_e32 v112, v96, v112
	v_cndmask_b32_e32 v112, v3, v112, vcc
	v_mul_f32_e32 v3, 0xc1000000, v113
	v_add_f32_e32 v114, 1.0, v114
	v_mul_f32_e32 v3, v97, v3
	v_rcp_f32_e32 v114, v114
	v_cndmask_b32_e32 v113, v113, v3, vcc
	v_add_f32_e32 v3, 1.0, v115
	v_rcp_f32_e32 v3, v3
	v_mfma_f32_16x16x32_bf16 v[108:111], v[80:83], v[154:157], v[162:165]
	v_mul_f32_e32 v115, 0xc1000000, v114
	v_mul_f32_e32 v115, v98, v115
	v_cndmask_b32_e32 v114, v114, v115, vcc
	v_mul_f32_e32 v115, 0xc1000000, v3
	v_mul_f32_e32 v115, v99, v115
	v_cndmask_b32_e32 v115, v3, v115, vcc
	s_nop 1
	v_add_f32_e32 v3, v88, v108
	v_mul_f32_e32 v3, 0xbfb8aa3b, v3
	v_exp_f32_e32 v3, v3
	v_add_f32_e32 v108, v89, v109
	v_mul_f32_e32 v108, 0xbfb8aa3b, v108
	v_exp_f32_e32 v108, v108
	v_add_f32_e32 v3, 1.0, v3
	v_rcp_f32_e32 v3, v3
	v_add_f32_e32 v110, v90, v110
	v_add_f32_e32 v108, 1.0, v108
	v_mul_f32_e32 v110, 0xbfb8aa3b, v110
	v_rcp_f32_e32 v109, v108
	v_exp_f32_e32 v110, v110
	v_add_f32_e32 v111, v91, v111
	v_mul_f32_e32 v111, 0xbfb8aa3b, v111
	v_mul_f32_e32 v108, 0xc1000000, v3
	v_exp_f32_e32 v111, v111
	v_mul_f32_e32 v108, v96, v108
	v_cndmask_b32_e32 v108, v3, v108, vcc
	v_mul_f32_e32 v3, 0xc1000000, v109
	v_add_f32_e32 v110, 1.0, v110
	v_mul_f32_e32 v3, v97, v3
	v_rcp_f32_e32 v110, v110
	v_cndmask_b32_e32 v109, v109, v3, vcc
	v_add_f32_e32 v3, 1.0, v111
	v_rcp_f32_e32 v3, v3
	v_mul_f32_e32 v111, 0xc1000000, v110
	v_mul_f32_e32 v111, v98, v111
	v_cndmask_b32_e32 v110, v110, v111, vcc
	v_mul_f32_e32 v111, 0xc1000000, v3
	v_mul_f32_e32 v111, v99, v111
	v_cndmask_b32_e32 v111, v3, v111, vcc
	ds_write_b128 v2, v[108:111] offset:12352
	v_lshlrev_b32_e32 v3, 2, v0
	v_lshlrev_b32_e32 v108, 4, v0
	ds_write_b128 v2, v[140:143]
	ds_write_b128 v2, v[132:135] offset:4096
	ds_write_b128 v2, v[128:131] offset:12288
	ds_write_b128 v2, v[120:123] offset:64
	ds_write_b128 v2, v[116:119] offset:4160
	ds_write_b128 v2, v[112:115] offset:8256
	v_and_b32_e32 v2, 60, v3
	v_and_b32_e32 v109, 0xffffc000, v108
	v_lshlrev_b32_e32 v2, 2, v2
	v_add_u32_e32 v109, 0, v109
	v_and_b32_e32 v108, 0x3f00, v108
	v_add3_u32 v128, v109, v108, v2
	s_waitcnt lgkmcnt(0)
	s_barrier
	ds_read_b128 v[120:123], v128 offset:25600
	ds_read_b128 v[112:115], v128 offset:58368
	v_add_u32_e32 v127, 0, v2
	v_add_u32_e32 v129, v127, v108
	ds_read_b128 v[116:119], v129
	s_waitcnt lgkmcnt(2)
	v_mul_f32_e32 v108, 0x3fb8aa3b, v120
	v_exp_f32_e32 v108, v108
	v_add_f32_e32 v109, v120, v120
	v_cmp_nlt_f32_e32 vcc, s75, v109
	s_and_saveexec_b64 s[8:9], vcc
	s_xor_b64 s[8:9], exec, s[8:9]
	v_fma_f32 v120, -v108, v108, 1.0
	s_andn2_saveexec_b64 s[8:9], s[8:9]
	v_fmamk_f32 v110, v109, 0x3c088889, v125
	v_fmaak_f32 v110, v109, v110, 0x3e2aaaab
	v_fma_f32 v110, v109, v110, 0.5
	v_fma_f32 v110, v109, v110, 1.0
	v_mul_f32_e64 v120, v110, -v109
	s_or_b64 exec, exec, s[8:9]
	v_mul_f32_e32 v109, 0x3fb8aa3b, v121
	v_exp_f32_e32 v109, v109
	v_add_f32_e32 v110, v121, v121
	v_cmp_nlt_f32_e32 vcc, s75, v110
	s_and_saveexec_b64 s[8:9], vcc
	s_xor_b64 s[8:9], exec, s[8:9]
	v_fma_f32 v121, -v109, v109, 1.0
	s_andn2_saveexec_b64 s[8:9], s[8:9]
	v_fmamk_f32 v111, v110, 0x3c088889, v125
	v_fmaak_f32 v111, v110, v111, 0x3e2aaaab
	v_fma_f32 v111, v110, v111, 0.5
	v_fma_f32 v111, v110, v111, 1.0
	v_mul_f32_e64 v121, v111, -v110
	s_or_b64 exec, exec, s[8:9]
	v_mul_f32_e32 v110, 0x3fb8aa3b, v122
	v_exp_f32_e32 v110, v110
	v_add_f32_e32 v111, v122, v122
	v_cmp_nlt_f32_e32 vcc, s75, v111
	s_and_saveexec_b64 s[8:9], vcc
	s_xor_b64 s[8:9], exec, s[8:9]
	v_fma_f32 v122, -v110, v110, 1.0
	s_andn2_saveexec_b64 s[8:9], s[8:9]
	v_fmamk_f32 v122, v111, 0x3c088889, v125
	v_fmaak_f32 v122, v111, v122, 0x3e2aaaab
	v_fma_f32 v122, v111, v122, 0.5
	v_fma_f32 v122, v111, v122, 1.0
	v_mul_f32_e64 v122, v122, -v111
	s_or_b64 exec, exec, s[8:9]
	v_mul_f32_e32 v111, 0x3fb8aa3b, v123
	v_exp_f32_e32 v111, v111
	v_add_f32_e32 v130, v123, v123
	v_cmp_nlt_f32_e32 vcc, s75, v130
	s_and_saveexec_b64 s[8:9], vcc
	s_xor_b64 s[8:9], exec, s[8:9]
	v_fma_f32 v123, -v111, v111, 1.0
	s_andn2_saveexec_b64 s[8:9], s[8:9]
	v_fmamk_f32 v123, v130, 0x3c088889, v125
	v_fmaak_f32 v123, v130, v123, 0x3e2aaaab
	v_fma_f32 v123, v130, v123, 0.5
	v_fma_f32 v123, v130, v123, 1.0
	v_mul_f32_e64 v123, v123, -v130
	s_or_b64 exec, exec, s[8:9]
	v_max_f32_e32 v120, v120, v120
	v_max_f32_e32 v120, 0, v120
	v_sqrt_f32_e32 v120, v120
	v_max_f32_e32 v121, v121, v121
	v_max_f32_e32 v121, 0, v121
	v_sqrt_f32_e32 v121, v121
	s_waitcnt lgkmcnt(1)
	v_mul_f32_e32 v112, v112, v120
	s_waitcnt lgkmcnt(0)
	v_mul_f32_e32 v112, v116, v112
	v_max_f32_e32 v116, v122, v122
	v_max_f32_e32 v120, v123, v123
	v_max_f32_e32 v116, 0, v116
	v_max_f32_e32 v120, 0, v120
	v_sqrt_f32_e32 v116, v116
	v_sqrt_f32_e32 v120, v120
	v_mul_f32_e32 v113, v113, v121
	v_mul_f32_e32 v113, v117, v113
	v_mul_f32_e32 v114, v114, v116
	v_mul_f32_e32 v115, v115, v120
	v_mul_f32_e32 v114, v118, v114
	v_mul_f32_e32 v115, v119, v115
	ds_write_b128 v128, v[108:111] offset:25600
	ds_write_b128 v128, v[112:115] offset:58368
	v_add_u32_e32 v108, 0x800, v3
	v_and_b32_e32 v109, 0x3ffff000, v108
	v_and_b32_e32 v108, 0xfc0, v108
	v_lshl_add_u32 v109, v109, 2, 0
	v_lshlrev_b32_e32 v108, 2, v108
	v_add3_u32 v130, v109, v108, v2
	ds_read_b128 v[120:123], v130 offset:25600
	ds_read_b128 v[112:115], v130 offset:58368
	v_add_u32_e32 v108, v127, v108
	ds_read_b128 v[116:119], v108
	s_waitcnt lgkmcnt(2)
	v_mul_f32_e32 v108, 0x3fb8aa3b, v120
	v_exp_f32_e32 v108, v108
	v_add_f32_e32 v109, v120, v120
	v_cmp_nlt_f32_e32 vcc, s75, v109
	s_and_saveexec_b64 s[8:9], vcc
	s_xor_b64 s[8:9], exec, s[8:9]
	v_fma_f32 v120, -v108, v108, 1.0
	s_andn2_saveexec_b64 s[8:9], s[8:9]
	v_fmamk_f32 v110, v109, 0x3c088889, v125
	v_fmaak_f32 v110, v109, v110, 0x3e2aaaab
	v_fma_f32 v110, v109, v110, 0.5
	v_fma_f32 v110, v109, v110, 1.0
	v_mul_f32_e64 v120, v110, -v109
	s_or_b64 exec, exec, s[8:9]
	v_mul_f32_e32 v109, 0x3fb8aa3b, v121
	v_exp_f32_e32 v109, v109
	v_add_f32_e32 v110, v121, v121
	v_cmp_nlt_f32_e32 vcc, s75, v110
	s_and_saveexec_b64 s[8:9], vcc
	s_xor_b64 s[8:9], exec, s[8:9]
	v_fma_f32 v121, -v109, v109, 1.0
	s_andn2_saveexec_b64 s[8:9], s[8:9]
	v_fmamk_f32 v111, v110, 0x3c088889, v125
	v_fmaak_f32 v111, v110, v111, 0x3e2aaaab
	v_fma_f32 v111, v110, v111, 0.5
	v_fma_f32 v111, v110, v111, 1.0
	v_mul_f32_e64 v121, v111, -v110
	s_or_b64 exec, exec, s[8:9]
	v_mul_f32_e32 v110, 0x3fb8aa3b, v122
	v_exp_f32_e32 v110, v110
	v_add_f32_e32 v111, v122, v122
	v_cmp_nlt_f32_e32 vcc, s75, v111
	s_and_saveexec_b64 s[8:9], vcc
	s_xor_b64 s[8:9], exec, s[8:9]
	v_fma_f32 v122, -v110, v110, 1.0
	s_andn2_saveexec_b64 s[8:9], s[8:9]
	v_fmamk_f32 v122, v111, 0x3c088889, v125
	v_fmaak_f32 v122, v111, v122, 0x3e2aaaab
	v_fma_f32 v122, v111, v122, 0.5
	v_fma_f32 v122, v111, v122, 1.0
	v_mul_f32_e64 v122, v122, -v111
	s_or_b64 exec, exec, s[8:9]
	v_mul_f32_e32 v111, 0x3fb8aa3b, v123
	v_exp_f32_e32 v111, v111
	v_add_f32_e32 v131, v123, v123
	v_cmp_nlt_f32_e32 vcc, s75, v131
	s_and_saveexec_b64 s[8:9], vcc
	s_xor_b64 s[8:9], exec, s[8:9]
	v_fma_f32 v123, -v111, v111, 1.0
	s_andn2_saveexec_b64 s[8:9], s[8:9]
	v_fmamk_f32 v123, v131, 0x3c088889, v125
	v_fmaak_f32 v123, v131, v123, 0x3e2aaaab
	v_fma_f32 v123, v131, v123, 0.5
	v_fma_f32 v123, v131, v123, 1.0
	v_mul_f32_e64 v123, v123, -v131
	s_or_b64 exec, exec, s[8:9]
	v_max_f32_e32 v120, v120, v120
	v_max_f32_e32 v120, 0, v120
	v_sqrt_f32_e32 v120, v120
	v_max_f32_e32 v121, v121, v121
	v_max_f32_e32 v121, 0, v121
	v_sqrt_f32_e32 v121, v121
	s_waitcnt lgkmcnt(1)
	v_mul_f32_e32 v112, v112, v120
	s_waitcnt lgkmcnt(0)
	v_mul_f32_e32 v112, v116, v112
	v_max_f32_e32 v116, v122, v122
	v_max_f32_e32 v120, v123, v123
	v_max_f32_e32 v116, 0, v116
	v_max_f32_e32 v120, 0, v120
	v_sqrt_f32_e32 v116, v116
	v_sqrt_f32_e32 v120, v120
	v_mul_f32_e32 v113, v113, v121
	v_mul_f32_e32 v113, v117, v113
	v_mul_f32_e32 v114, v114, v116
	v_mul_f32_e32 v115, v115, v120
	v_mul_f32_e32 v114, v118, v114
	v_mul_f32_e32 v115, v119, v115
	ds_write_b128 v130, v[108:111] offset:25600
	ds_write_b128 v130, v[112:115] offset:58368
	ds_read_b128 v[120:123], v128 offset:41984
	v_add_u32_e32 v130, 0xe400, v128
	ds_read_b128 v[112:115], v130 offset:16384
	ds_read_b128 v[116:119], v129
	s_waitcnt lgkmcnt(2)
	v_mul_f32_e32 v108, 0x3fb8aa3b, v120
	v_exp_f32_e32 v108, v108
	v_add_f32_e32 v109, v120, v120
	v_cmp_nlt_f32_e32 vcc, s75, v109
	s_and_saveexec_b64 s[8:9], vcc
	s_xor_b64 s[8:9], exec, s[8:9]
	v_fma_f32 v120, -v108, v108, 1.0
	s_andn2_saveexec_b64 s[8:9], s[8:9]
	v_fmamk_f32 v110, v109, 0x3c088889, v125
	v_fmaak_f32 v110, v109, v110, 0x3e2aaaab
	v_fma_f32 v110, v109, v110, 0.5
	v_fma_f32 v110, v109, v110, 1.0
	v_mul_f32_e64 v120, v110, -v109
	s_or_b64 exec, exec, s[8:9]
	v_mul_f32_e32 v109, 0x3fb8aa3b, v121
	v_exp_f32_e32 v109, v109
	v_add_f32_e32 v110, v121, v121
	v_cmp_nlt_f32_e32 vcc, s75, v110
	s_and_saveexec_b64 s[8:9], vcc
	s_xor_b64 s[8:9], exec, s[8:9]
	v_fma_f32 v121, -v109, v109, 1.0
	s_andn2_saveexec_b64 s[8:9], s[8:9]
	v_fmamk_f32 v111, v110, 0x3c088889, v125
	v_fmaak_f32 v111, v110, v111, 0x3e2aaaab
	v_fma_f32 v111, v110, v111, 0.5
	v_fma_f32 v111, v110, v111, 1.0
	v_mul_f32_e64 v121, v111, -v110
	s_or_b64 exec, exec, s[8:9]
	v_mul_f32_e32 v110, 0x3fb8aa3b, v122
	v_exp_f32_e32 v110, v110
	v_add_f32_e32 v111, v122, v122
	v_cmp_nlt_f32_e32 vcc, s75, v111
	s_and_saveexec_b64 s[8:9], vcc
	s_xor_b64 s[8:9], exec, s[8:9]
	v_fma_f32 v122, -v110, v110, 1.0
	s_andn2_saveexec_b64 s[8:9], s[8:9]
	v_fmamk_f32 v122, v111, 0x3c088889, v125
	v_fmaak_f32 v122, v111, v122, 0x3e2aaaab
	v_fma_f32 v122, v111, v122, 0.5
	v_fma_f32 v122, v111, v122, 1.0
	v_mul_f32_e64 v122, v122, -v111
	s_or_b64 exec, exec, s[8:9]
	v_mul_f32_e32 v111, 0x3fb8aa3b, v123
	v_exp_f32_e32 v111, v111
	v_add_f32_e32 v129, v123, v123
	v_cmp_nlt_f32_e32 vcc, s75, v129
	s_and_saveexec_b64 s[8:9], vcc
	s_xor_b64 s[8:9], exec, s[8:9]
	v_fma_f32 v123, -v111, v111, 1.0
	s_andn2_saveexec_b64 s[8:9], s[8:9]
	v_fmamk_f32 v123, v129, 0x3c088889, v125
	v_fmaak_f32 v123, v129, v123, 0x3e2aaaab
	v_fma_f32 v123, v129, v123, 0.5
	v_fma_f32 v123, v129, v123, 1.0
	v_mul_f32_e64 v123, v123, -v129
	s_or_b64 exec, exec, s[8:9]
	v_max_f32_e32 v120, v120, v120
	v_max_f32_e32 v120, 0, v120
	v_sqrt_f32_e32 v120, v120
	v_max_f32_e32 v121, v121, v121
	v_max_f32_e32 v121, 0, v121
	v_sqrt_f32_e32 v121, v121
	s_waitcnt lgkmcnt(1)
	v_mul_f32_e32 v112, v112, v120
	s_waitcnt lgkmcnt(0)
	v_mul_f32_e32 v112, v116, v112
	v_max_f32_e32 v116, v122, v122
	v_max_f32_e32 v120, v123, v123
	v_max_f32_e32 v116, 0, v116
	v_max_f32_e32 v120, 0, v120
	v_sqrt_f32_e32 v116, v116
	v_sqrt_f32_e32 v120, v120
	v_mul_f32_e32 v113, v113, v121
	v_add_u32_e32 v3, 0x1800, v3
	v_mul_f32_e32 v114, v114, v116
	v_mul_f32_e32 v115, v115, v120
	v_mul_f32_e32 v113, v117, v113
	v_mul_f32_e32 v114, v118, v114
	v_mul_f32_e32 v115, v119, v115
	ds_write_b128 v128, v[108:111] offset:41984
	ds_write_b128 v130, v[112:115] offset:16384
	v_and_b32_e32 v108, 0x3ffff000, v3
	v_and_b32_e32 v3, 0xfc0, v3
	v_lshl_add_u32 v108, v108, 2, 0
	v_lshlrev_b32_e32 v3, 2, v3
	v_add3_u32 v2, v108, v3, v2
	ds_read_b128 v[120:123], v2 offset:25600
	ds_read_b128 v[112:115], v2 offset:58368
	v_add_u32_e32 v3, v127, v3
	ds_read_b128 v[116:119], v3
	s_waitcnt lgkmcnt(2)
	v_mul_f32_e32 v3, 0x3fb8aa3b, v120
	v_exp_f32_e32 v108, v3
	v_add_f32_e32 v109, v120, v120
	v_cmp_nlt_f32_e32 vcc, s75, v109
	s_and_saveexec_b64 s[8:9], vcc
	s_xor_b64 s[8:9], exec, s[8:9]
	v_fma_f32 v3, -v108, v108, 1.0
	s_andn2_saveexec_b64 s[8:9], s[8:9]
	v_fmamk_f32 v3, v109, 0x3c088889, v125
	v_fmaak_f32 v3, v109, v3, 0x3e2aaaab
	v_fma_f32 v3, v109, v3, 0.5
	v_fma_f32 v3, v109, v3, 1.0
	v_mul_f32_e64 v3, v3, -v109
	s_or_b64 exec, exec, s[8:9]
	v_mul_f32_e32 v109, 0x3fb8aa3b, v121
	v_exp_f32_e32 v109, v109
	v_add_f32_e32 v110, v121, v121
	v_cmp_nlt_f32_e32 vcc, s75, v110
	s_and_saveexec_b64 s[8:9], vcc
	s_xor_b64 s[8:9], exec, s[8:9]
	v_fma_f32 v121, -v109, v109, 1.0
	s_andn2_saveexec_b64 s[8:9], s[8:9]
	v_fmamk_f32 v111, v110, 0x3c088889, v125
	v_fmaak_f32 v111, v110, v111, 0x3e2aaaab
	v_fma_f32 v111, v110, v111, 0.5
	v_fma_f32 v111, v110, v111, 1.0
	v_mul_f32_e64 v121, v111, -v110
	s_or_b64 exec, exec, s[8:9]
	v_mul_f32_e32 v110, 0x3fb8aa3b, v122
	v_exp_f32_e32 v110, v110
	v_add_f32_e32 v111, v122, v122
	v_cmp_nlt_f32_e32 vcc, s75, v111
	s_and_saveexec_b64 s[8:9], vcc
	s_xor_b64 s[8:9], exec, s[8:9]
	v_fma_f32 v122, -v110, v110, 1.0
	s_andn2_saveexec_b64 s[8:9], s[8:9]
	v_fmamk_f32 v120, v111, 0x3c088889, v125
	v_fmaak_f32 v120, v111, v120, 0x3e2aaaab
	v_fma_f32 v120, v111, v120, 0.5
	v_fma_f32 v120, v111, v120, 1.0
	v_mul_f32_e64 v122, v120, -v111
	s_or_b64 exec, exec, s[8:9]
	v_mul_f32_e32 v111, 0x3fb8aa3b, v123
	v_exp_f32_e32 v111, v111
	v_add_f32_e32 v120, v123, v123
	v_cmp_nlt_f32_e32 vcc, s75, v120
	s_and_saveexec_b64 s[8:9], vcc
	s_xor_b64 s[8:9], exec, s[8:9]
	v_fma_f32 v123, -v111, v111, 1.0
	s_andn2_saveexec_b64 s[8:9], s[8:9]
	v_fmamk_f32 v123, v120, 0x3c088889, v125
	v_fmaak_f32 v123, v120, v123, 0x3e2aaaab
	v_fma_f32 v123, v120, v123, 0.5
	v_fma_f32 v123, v120, v123, 1.0
	v_mul_f32_e64 v123, v123, -v120
	s_or_b64 exec, exec, s[8:9]
	v_max_f32_e32 v3, v3, v3
	v_max_f32_e32 v3, 0, v3
	v_sqrt_f32_e32 v3, v3
	v_max_f32_e32 v121, v121, v121
	v_max_f32_e32 v121, 0, v121
	v_mov_b32_e32 v120, 0
	s_waitcnt lgkmcnt(1)
	v_mul_f32_e32 v3, v112, v3
	v_sqrt_f32_e32 v112, v121
	v_max_f32_e32 v121, v122, v122
	v_max_f32_e32 v121, 0, v121
	v_sqrt_f32_e32 v121, v121
	s_waitcnt lgkmcnt(0)
	v_mul_f32_e32 v116, v116, v3
	v_mul_f32_e32 v3, v113, v112
	v_mul_f32_e32 v117, v117, v3
	v_mul_f32_e32 v3, v114, v121
	v_mul_f32_e32 v118, v118, v3
	v_max_f32_e32 v3, v123, v123
	v_max_f32_e32 v3, 0, v3
	v_sqrt_f32_e32 v3, v3
	v_ashrrev_i32_e32 v114, 7, v0
	v_and_b32_e32 v121, 0x7f, v0
	v_bfe_u32 v113, v0, 6, 1
	v_mul_f32_e32 v3, v115, v3
	v_mul_f32_e32 v119, v119, v3
	ds_write_b128 v2, v[108:111] offset:25600
	ds_write_b128 v2, v[116:119] offset:58368
	v_lshlrev_b32_e32 v2, 4, v114
	v_or_b32_e32 v115, 2, v2
	v_and_b32_e32 v112, 63, v0
	v_cmp_gt_u32_e32 vcc, 64, v121
	v_sub_u32_e32 v116, 63, v115
	v_lshl_or_b32 v3, v113, 12, v112
	v_cndmask_b32_e32 v115, v116, v115, vcc
	v_lshl_add_u32 v115, v115, 6, v3
	v_lshl_add_u32 v115, v115, 2, 0
	s_waitcnt lgkmcnt(0)
	s_barrier
	ds_read2st64_b32 v[116:117], v115 offset0:100 offset1:228
	v_or_b32_e32 v115, 3, v2
	v_sub_u32_e32 v118, 63, v115
	v_cndmask_b32_e32 v115, v118, v115, vcc
	v_lshl_add_u32 v115, v115, 6, v3
	v_lshl_add_u32 v115, v115, 2, 0
	ds_read2st64_b32 v[118:119], v115 offset0:100 offset1:228
	v_or_b32_e32 v115, 4, v2
	v_sub_u32_e32 v122, 63, v115
	v_cndmask_b32_e32 v115, v122, v115, vcc
	v_lshl_add_u32 v115, v115, 6, v3
	v_lshl_add_u32 v115, v115, 2, 0
	ds_read2st64_b32 v[122:123], v115 offset0:100 offset1:228
	v_or_b32_e32 v115, 5, v2
	v_sub_u32_e32 v127, 63, v115
	v_cndmask_b32_e32 v115, v127, v115, vcc
	v_lshl_add_u32 v115, v115, 6, v3
	v_lshl_add_u32 v115, v115, 2, 0
	ds_read2st64_b32 v[128:129], v115 offset0:100 offset1:228
	v_or_b32_e32 v115, 6, v2
	v_sub_u32_e32 v127, 63, v115
	v_cndmask_b32_e32 v115, v127, v115, vcc
	v_lshl_add_u32 v115, v115, 6, v3
	v_lshl_add_u32 v115, v115, 2, 0
	ds_read2st64_b32 v[130:131], v115 offset0:100 offset1:228
	v_or_b32_e32 v115, 7, v2
	v_sub_u32_e32 v127, 63, v115
	v_cndmask_b32_e32 v115, v127, v115, vcc
	v_lshl_add_u32 v115, v115, 6, v3
	v_lshl_add_u32 v115, v115, 2, 0
	ds_read2st64_b32 v[132:133], v115 offset0:100 offset1:228
	v_or_b32_e32 v115, 8, v2
	v_sub_u32_e32 v127, 63, v115
	v_cndmask_b32_e32 v115, v127, v115, vcc
	v_lshl_add_u32 v115, v115, 6, v3
	v_lshl_add_u32 v115, v115, 2, 0
	ds_read2st64_b32 v[134:135], v115 offset0:100 offset1:228
	v_or_b32_e32 v115, 9, v2
	v_sub_u32_e32 v127, 63, v115
	v_cndmask_b32_e32 v115, v127, v115, vcc
	v_lshl_add_u32 v115, v115, 6, v3
	v_lshl_add_u32 v115, v115, 2, 0
	ds_read2st64_b32 v[136:137], v115 offset0:100 offset1:228
	v_or_b32_e32 v115, 10, v2
	v_sub_u32_e32 v127, 63, v115
	v_cndmask_b32_e32 v115, v127, v115, vcc
	v_lshl_add_u32 v115, v115, 6, v3
	v_lshl_add_u32 v115, v115, 2, 0
	ds_read2st64_b32 v[138:139], v115 offset0:100 offset1:228
	v_or_b32_e32 v115, 11, v2
	v_sub_u32_e32 v127, 63, v115
	v_cndmask_b32_e32 v115, v127, v115, vcc
	v_lshl_add_u32 v115, v115, 6, v3
	v_lshl_add_u32 v115, v115, 2, 0
	v_sub_u32_e32 v108, 63, v2
	v_or_b32_e32 v110, 1, v2
	ds_read2st64_b32 v[140:141], v115 offset0:100 offset1:228
	v_or_b32_e32 v115, 12, v2
	v_cndmask_b32_e32 v108, v108, v2, vcc
	v_sub_u32_e32 v111, 63, v110
	v_sub_u32_e32 v127, 63, v115
	v_lshl_add_u32 v108, v108, 6, v3
	v_cndmask_b32_e32 v110, v111, v110, vcc
	v_cndmask_b32_e32 v115, v127, v115, vcc
	v_lshl_add_u32 v108, v108, 2, 0
	v_lshl_add_u32 v110, v110, 6, v3
	v_lshl_add_u32 v115, v115, 6, v3
	ds_read2st64_b32 v[108:109], v108 offset0:100 offset1:228
	v_lshl_add_u32 v110, v110, 2, 0
	v_lshl_add_u32 v115, v115, 2, 0
	ds_read2st64_b32 v[110:111], v110 offset0:100 offset1:228
	ds_read2st64_b32 v[142:143], v115 offset0:100 offset1:228
	v_or_b32_e32 v115, 13, v2
	v_sub_u32_e32 v127, 63, v115
	v_cndmask_b32_e32 v115, v127, v115, vcc
	v_lshl_add_u32 v115, v115, 6, v3
	v_lshl_add_u32 v115, v115, 2, 0
	s_waitcnt lgkmcnt(2)
	v_fma_f32 v109, 0, v108, v109
	ds_read2st64_b32 v[144:145], v115 offset0:100 offset1:228
	v_or_b32_e32 v115, 14, v2
	s_waitcnt lgkmcnt(2)
	v_mul_f32_e32 v108, v108, v110
	v_fmac_f32_e32 v111, v109, v110
	v_sub_u32_e32 v127, 63, v115
	v_mul_f32_e32 v108, v108, v116
	v_fmac_f32_e32 v117, v111, v116
	v_cndmask_b32_e32 v115, v127, v115, vcc
	v_mul_f32_e32 v108, v108, v118
	v_fmac_f32_e32 v119, v117, v118
	v_lshl_add_u32 v115, v115, 6, v3
	v_mul_f32_e32 v108, v108, v122
	v_fmac_f32_e32 v123, v119, v122
	v_lshl_add_u32 v115, v115, 2, 0
	v_or_b32_e32 v2, 15, v2
	v_mul_f32_e32 v108, v108, v128
	v_fmac_f32_e32 v129, v123, v128
	ds_read2st64_b32 v[146:147], v115 offset0:100 offset1:228
	v_sub_u32_e32 v115, 63, v2
	v_mul_f32_e32 v108, v108, v130
	v_fmac_f32_e32 v131, v129, v130
	v_cndmask_b32_e32 v2, v115, v2, vcc
	v_mul_f32_e32 v108, v108, v132
	v_fmac_f32_e32 v133, v131, v132
	v_lshl_add_u32 v2, v2, 6, v3
	v_mul_f32_e32 v108, v108, v134
	v_fmac_f32_e32 v135, v133, v134
	v_lshl_add_u32 v2, v2, 2, 0
	v_mul_f32_e32 v108, v108, v136
	v_fmac_f32_e32 v137, v135, v136
	ds_read2st64_b32 v[2:3], v2 offset0:100 offset1:228
	v_mul_f32_e32 v108, v108, v138
	v_fmac_f32_e32 v139, v137, v138
	v_mul_f32_e32 v108, v108, v140
	v_fmac_f32_e32 v141, v139, v140
	s_waitcnt lgkmcnt(3)
	v_mul_f32_e32 v108, v108, v142
	v_fmac_f32_e32 v143, v141, v142
	s_waitcnt lgkmcnt(2)
	v_mul_f32_e32 v108, v108, v144
	v_fmac_f32_e32 v145, v143, v144
	s_waitcnt lgkmcnt(1)
	v_mul_f32_e32 v108, v108, v146
	v_fmac_f32_e32 v147, v145, v146
	v_lshl_add_u32 v0, v0, 2, 0
	s_waitcnt lgkmcnt(0)
	v_mul_f32_e32 v108, v108, v2
	v_fmac_f32_e32 v3, v147, v2
	v_add_u32_e32 v2, 0x16400, v0
	v_add_u32_e32 v0, 0x16c00, v0
	ds_write_b32 v2, v108
	ds_write_b32 v0, v3
	v_cmp_lt_i32_e32 vcc, 0, v114
	v_mov_b32_e32 v0, 1.0
	v_lshl_add_u32 v2, v121, 2, 0
	s_waitcnt vmcnt(0) lgkmcnt(0)
	s_barrier
	s_and_saveexec_b64 s[8:9], vcc
	s_cbranch_execnz .LBB0_431
	s_or_b64 exec, exec, s[8:9]
	v_cmp_lt_i32_e32 vcc, 1, v114
	s_and_saveexec_b64 s[8:9], vcc
	s_cbranch_execnz .LBB0_432

.LBB0_361:
	s_and_b64 vcc, exec, s[6:7]
	s_cbranch_vccnz .LBB0_363
	v_mov_b32_e32 v82, v204
	s_and_b32 s6, s68, 7
	s_lshl_b32 s26, s6, 8
	v_lshlrev_b32_e32 v0, 5, v82
	v_and_b32_e32 v0, 0xe0, v0
	v_or_b32_e32 v0, s26, v0
	v_lshl_add_u64 v[2:3], s[12:13], 0, v[0:1]
	v_add_co_u32_e32 v2, vcc, s1, v2
	v_ashrrev_i32_e32 v60, 7, v82
	global_load_dwordx4 v[4:7], v0, s[12:13] offset:2064
	global_load_dwordx4 v[8:11], v0, s[12:13] offset:2048
	v_addc_co_u32_e32 v3, vcc, 0, v3, vcc
	global_load_dwordx4 v[12:15], v0, s[38:39]
	global_load_dwordx4 v[16:19], v0, s[48:49]
	global_load_dwordx4 v[20:23], v[2:3], off offset:16
	global_load_dwordx4 v[36:39], v[2:3], off offset:2064
	global_load_dwordx4 v[28:31], v0, s[12:13] offset:16
	global_load_dwordx4 v[44:47], v0, s[14:15] offset:16
	global_load_dwordx4 v[32:35], v0, s[12:13]
	global_load_dwordx4 v[48:51], v0, s[14:15]
	v_lshl_or_b32 v2, v60, 3, s6
	v_lshlrev_b32_e32 v60, 11, v60
	v_lshrrev_b32_e32 v0, 1, v82
	v_ashrrev_i32_e32 v3, 31, v2
	v_and_b32_e32 v76, 0x800, v60
	v_mov_b32_e32 v77, v1
	v_and_b32_e32 v84, 32, v0
	v_lshlrev_b64 v[2:3], 13, v[2:3]
	v_lshl_add_u64 v[60:61], s[36:37], 0, v[76:77]
	v_lshl_add_u64 v[2:3], s[50:51], 0, v[2:3]
	v_and_b32_e32 v0, 48, v82
	v_lshl_add_u64 v[78:79], v[60:61], 0, s[26:27]
	v_and_or_b32 v60, v82, 15, v84
	v_lshl_add_u64 v[2:3], v[2:3], 0, v[0:1]
	v_lshlrev_b32_e32 v80, 7, v60
	v_mov_b32_e32 v81, v1
	v_lshl_add_u64 v[64:65], v[2:3], 0, v[80:81]
	v_mov_b32_e32 v81, s25
	v_mov_b32_e32 v83, s19
	v_cmp_gt_u32_e32 vcc, s45, v82
	v_mov_b32_e32 v82, s18
	v_lshl_or_b32 v0, v84, 2, v0
	v_cndmask_b32_e32 v83, v81, v83, vcc
	v_mov_b32_e32 v81, s24
	v_cndmask_b32_e32 v82, v81, v82, vcc
	v_lshl_add_u64 v[76:77], v[82:83], 0, v[76:77]
	v_lshl_add_u64 v[76:77], v[76:77], 0, s[26:27]
	v_lshl_add_u64 v[88:89], v[76:77], 0, v[0:1]
	v_lshl_add_u64 v[96:97], v[78:79], 0, v[0:1]
	v_or_b32_e32 v0, 0x800, v80
	v_lshl_add_u64 v[2:3], v[2:3], 0, v[0:1]
	global_load_dwordx4 v[60:63], v[64:65], off
	s_nop 0
	global_load_dwordx4 v[64:67], v[64:65], off offset:64
	s_nop 0
	global_load_dwordx4 v[76:79], v[2:3], off
	global_load_dwordx4 v[80:83], v[2:3], off offset:64
	global_load_dwordx4 v[84:87], v[88:89], off
	s_nop 0
	global_load_dwordx4 v[88:91], v[88:89], off offset:64
	s_nop 0
	global_load_dwordx4 v[92:95], v[96:97], off
	s_nop 0
	global_load_dwordx4 v[96:99], v[96:97], off offset:64
	s_waitcnt vmcnt(0)
.LBB0_363:
	v_mov_b32_e32 v0, v204
	v_and_b32_e32 v3, 0xffff0000, v68
	v_lshlrev_b32_e32 v2, 3, v0
	v_and_b32_e32 v116, 56, v2
	v_lshlrev_b32_e32 v2, 16, v68
	s_nop 0
	v_pk_fma_f32 v[2:3], v[32:33], v[2:3], v[48:49]
	v_lshlrev_b32_e32 v108, 16, v72
	v_and_b32_e32 v109, 0xffff0000, v72
	v_pk_fma_f32 v[2:3], v[8:9], v[108:109], v[2:3]
	v_lshlrev_b32_e32 v108, 16, v100
	v_and_b32_e32 v109, 0xffff0000, v100
	v_pk_fma_f32 v[2:3], v[12:13], v[108:109], v[2:3]
	v_lshlrev_b32_e32 v108, 16, v104
	v_and_b32_e32 v109, 0xffff0000, v104
	v_pk_fma_f32 v[108:109], v[16:17], v[108:109], v[2:3]
	v_lshlrev_b32_e32 v2, 16, v70
	v_and_b32_e32 v3, 0xffff0000, v70
	v_pk_fma_f32 v[2:3], v[28:29], v[2:3], v[44:45]
	v_lshlrev_b32_e32 v110, 16, v74
	v_and_b32_e32 v111, 0xffff0000, v74
	v_pk_fma_f32 v[2:3], v[4:5], v[110:111], v[2:3]
	v_lshlrev_b32_e32 v110, 16, v102
	v_and_b32_e32 v111, 0xffff0000, v102
	v_pk_fma_f32 v[2:3], v[20:21], v[110:111], v[2:3]
	v_lshlrev_b32_e32 v110, 16, v106
	v_and_b32_e32 v111, 0xffff0000, v106
	v_pk_fma_f32 v[112:113], v[36:37], v[110:111], v[2:3]
	v_lshlrev_b32_e32 v2, 16, v69
	v_and_b32_e32 v3, 0xffff0000, v69
	v_pk_fma_f32 v[2:3], v[34:35], v[2:3], v[50:51]
	v_lshlrev_b32_e32 v110, 16, v73
	v_and_b32_e32 v111, 0xffff0000, v73
	v_pk_fma_f32 v[2:3], v[10:11], v[110:111], v[2:3]
	v_lshlrev_b32_e32 v110, 16, v101
	v_and_b32_e32 v111, 0xffff0000, v101
	v_pk_fma_f32 v[2:3], v[14:15], v[110:111], v[2:3]
	v_lshlrev_b32_e32 v110, 16, v105
	v_and_b32_e32 v111, 0xffff0000, v105
	v_pk_fma_f32 v[110:111], v[18:19], v[110:111], v[2:3]
	v_lshlrev_b32_e32 v2, 16, v71
	v_and_b32_e32 v3, 0xffff0000, v71
	v_pk_fma_f32 v[2:3], v[30:31], v[2:3], v[46:47]
	v_lshlrev_b32_e32 v114, 16, v75
	v_and_b32_e32 v115, 0xffff0000, v75
	v_pk_fma_f32 v[2:3], v[6:7], v[114:115], v[2:3]
	v_lshlrev_b32_e32 v114, 16, v103
	v_and_b32_e32 v115, 0xffff0000, v103
	v_pk_fma_f32 v[2:3], v[22:23], v[114:115], v[2:3]
	v_lshlrev_b32_e32 v114, 16, v107
	v_and_b32_e32 v115, 0xffff0000, v107
	v_pk_fma_f32 v[114:115], v[38:39], v[114:115], v[2:3]
	v_ashrrev_i32_e32 v3, 3, v0
	v_lshl_add_u32 v117, v3, 8, 0
	v_lshl_add_u32 v118, v116, 2, v117
	ds_write_b128 v118, v[108:111]
	ds_write_b128 v118, v[112:115] offset:16
	v_cvt_pk_bf16_f32 v108, v108, v109
	v_cvt_pk_bf16_f32 v109, v110, v111
	v_cvt_pk_bf16_f32 v110, v112, v113
	v_mul_lo_u32 v3, v3, s67
	v_lshlrev_b32_e32 v112, 1, v116
	v_and_b32_e32 v127, 15, v0
	v_cvt_pk_bf16_f32 v111, v114, v115
	v_add3_u32 v3, v117, v3, v112
	v_and_b32_e32 v2, 48, v0
	ds_write_b128 v3, v[108:111] offset:16384
	v_mul_u32_u24_e32 v3, 0x90, v127
	v_add3_u32 v3, 0, v2, v3
	s_waitcnt lgkmcnt(0)
	s_barrier
	ds_read_b128 v[108:111], v3 offset:16384
	ds_read_b128 v[112:115], v3 offset:16448
	ds_read_b128 v[120:123], v3 offset:18688
	ds_read_b128 v[128:131], v3 offset:18752
	ds_read_b128 v[136:139], v3 offset:20992
	ds_read_b128 v[140:143], v3 offset:21056
	s_waitcnt lgkmcnt(5)
	v_mfma_f32_16x16x32_bf16 v[116:119], v[60:63], v[108:111], 0
	ds_read_b128 v[148:151], v3 offset:23296
	ds_read_b128 v[154:157], v3 offset:23360
	v_mov_b32_e32 v3, s2
	v_cmp_gt_u32_e32 vcc, s45, v0
	s_nop 0
	v_mfma_f32_16x16x32_bf16 v[108:111], v[76:79], v[108:111], 0
	v_lshlrev_b32_e32 v127, 8, v127
	s_waitcnt lgkmcnt(3)
	v_mfma_f32_16x16x32_bf16 v[144:147], v[60:63], v[136:139], 0
	v_mfma_f32_16x16x32_bf16 v[136:139], v[76:79], v[136:139], 0
	v_mfma_f32_16x16x32_bf16 v[162:165], v[64:67], v[112:115], v[116:119]
	s_nop 0
	v_mfma_f32_16x16x32_bf16 v[166:169], v[80:83], v[112:115], v[108:111]
	s_waitcnt lgkmcnt(2)
	v_mfma_f32_16x16x32_bf16 v[112:115], v[80:83], v[140:143], v[136:139]
	s_nop 2
	v_mov_b32_e32 v136, s73
	v_cndmask_b32_e32 v3, v3, v136, vcc
	v_lshlrev_b32_e32 v136, 7, v0
	v_and_b32_e32 v136, 0x4000, v136
	v_add3_u32 v3, v3, v136, v127
	s_nop 0
	v_add_f32_e32 v136, v84, v162
	v_mul_f32_e32 v136, 0xbfb8aa3b, v136
	v_add_f32_e32 v137, v85, v163
	v_exp_f32_e32 v136, v136
	v_mul_f32_e32 v137, 0xbfb8aa3b, v137
	v_exp_f32_e32 v137, v137
	v_lshlrev_b32_e32 v127, 1, v0
	v_and_b32_e32 v127, 0x80, v127
	v_add_f32_e32 v136, 1.0, v136
	v_rcp_f32_e32 v136, v136
	v_add3_u32 v2, v3, v127, v2
	v_add_f32_e32 v3, 1.0, v137
	v_add_f32_e32 v137, v86, v164
	v_mul_f32_e32 v137, 0xbfb8aa3b, v137
	v_rcp_f32_e32 v3, v3
	v_exp_f32_e32 v137, v137
	v_add_f32_e32 v138, v87, v165
	v_mul_f32_e32 v138, 0xbfb8aa3b, v138
	v_mul_f32_e32 v127, 0xc1000000, v136
	v_exp_f32_e32 v138, v138
	s_nop 0
	v_mul_f32_e32 v127, v92, v127
	v_cndmask_b32_e32 v136, v136, v127, vcc
	v_mul_f32_e32 v127, 0xc1000000, v3
	v_add_f32_e32 v137, 1.0, v137
	v_mfma_f32_16x16x32_bf16 v[132:135], v[60:63], v[120:123], 0
	v_mul_f32_e32 v127, v93, v127
	v_rcp_f32_e32 v139, v137
	v_cndmask_b32_e32 v137, v3, v127, vcc
	v_add_f32_e32 v3, 1.0, v138
	v_rcp_f32_e32 v3, v3
	v_mfma_f32_16x16x32_bf16 v[132:135], v[64:67], v[128:131], v[132:135]
	v_mul_f32_e32 v127, 0xc1000000, v139
	v_mul_f32_e32 v127, v94, v127
	v_cndmask_b32_e32 v138, v139, v127, vcc
	v_mul_f32_e32 v127, 0xc1000000, v3
	v_mul_f32_e32 v127, v95, v127
	v_cndmask_b32_e32 v139, v3, v127, vcc
	s_nop 1
	v_add_f32_e32 v3, v84, v132
	v_mul_f32_e32 v3, 0xbfb8aa3b, v3
	v_exp_f32_e32 v3, v3
	v_add_f32_e32 v127, v85, v133
	v_mul_f32_e32 v127, 0xbfb8aa3b, v127
	v_exp_f32_e32 v127, v127
	v_add_f32_e32 v3, 1.0, v3
	v_rcp_f32_e32 v3, v3
	v_add_f32_e32 v133, v86, v134
	v_add_f32_e32 v127, 1.0, v127
	v_mul_f32_e32 v133, 0xbfb8aa3b, v133
	v_rcp_f32_e32 v127, v127
	v_exp_f32_e32 v133, v133
	v_add_f32_e32 v134, v87, v135
	v_mul_f32_e32 v134, 0xbfb8aa3b, v134
	v_mul_f32_e32 v132, 0xc1000000, v3
	v_exp_f32_e32 v134, v134
	v_mul_f32_e32 v132, v92, v132
	v_cndmask_b32_e32 v132, v3, v132, vcc
	v_mul_f32_e32 v3, 0xc1000000, v127
	v_add_f32_e32 v133, 1.0, v133
	v_mfma_f32_16x16x32_bf16 v[120:123], v[76:79], v[120:123], 0
	v_mul_f32_e32 v3, v93, v3
	v_rcp_f32_e32 v135, v133
	v_cndmask_b32_e32 v133, v127, v3, vcc
	v_add_f32_e32 v3, 1.0, v134
	v_rcp_f32_e32 v3, v3
	v_mfma_f32_16x16x32_bf16 v[116:119], v[80:83], v[128:131], v[120:123]
	v_mul_f32_e32 v127, 0xc1000000, v135
	v_mul_f32_e32 v127, v94, v127
	v_cndmask_b32_e32 v134, v135, v127, vcc
	v_mfma_f32_16x16x32_bf16 v[120:123], v[64:67], v[140:143], v[144:147]
	v_mul_f32_e32 v127, 0xc1000000, v3
	v_mul_f32_e32 v127, v95, v127
	v_cndmask_b32_e32 v135, v3, v127, vcc
	s_waitcnt lgkmcnt(1)
	v_mfma_f32_16x16x32_bf16 v[158:161], v[60:63], v[148:151], 0
	v_add_f32_e32 v118, v90, v118
	s_nop 1
	v_add_f32_e32 v3, v84, v120
	v_mul_f32_e32 v3, 0xbfb8aa3b, v3
	v_exp_f32_e32 v3, v3
	v_add_f32_e32 v120, v85, v121
	v_mul_f32_e32 v120, 0xbfb8aa3b, v120
	v_exp_f32_e32 v120, v120
	v_add_f32_e32 v3, 1.0, v3
	v_rcp_f32_e32 v3, v3
	v_add_f32_e32 v122, v86, v122
	v_add_f32_e32 v120, 1.0, v120
	v_mul_f32_e32 v122, 0xbfb8aa3b, v122
	v_rcp_f32_e32 v121, v120
	v_exp_f32_e32 v122, v122
	v_add_f32_e32 v123, v87, v123
	v_mul_f32_e32 v123, 0xbfb8aa3b, v123
	v_mul_f32_e32 v120, 0xc1000000, v3
	v_exp_f32_e32 v123, v123
	v_mul_f32_e32 v120, v92, v120
	v_cndmask_b32_e32 v120, v3, v120, vcc
	v_mul_f32_e32 v3, 0xc1000000, v121
	v_add_f32_e32 v122, 1.0, v122
	v_mul_f32_e32 v3, v93, v3
	v_rcp_f32_e32 v122, v122
	v_cndmask_b32_e32 v121, v121, v3, vcc
	v_add_f32_e32 v3, 1.0, v123
	v_rcp_f32_e32 v3, v3
	s_waitcnt lgkmcnt(0)
	v_mfma_f32_16x16x32_bf16 v[128:131], v[64:67], v[154:157], v[158:161]
	v_mul_f32_e32 v123, 0xc1000000, v122
	v_mul_f32_e32 v123, v94, v123
	v_cndmask_b32_e32 v122, v122, v123, vcc
	v_mul_f32_e32 v123, 0xc1000000, v3
	v_mul_f32_e32 v123, v95, v123
	v_cndmask_b32_e32 v123, v3, v123, vcc
	s_nop 1
	v_add_f32_e32 v3, v84, v128
	v_mul_f32_e32 v3, 0xbfb8aa3b, v3
	v_exp_f32_e32 v3, v3
	v_add_f32_e32 v127, v85, v129
	v_mul_f32_e32 v127, 0xbfb8aa3b, v127
	v_exp_f32_e32 v127, v127
	v_add_f32_e32 v3, 1.0, v3
	v_rcp_f32_e32 v3, v3
	ds_write_b128 v2, v[120:123] offset:8192
	v_add_f32_e32 v122, v86, v130
	v_add_f32_e32 v120, 1.0, v127
	v_mul_f32_e32 v122, 0xbfb8aa3b, v122
	v_rcp_f32_e32 v121, v120
	v_exp_f32_e32 v122, v122
	v_add_f32_e32 v123, v87, v131
	v_mul_f32_e32 v123, 0xbfb8aa3b, v123
	v_mul_f32_e32 v120, 0xc1000000, v3
	v_exp_f32_e32 v123, v123
	v_mul_f32_e32 v120, v92, v120
	v_cndmask_b32_e32 v120, v3, v120, vcc
	v_mul_f32_e32 v3, 0xc1000000, v121
	v_add_f32_e32 v122, 1.0, v122
	v_mul_f32_e32 v3, v93, v3
	v_rcp_f32_e32 v122, v122
	v_cndmask_b32_e32 v121, v121, v3, vcc
	v_add_f32_e32 v3, 1.0, v123
	v_rcp_f32_e32 v3, v3
	v_mul_f32_e32 v123, 0xc1000000, v122
	v_mul_f32_e32 v123, v94, v123
	v_cndmask_b32_e32 v122, v122, v123, vcc
	v_mul_f32_e32 v123, 0xc1000000, v3
	v_mul_f32_e32 v123, v95, v123
	v_cndmask_b32_e32 v123, v3, v123, vcc
	v_add_f32_e32 v3, v88, v166
	v_mul_f32_e32 v3, 0xbfb8aa3b, v3
	v_exp_f32_e32 v3, v3
	v_add_f32_e32 v127, v89, v167
	v_mul_f32_e32 v127, 0xbfb8aa3b, v127
	v_exp_f32_e32 v127, v127
	v_add_f32_e32 v3, 1.0, v3
	v_rcp_f32_e32 v3, v3
	ds_write_b128 v2, v[120:123] offset:12288
	v_add_f32_e32 v122, v90, v168
	v_add_f32_e32 v120, 1.0, v127
	v_mul_f32_e32 v122, 0xbfb8aa3b, v122
	v_rcp_f32_e32 v121, v120
	v_exp_f32_e32 v122, v122
	v_add_f32_e32 v123, v91, v169
	v_mul_f32_e32 v123, 0xbfb8aa3b, v123
	v_mul_f32_e32 v120, 0xc1000000, v3
	v_exp_f32_e32 v123, v123
	s_nop 0
	v_mul_f32_e32 v120, v96, v120
	v_cndmask_b32_e32 v120, v3, v120, vcc
	v_mul_f32_e32 v3, 0xc1000000, v121
	v_add_f32_e32 v122, 1.0, v122
	v_mul_f32_e32 v3, v97, v3
	v_rcp_f32_e32 v122, v122
	v_cndmask_b32_e32 v121, v121, v3, vcc
	v_add_f32_e32 v3, 1.0, v123
	v_rcp_f32_e32 v3, v3
	v_mul_f32_e32 v123, 0xc1000000, v122
	v_mul_f32_e32 v123, v98, v123
	v_cndmask_b32_e32 v122, v122, v123, vcc
	v_mul_f32_e32 v123, 0xc1000000, v3
	v_mul_f32_e32 v123, v99, v123
	v_cndmask_b32_e32 v123, v3, v123, vcc
	v_add_f32_e32 v3, v88, v116
	v_mul_f32_e32 v3, 0xbfb8aa3b, v3
	v_exp_f32_e32 v3, v3
	v_add_f32_e32 v116, v89, v117
	v_mul_f32_e32 v116, 0xbfb8aa3b, v116
	v_exp_f32_e32 v116, v116
	v_add_f32_e32 v3, 1.0, v3
	v_rcp_f32_e32 v3, v3
	v_mul_f32_e32 v118, 0xbfb8aa3b, v118
	v_add_f32_e32 v116, 1.0, v116
	v_rcp_f32_e32 v117, v116
	v_exp_f32_e32 v118, v118
	v_add_f32_e32 v119, v91, v119
	v_mul_f32_e32 v119, 0xbfb8aa3b, v119
	v_mul_f32_e32 v116, 0xc1000000, v3
	v_exp_f32_e32 v119, v119
	v_mul_f32_e32 v116, v96, v116
	v_cndmask_b32_e32 v116, v3, v116, vcc
	v_mul_f32_e32 v3, 0xc1000000, v117
	v_add_f32_e32 v118, 1.0, v118
	v_mul_f32_e32 v3, v97, v3
	v_rcp_f32_e32 v118, v118
	v_cndmask_b32_e32 v117, v117, v3, vcc
	v_add_f32_e32 v3, 1.0, v119
	v_rcp_f32_e32 v3, v3
	v_mul_f32_e32 v119, 0xc1000000, v118
	v_mul_f32_e32 v119, v98, v119
	v_cndmask_b32_e32 v118, v118, v119, vcc
	v_mul_f32_e32 v119, 0xc1000000, v3
	v_mul_f32_e32 v119, v99, v119
	v_cndmask_b32_e32 v119, v3, v119, vcc
	v_add_f32_e32 v3, v88, v112
	v_mul_f32_e32 v3, 0xbfb8aa3b, v3
	v_exp_f32_e32 v3, v3
	v_add_f32_e32 v112, v89, v113
	v_mul_f32_e32 v112, 0xbfb8aa3b, v112
	v_exp_f32_e32 v112, v112
	v_add_f32_e32 v3, 1.0, v3
	v_rcp_f32_e32 v3, v3
	v_add_f32_e32 v114, v90, v114
	v_add_f32_e32 v112, 1.0, v112
	v_mul_f32_e32 v114, 0xbfb8aa3b, v114
	v_rcp_f32_e32 v113, v112
	v_exp_f32_e32 v114, v114
	v_add_f32_e32 v115, v91, v115
	v_mul_f32_e32 v115, 0xbfb8aa3b, v115
	v_mul_f32_e32 v112, 0xc1000000, v3
	v_exp_f32_e32 v115, v115
	v_mul_f32_e32 v112, v96, v112
	v_cndmask_b32_e32 v112, v3, v112, vcc
	v_mul_f32_e32 v3, 0xc1000000, v113
	v_add_f32_e32 v114, 1.0, v114
	v_mfma_f32_16x16x32_bf16 v[148:151], v[76:79], v[148:151], 0
	v_mul_f32_e32 v3, v97, v3
	v_rcp_f32_e32 v114, v114
	v_cndmask_b32_e32 v113, v113, v3, vcc
	v_add_f32_e32 v3, 1.0, v115
	v_rcp_f32_e32 v3, v3
	v_mfma_f32_16x16x32_bf16 v[108:111], v[80:83], v[154:157], v[148:151]
	v_mul_f32_e32 v115, 0xc1000000, v114
	v_mul_f32_e32 v115, v98, v115
	v_cndmask_b32_e32 v114, v114, v115, vcc
	v_mul_f32_e32 v115, 0xc1000000, v3
	v_mul_f32_e32 v115, v99, v115
	v_cndmask_b32_e32 v115, v3, v115, vcc
	s_nop 1
	v_add_f32_e32 v3, v88, v108
	v_mul_f32_e32 v3, 0xbfb8aa3b, v3
	v_exp_f32_e32 v3, v3
	v_add_f32_e32 v108, v89, v109
	v_mul_f32_e32 v108, 0xbfb8aa3b, v108
	v_exp_f32_e32 v108, v108
	v_add_f32_e32 v3, 1.0, v3
	v_rcp_f32_e32 v3, v3
	v_add_f32_e32 v110, v90, v110
	v_add_f32_e32 v108, 1.0, v108
	v_mul_f32_e32 v110, 0xbfb8aa3b, v110
	v_rcp_f32_e32 v109, v108
	v_exp_f32_e32 v110, v110
	v_add_f32_e32 v111, v91, v111
	v_mul_f32_e32 v111, 0xbfb8aa3b, v111
	v_mul_f32_e32 v108, 0xc1000000, v3
	v_exp_f32_e32 v111, v111
	v_mul_f32_e32 v108, v96, v108
	v_cndmask_b32_e32 v108, v3, v108, vcc
	v_mul_f32_e32 v3, 0xc1000000, v109
	v_add_f32_e32 v110, 1.0, v110
	v_mul_f32_e32 v3, v97, v3
	v_rcp_f32_e32 v110, v110
	v_cndmask_b32_e32 v109, v109, v3, vcc
	v_add_f32_e32 v3, 1.0, v111
	v_rcp_f32_e32 v3, v3
	v_mul_f32_e32 v111, 0xc1000000, v110
	v_mul_f32_e32 v111, v98, v111
	v_cndmask_b32_e32 v110, v110, v111, vcc
	v_mul_f32_e32 v111, 0xc1000000, v3
	v_mul_f32_e32 v111, v99, v111
	v_cndmask_b32_e32 v111, v3, v111, vcc
	ds_write_b128 v2, v[108:111] offset:12352
	v_lshlrev_b32_e32 v3, 2, v0
	v_lshlrev_b32_e32 v108, 4, v0
	ds_write_b128 v2, v[136:139]
	ds_write_b128 v2, v[132:135] offset:4096
	ds_write_b128 v2, v[120:123] offset:64
	ds_write_b128 v2, v[116:119] offset:4160
	ds_write_b128 v2, v[112:115] offset:8256
	v_and_b32_e32 v2, 60, v3
	v_and_b32_e32 v109, 0xffffc000, v108
	v_lshlrev_b32_e32 v2, 2, v2
	v_add_u32_e32 v109, 0, v109
	v_and_b32_e32 v108, 0x3f00, v108
	v_add3_u32 v128, v109, v108, v2
	s_waitcnt lgkmcnt(0)
	s_barrier
	ds_read_b128 v[120:123], v128 offset:25600
	ds_read_b128 v[112:115], v128 offset:58368
	v_add_u32_e32 v127, 0, v2
	v_add_u32_e32 v129, v127, v108
	ds_read_b128 v[116:119], v129
	s_waitcnt lgkmcnt(2)
	v_mul_f32_e32 v108, 0x3fb8aa3b, v120
	v_exp_f32_e32 v108, v108
	v_add_f32_e32 v109, v120, v120
	v_cmp_nlt_f32_e32 vcc, s75, v109
	s_and_saveexec_b64 s[6:7], vcc
	s_xor_b64 s[6:7], exec, s[6:7]
	v_fma_f32 v120, -v108, v108, 1.0
	s_andn2_saveexec_b64 s[6:7], s[6:7]
	v_fmamk_f32 v110, v109, 0x3c088889, v125
	v_fmaak_f32 v110, v109, v110, 0x3e2aaaab
	v_fma_f32 v110, v109, v110, 0.5
	v_fma_f32 v110, v109, v110, 1.0
	v_mul_f32_e64 v120, v110, -v109
	s_or_b64 exec, exec, s[6:7]
	v_mul_f32_e32 v109, 0x3fb8aa3b, v121
	v_exp_f32_e32 v109, v109
	v_add_f32_e32 v110, v121, v121
	v_cmp_nlt_f32_e32 vcc, s75, v110
	s_and_saveexec_b64 s[6:7], vcc
	s_xor_b64 s[6:7], exec, s[6:7]
	v_fma_f32 v121, -v109, v109, 1.0
	s_andn2_saveexec_b64 s[6:7], s[6:7]
	v_fmamk_f32 v111, v110, 0x3c088889, v125
	v_fmaak_f32 v111, v110, v111, 0x3e2aaaab
	v_fma_f32 v111, v110, v111, 0.5
	v_fma_f32 v111, v110, v111, 1.0
	v_mul_f32_e64 v121, v111, -v110
	s_or_b64 exec, exec, s[6:7]
	v_mul_f32_e32 v110, 0x3fb8aa3b, v122
	v_exp_f32_e32 v110, v110
	v_add_f32_e32 v111, v122, v122
	v_cmp_nlt_f32_e32 vcc, s75, v111
	s_and_saveexec_b64 s[6:7], vcc
	s_xor_b64 s[6:7], exec, s[6:7]
	v_fma_f32 v122, -v110, v110, 1.0
	s_andn2_saveexec_b64 s[6:7], s[6:7]
	v_fmamk_f32 v122, v111, 0x3c088889, v125
	v_fmaak_f32 v122, v111, v122, 0x3e2aaaab
	v_fma_f32 v122, v111, v122, 0.5
	v_fma_f32 v122, v111, v122, 1.0
	v_mul_f32_e64 v122, v122, -v111
	s_or_b64 exec, exec, s[6:7]
	v_mul_f32_e32 v111, 0x3fb8aa3b, v123
	v_exp_f32_e32 v111, v111
	v_add_f32_e32 v130, v123, v123
	v_cmp_nlt_f32_e32 vcc, s75, v130
	s_and_saveexec_b64 s[6:7], vcc
	s_xor_b64 s[6:7], exec, s[6:7]
	v_fma_f32 v123, -v111, v111, 1.0
	s_andn2_saveexec_b64 s[6:7], s[6:7]
	v_fmamk_f32 v123, v130, 0x3c088889, v125
	v_fmaak_f32 v123, v130, v123, 0x3e2aaaab
	v_fma_f32 v123, v130, v123, 0.5
	v_fma_f32 v123, v130, v123, 1.0
	v_mul_f32_e64 v123, v123, -v130
	s_or_b64 exec, exec, s[6:7]
	v_max_f32_e32 v120, v120, v120
	v_max_f32_e32 v120, 0, v120
	v_sqrt_f32_e32 v120, v120
	v_max_f32_e32 v121, v121, v121
	v_max_f32_e32 v121, 0, v121
	v_sqrt_f32_e32 v121, v121
	s_waitcnt lgkmcnt(1)
	v_mul_f32_e32 v112, v112, v120
	s_waitcnt lgkmcnt(0)
	v_mul_f32_e32 v112, v116, v112
	v_max_f32_e32 v116, v122, v122
	v_max_f32_e32 v120, v123, v123
	v_max_f32_e32 v116, 0, v116
	v_max_f32_e32 v120, 0, v120
	v_sqrt_f32_e32 v116, v116
	v_sqrt_f32_e32 v120, v120
	v_mul_f32_e32 v113, v113, v121
	v_mul_f32_e32 v113, v117, v113
	v_mul_f32_e32 v114, v114, v116
	v_mul_f32_e32 v115, v115, v120
	v_mul_f32_e32 v114, v118, v114
	v_mul_f32_e32 v115, v119, v115
	ds_write_b128 v128, v[108:111] offset:25600
	ds_write_b128 v128, v[112:115] offset:58368
	v_add_u32_e32 v108, 0x800, v3
	v_and_b32_e32 v109, 0x3ffff000, v108
	v_and_b32_e32 v108, 0xfc0, v108
	v_lshl_add_u32 v109, v109, 2, 0
	v_lshlrev_b32_e32 v108, 2, v108
	v_add3_u32 v130, v109, v108, v2
	ds_read_b128 v[120:123], v130 offset:25600
	ds_read_b128 v[112:115], v130 offset:58368
	v_add_u32_e32 v108, v127, v108
	ds_read_b128 v[116:119], v108
	s_waitcnt lgkmcnt(2)
	v_mul_f32_e32 v108, 0x3fb8aa3b, v120
	v_exp_f32_e32 v108, v108
	v_add_f32_e32 v109, v120, v120
	v_cmp_nlt_f32_e32 vcc, s75, v109
	s_and_saveexec_b64 s[6:7], vcc
	s_xor_b64 s[6:7], exec, s[6:7]
	v_fma_f32 v120, -v108, v108, 1.0
	s_andn2_saveexec_b64 s[6:7], s[6:7]
	v_fmamk_f32 v110, v109, 0x3c088889, v125
	v_fmaak_f32 v110, v109, v110, 0x3e2aaaab
	v_fma_f32 v110, v109, v110, 0.5
	v_fma_f32 v110, v109, v110, 1.0
	v_mul_f32_e64 v120, v110, -v109
	s_or_b64 exec, exec, s[6:7]
	v_mul_f32_e32 v109, 0x3fb8aa3b, v121
	v_exp_f32_e32 v109, v109
	v_add_f32_e32 v110, v121, v121
	v_cmp_nlt_f32_e32 vcc, s75, v110
	s_and_saveexec_b64 s[6:7], vcc
	s_xor_b64 s[6:7], exec, s[6:7]
	v_fma_f32 v121, -v109, v109, 1.0
	s_andn2_saveexec_b64 s[6:7], s[6:7]
	v_fmamk_f32 v111, v110, 0x3c088889, v125
	v_fmaak_f32 v111, v110, v111, 0x3e2aaaab
	v_fma_f32 v111, v110, v111, 0.5
	v_fma_f32 v111, v110, v111, 1.0
	v_mul_f32_e64 v121, v111, -v110
	s_or_b64 exec, exec, s[6:7]
	v_mul_f32_e32 v110, 0x3fb8aa3b, v122
	v_exp_f32_e32 v110, v110
	v_add_f32_e32 v111, v122, v122
	v_cmp_nlt_f32_e32 vcc, s75, v111
	s_and_saveexec_b64 s[6:7], vcc
	s_xor_b64 s[6:7], exec, s[6:7]
	v_fma_f32 v122, -v110, v110, 1.0
	s_andn2_saveexec_b64 s[6:7], s[6:7]
	v_fmamk_f32 v122, v111, 0x3c088889, v125
	v_fmaak_f32 v122, v111, v122, 0x3e2aaaab
	v_fma_f32 v122, v111, v122, 0.5
	v_fma_f32 v122, v111, v122, 1.0
	v_mul_f32_e64 v122, v122, -v111
	s_or_b64 exec, exec, s[6:7]
	v_mul_f32_e32 v111, 0x3fb8aa3b, v123
	v_exp_f32_e32 v111, v111
	v_add_f32_e32 v131, v123, v123
	v_cmp_nlt_f32_e32 vcc, s75, v131
	s_and_saveexec_b64 s[6:7], vcc
	s_xor_b64 s[6:7], exec, s[6:7]
	v_fma_f32 v123, -v111, v111, 1.0
	s_andn2_saveexec_b64 s[6:7], s[6:7]
	v_fmamk_f32 v123, v131, 0x3c088889, v125
	v_fmaak_f32 v123, v131, v123, 0x3e2aaaab
	v_fma_f32 v123, v131, v123, 0.5
	v_fma_f32 v123, v131, v123, 1.0
	v_mul_f32_e64 v123, v123, -v131
	s_or_b64 exec, exec, s[6:7]
	v_max_f32_e32 v120, v120, v120
	v_max_f32_e32 v120, 0, v120
	v_sqrt_f32_e32 v120, v120
	v_max_f32_e32 v121, v121, v121
	v_max_f32_e32 v121, 0, v121
	v_sqrt_f32_e32 v121, v121
	s_waitcnt lgkmcnt(1)
	v_mul_f32_e32 v112, v112, v120
	s_waitcnt lgkmcnt(0)
	v_mul_f32_e32 v112, v116, v112
	v_max_f32_e32 v116, v122, v122
	v_max_f32_e32 v120, v123, v123
	v_max_f32_e32 v116, 0, v116
	v_max_f32_e32 v120, 0, v120
	v_sqrt_f32_e32 v116, v116
	v_sqrt_f32_e32 v120, v120
	v_mul_f32_e32 v113, v113, v121
	v_mul_f32_e32 v113, v117, v113
	v_mul_f32_e32 v114, v114, v116
	v_mul_f32_e32 v115, v115, v120
	v_mul_f32_e32 v114, v118, v114
	v_mul_f32_e32 v115, v119, v115
	ds_write_b128 v130, v[108:111] offset:25600
	ds_write_b128 v130, v[112:115] offset:58368
	ds_read_b128 v[120:123], v128 offset:41984
	v_add_u32_e32 v130, 0xe400, v128
	ds_read_b128 v[112:115], v130 offset:16384
	ds_read_b128 v[116:119], v129
	s_waitcnt lgkmcnt(2)
	v_mul_f32_e32 v108, 0x3fb8aa3b, v120
	v_exp_f32_e32 v108, v108
	v_add_f32_e32 v109, v120, v120
	v_cmp_nlt_f32_e32 vcc, s75, v109
	s_and_saveexec_b64 s[6:7], vcc
	s_xor_b64 s[6:7], exec, s[6:7]
	v_fma_f32 v120, -v108, v108, 1.0
	s_andn2_saveexec_b64 s[6:7], s[6:7]
	v_fmamk_f32 v110, v109, 0x3c088889, v125
	v_fmaak_f32 v110, v109, v110, 0x3e2aaaab
	v_fma_f32 v110, v109, v110, 0.5
	v_fma_f32 v110, v109, v110, 1.0
	v_mul_f32_e64 v120, v110, -v109
	s_or_b64 exec, exec, s[6:7]
	v_mul_f32_e32 v109, 0x3fb8aa3b, v121
	v_exp_f32_e32 v109, v109
	v_add_f32_e32 v110, v121, v121
	v_cmp_nlt_f32_e32 vcc, s75, v110
	s_and_saveexec_b64 s[6:7], vcc
	s_xor_b64 s[6:7], exec, s[6:7]
	v_fma_f32 v121, -v109, v109, 1.0
	s_andn2_saveexec_b64 s[6:7], s[6:7]
	v_fmamk_f32 v111, v110, 0x3c088889, v125
	v_fmaak_f32 v111, v110, v111, 0x3e2aaaab
	v_fma_f32 v111, v110, v111, 0.5
	v_fma_f32 v111, v110, v111, 1.0
	v_mul_f32_e64 v121, v111, -v110
	s_or_b64 exec, exec, s[6:7]
	v_mul_f32_e32 v110, 0x3fb8aa3b, v122
	v_exp_f32_e32 v110, v110
	v_add_f32_e32 v111, v122, v122
	v_cmp_nlt_f32_e32 vcc, s75, v111
	s_and_saveexec_b64 s[6:7], vcc
	s_xor_b64 s[6:7], exec, s[6:7]
	v_fma_f32 v122, -v110, v110, 1.0
	s_andn2_saveexec_b64 s[6:7], s[6:7]
	v_fmamk_f32 v122, v111, 0x3c088889, v125
	v_fmaak_f32 v122, v111, v122, 0x3e2aaaab
	v_fma_f32 v122, v111, v122, 0.5
	v_fma_f32 v122, v111, v122, 1.0
	v_mul_f32_e64 v122, v122, -v111
	s_or_b64 exec, exec, s[6:7]
	v_mul_f32_e32 v111, 0x3fb8aa3b, v123
	v_exp_f32_e32 v111, v111
	v_add_f32_e32 v129, v123, v123
	v_cmp_nlt_f32_e32 vcc, s75, v129
	s_and_saveexec_b64 s[6:7], vcc
	s_xor_b64 s[6:7], exec, s[6:7]
	v_fma_f32 v123, -v111, v111, 1.0
	s_andn2_saveexec_b64 s[6:7], s[6:7]
	v_fmamk_f32 v123, v129, 0x3c088889, v125
	v_fmaak_f32 v123, v129, v123, 0x3e2aaaab
	v_fma_f32 v123, v129, v123, 0.5
	v_fma_f32 v123, v129, v123, 1.0
	v_mul_f32_e64 v123, v123, -v129
	s_or_b64 exec, exec, s[6:7]
	v_max_f32_e32 v120, v120, v120
	v_max_f32_e32 v120, 0, v120
	v_sqrt_f32_e32 v120, v120
	v_max_f32_e32 v121, v121, v121
	v_max_f32_e32 v121, 0, v121
	v_sqrt_f32_e32 v121, v121
	s_waitcnt lgkmcnt(1)
	v_mul_f32_e32 v112, v112, v120
	s_waitcnt lgkmcnt(0)
	v_mul_f32_e32 v112, v116, v112
	v_max_f32_e32 v116, v122, v122
	v_max_f32_e32 v120, v123, v123
	v_max_f32_e32 v116, 0, v116
	v_max_f32_e32 v120, 0, v120
	v_sqrt_f32_e32 v116, v116
	v_sqrt_f32_e32 v120, v120
	v_mul_f32_e32 v113, v113, v121
	v_add_u32_e32 v3, 0x1800, v3
	v_mul_f32_e32 v114, v114, v116
	v_mul_f32_e32 v115, v115, v120
	v_mul_f32_e32 v113, v117, v113
	v_mul_f32_e32 v114, v118, v114
	v_mul_f32_e32 v115, v119, v115
	ds_write_b128 v128, v[108:111] offset:41984
	ds_write_b128 v130, v[112:115] offset:16384
	v_and_b32_e32 v108, 0x3ffff000, v3
	v_and_b32_e32 v3, 0xfc0, v3
	v_lshl_add_u32 v108, v108, 2, 0
	v_lshlrev_b32_e32 v3, 2, v3
	v_add3_u32 v2, v108, v3, v2
	ds_read_b128 v[120:123], v2 offset:25600
	ds_read_b128 v[112:115], v2 offset:58368
	v_add_u32_e32 v3, v127, v3
	ds_read_b128 v[116:119], v3
	s_waitcnt lgkmcnt(2)
	v_mul_f32_e32 v3, 0x3fb8aa3b, v120
	v_exp_f32_e32 v108, v3
	v_add_f32_e32 v109, v120, v120
	v_cmp_nlt_f32_e32 vcc, s75, v109
	s_and_saveexec_b64 s[6:7], vcc
	s_xor_b64 s[6:7], exec, s[6:7]
	v_fma_f32 v3, -v108, v108, 1.0
	s_andn2_saveexec_b64 s[6:7], s[6:7]
	v_fmamk_f32 v3, v109, 0x3c088889, v125
	v_fmaak_f32 v3, v109, v3, 0x3e2aaaab
	v_fma_f32 v3, v109, v3, 0.5
	v_fma_f32 v3, v109, v3, 1.0
	v_mul_f32_e64 v3, v3, -v109
	s_or_b64 exec, exec, s[6:7]
	v_mul_f32_e32 v109, 0x3fb8aa3b, v121
	v_exp_f32_e32 v109, v109
	v_add_f32_e32 v110, v121, v121
	v_cmp_nlt_f32_e32 vcc, s75, v110
	s_and_saveexec_b64 s[6:7], vcc
	s_xor_b64 s[6:7], exec, s[6:7]
	v_fma_f32 v121, -v109, v109, 1.0
	s_andn2_saveexec_b64 s[6:7], s[6:7]
	v_fmamk_f32 v111, v110, 0x3c088889, v125
	v_fmaak_f32 v111, v110, v111, 0x3e2aaaab
	v_fma_f32 v111, v110, v111, 0.5
	v_fma_f32 v111, v110, v111, 1.0
	v_mul_f32_e64 v121, v111, -v110
	s_or_b64 exec, exec, s[6:7]
	v_mul_f32_e32 v110, 0x3fb8aa3b, v122
	v_exp_f32_e32 v110, v110
	v_add_f32_e32 v111, v122, v122
	v_cmp_nlt_f32_e32 vcc, s75, v111
	s_and_saveexec_b64 s[6:7], vcc
	s_xor_b64 s[6:7], exec, s[6:7]
	v_fma_f32 v122, -v110, v110, 1.0
	s_andn2_saveexec_b64 s[6:7], s[6:7]
	v_fmamk_f32 v120, v111, 0x3c088889, v125
	v_fmaak_f32 v120, v111, v120, 0x3e2aaaab
	v_fma_f32 v120, v111, v120, 0.5
	v_fma_f32 v120, v111, v120, 1.0
	v_mul_f32_e64 v122, v120, -v111
	s_or_b64 exec, exec, s[6:7]
	v_mul_f32_e32 v111, 0x3fb8aa3b, v123
	v_exp_f32_e32 v111, v111
	v_add_f32_e32 v120, v123, v123
	v_cmp_nlt_f32_e32 vcc, s75, v120
	s_and_saveexec_b64 s[6:7], vcc
	s_xor_b64 s[6:7], exec, s[6:7]
	v_fma_f32 v123, -v111, v111, 1.0
	s_andn2_saveexec_b64 s[6:7], s[6:7]
	v_fmamk_f32 v123, v120, 0x3c088889, v125
	v_fmaak_f32 v123, v120, v123, 0x3e2aaaab
	v_fma_f32 v123, v120, v123, 0.5
	v_fma_f32 v123, v120, v123, 1.0
	v_mul_f32_e64 v123, v123, -v120
	s_or_b64 exec, exec, s[6:7]
	v_max_f32_e32 v3, v3, v3
	v_max_f32_e32 v3, 0, v3
	v_sqrt_f32_e32 v3, v3
	v_max_f32_e32 v121, v121, v121
	v_max_f32_e32 v121, 0, v121
	v_mov_b32_e32 v120, 0
	s_waitcnt lgkmcnt(1)
	v_mul_f32_e32 v3, v112, v3
	v_sqrt_f32_e32 v112, v121
	v_max_f32_e32 v121, v122, v122
	v_max_f32_e32 v121, 0, v121
	v_sqrt_f32_e32 v121, v121
	s_waitcnt lgkmcnt(0)
	v_mul_f32_e32 v116, v116, v3
	v_mul_f32_e32 v3, v113, v112
	v_mul_f32_e32 v117, v117, v3
	v_mul_f32_e32 v3, v114, v121
	v_mul_f32_e32 v118, v118, v3
	v_max_f32_e32 v3, v123, v123
	v_max_f32_e32 v3, 0, v3
	v_sqrt_f32_e32 v3, v3
	v_ashrrev_i32_e32 v114, 7, v0
	v_and_b32_e32 v121, 0x7f, v0
	v_bfe_u32 v113, v0, 6, 1
	v_mul_f32_e32 v3, v115, v3
	v_mul_f32_e32 v119, v119, v3
	ds_write_b128 v2, v[108:111] offset:25600
	ds_write_b128 v2, v[116:119] offset:58368
	v_lshlrev_b32_e32 v2, 4, v114
	v_or_b32_e32 v115, 2, v2
	v_and_b32_e32 v112, 63, v0
	v_cmp_gt_u32_e32 vcc, 64, v121
	v_sub_u32_e32 v116, 63, v115
	v_lshl_or_b32 v3, v113, 12, v112
	v_cndmask_b32_e32 v115, v116, v115, vcc
	v_lshl_add_u32 v115, v115, 6, v3
	v_lshl_add_u32 v115, v115, 2, 0
	s_waitcnt lgkmcnt(0)
	s_barrier
	ds_read2st64_b32 v[116:117], v115 offset0:100 offset1:228
	v_or_b32_e32 v115, 3, v2
	v_sub_u32_e32 v118, 63, v115
	v_cndmask_b32_e32 v115, v118, v115, vcc
	v_lshl_add_u32 v115, v115, 6, v3
	v_lshl_add_u32 v115, v115, 2, 0
	ds_read2st64_b32 v[118:119], v115 offset0:100 offset1:228
	v_or_b32_e32 v115, 4, v2
	v_sub_u32_e32 v122, 63, v115
	v_cndmask_b32_e32 v115, v122, v115, vcc
	v_lshl_add_u32 v115, v115, 6, v3
	v_lshl_add_u32 v115, v115, 2, 0
	ds_read2st64_b32 v[122:123], v115 offset0:100 offset1:228
	v_or_b32_e32 v115, 5, v2
	v_sub_u32_e32 v127, 63, v115
	v_cndmask_b32_e32 v115, v127, v115, vcc
	v_lshl_add_u32 v115, v115, 6, v3
	v_lshl_add_u32 v115, v115, 2, 0
	ds_read2st64_b32 v[128:129], v115 offset0:100 offset1:228
	v_or_b32_e32 v115, 6, v2
	v_sub_u32_e32 v127, 63, v115
	v_cndmask_b32_e32 v115, v127, v115, vcc
	v_lshl_add_u32 v115, v115, 6, v3
	v_lshl_add_u32 v115, v115, 2, 0
	ds_read2st64_b32 v[130:131], v115 offset0:100 offset1:228
	v_or_b32_e32 v115, 7, v2
	v_sub_u32_e32 v127, 63, v115
	v_cndmask_b32_e32 v115, v127, v115, vcc
	v_lshl_add_u32 v115, v115, 6, v3
	v_lshl_add_u32 v115, v115, 2, 0
	ds_read2st64_b32 v[132:133], v115 offset0:100 offset1:228
	v_or_b32_e32 v115, 8, v2
	v_sub_u32_e32 v127, 63, v115
	v_cndmask_b32_e32 v115, v127, v115, vcc
	v_lshl_add_u32 v115, v115, 6, v3
	v_lshl_add_u32 v115, v115, 2, 0
	ds_read2st64_b32 v[134:135], v115 offset0:100 offset1:228
	v_or_b32_e32 v115, 9, v2
	v_sub_u32_e32 v127, 63, v115
	v_cndmask_b32_e32 v115, v127, v115, vcc
	v_lshl_add_u32 v115, v115, 6, v3
	v_lshl_add_u32 v115, v115, 2, 0
	ds_read2st64_b32 v[136:137], v115 offset0:100 offset1:228
	v_or_b32_e32 v115, 10, v2
	v_sub_u32_e32 v127, 63, v115
	v_cndmask_b32_e32 v115, v127, v115, vcc
	v_lshl_add_u32 v115, v115, 6, v3
	v_lshl_add_u32 v115, v115, 2, 0
	ds_read2st64_b32 v[138:139], v115 offset0:100 offset1:228
	v_or_b32_e32 v115, 11, v2
	v_sub_u32_e32 v127, 63, v115
	v_cndmask_b32_e32 v115, v127, v115, vcc
	v_lshl_add_u32 v115, v115, 6, v3
	v_lshl_add_u32 v115, v115, 2, 0
	v_sub_u32_e32 v108, 63, v2
	v_or_b32_e32 v110, 1, v2
	ds_read2st64_b32 v[140:141], v115 offset0:100 offset1:228
	v_or_b32_e32 v115, 12, v2
	v_cndmask_b32_e32 v108, v108, v2, vcc
	v_sub_u32_e32 v111, 63, v110
	v_sub_u32_e32 v127, 63, v115
	v_lshl_add_u32 v108, v108, 6, v3
	v_cndmask_b32_e32 v110, v111, v110, vcc
	v_cndmask_b32_e32 v115, v127, v115, vcc
	v_lshl_add_u32 v108, v108, 2, 0
	v_lshl_add_u32 v110, v110, 6, v3
	v_lshl_add_u32 v115, v115, 6, v3
	ds_read2st64_b32 v[108:109], v108 offset0:100 offset1:228
	v_lshl_add_u32 v110, v110, 2, 0
	v_lshl_add_u32 v115, v115, 2, 0
	ds_read2st64_b32 v[110:111], v110 offset0:100 offset1:228
	ds_read2st64_b32 v[142:143], v115 offset0:100 offset1:228
	v_or_b32_e32 v115, 13, v2
	v_sub_u32_e32 v127, 63, v115
	v_cndmask_b32_e32 v115, v127, v115, vcc
	v_lshl_add_u32 v115, v115, 6, v3
	v_lshl_add_u32 v115, v115, 2, 0
	s_waitcnt lgkmcnt(2)
	v_fma_f32 v109, 0, v108, v109
	ds_read2st64_b32 v[144:145], v115 offset0:100 offset1:228
	v_or_b32_e32 v115, 14, v2
	s_waitcnt lgkmcnt(2)
	v_mul_f32_e32 v108, v108, v110
	v_fmac_f32_e32 v111, v109, v110
	v_sub_u32_e32 v127, 63, v115
	v_mul_f32_e32 v108, v108, v116
	v_fmac_f32_e32 v117, v111, v116
	v_cndmask_b32_e32 v115, v127, v115, vcc
	v_mul_f32_e32 v108, v108, v118
	v_fmac_f32_e32 v119, v117, v118
	v_lshl_add_u32 v115, v115, 6, v3
	v_mul_f32_e32 v108, v108, v122
	v_fmac_f32_e32 v123, v119, v122
	v_lshl_add_u32 v115, v115, 2, 0
	v_or_b32_e32 v2, 15, v2
	v_mul_f32_e32 v108, v108, v128
	v_fmac_f32_e32 v129, v123, v128
	ds_read2st64_b32 v[146:147], v115 offset0:100 offset1:228
	v_sub_u32_e32 v115, 63, v2
	v_mul_f32_e32 v108, v108, v130
	v_fmac_f32_e32 v131, v129, v130
	v_cndmask_b32_e32 v2, v115, v2, vcc
	v_mul_f32_e32 v108, v108, v132
	v_fmac_f32_e32 v133, v131, v132
	v_lshl_add_u32 v2, v2, 6, v3
	v_mul_f32_e32 v108, v108, v134
	v_fmac_f32_e32 v135, v133, v134
	v_lshl_add_u32 v2, v2, 2, 0
	v_mul_f32_e32 v108, v108, v136
	v_fmac_f32_e32 v137, v135, v136
	ds_read2st64_b32 v[2:3], v2 offset0:100 offset1:228
	v_mul_f32_e32 v108, v108, v138
	v_fmac_f32_e32 v139, v137, v138
	v_mul_f32_e32 v108, v108, v140
	v_fmac_f32_e32 v141, v139, v140
	s_waitcnt lgkmcnt(3)
	v_mul_f32_e32 v108, v108, v142
	v_fmac_f32_e32 v143, v141, v142
	s_waitcnt lgkmcnt(2)
	v_mul_f32_e32 v108, v108, v144
	v_fmac_f32_e32 v145, v143, v144
	s_waitcnt lgkmcnt(1)
	v_mul_f32_e32 v108, v108, v146
	v_fmac_f32_e32 v147, v145, v146
	v_lshl_add_u32 v0, v0, 2, 0
	s_waitcnt lgkmcnt(0)
	v_mul_f32_e32 v108, v108, v2
	v_fmac_f32_e32 v3, v147, v2
	v_add_u32_e32 v2, 0x16400, v0
	v_add_u32_e32 v0, 0x16c00, v0
	ds_write_b32 v2, v108
	ds_write_b32 v0, v3
	v_cmp_lt_i32_e32 vcc, 0, v114
	v_mov_b32_e32 v0, 1.0
	v_lshl_add_u32 v2, v121, 2, 0
	s_waitcnt vmcnt(0) lgkmcnt(0)
	s_barrier
	s_and_saveexec_b64 s[6:7], vcc
	s_cbranch_execnz .LBB0_434
	s_or_b64 exec, exec, s[6:7]
	v_cmp_lt_i32_e32 vcc, 1, v114
	s_and_saveexec_b64 s[6:7], vcc
	s_cbranch_execnz .LBB0_435

.LBB0_609:
	s_waitcnt vmcnt(0)
	v_mov_b32_e32 v2, v0
	v_mov_b32_e32 v3, v0
	v_mov_b32_e32 v1, v0
	v_mov_b32_e32 v68, 0
	v_mov_b64_e32 v[114:115], v[2:3]
	v_mov_b32_e32 v150, 0
	v_readlane_b32 s12, v238, 15
	s_mov_b32 s13, s3
	s_mov_b32 s2, s97
	v_mov_b64_e32 v[112:113], v[0:1]
	v_mov_b32_e32 v69, v68
	v_mov_b32_e32 v70, v68
	v_mov_b32_e32 v71, v68
	v_mov_b32_e32 v96, v68
	v_mov_b32_e32 v97, v68
	v_mov_b32_e32 v98, v68
	v_mov_b32_e32 v99, v68
	v_mov_b32_e32 v104, v68
	v_mov_b32_e32 v105, v68
	v_mov_b32_e32 v106, v68
	v_mov_b32_e32 v107, v68
	v_mov_b32_e32 v108, v68
	v_mov_b32_e32 v109, v68
	v_mov_b32_e32 v110, v68
	v_mov_b32_e32 v111, v68
	s_branch .LBB0_612
.LBB0_610:
	s_or_b64 exec, exec, s[6:7]
	v_lshlrev_b32_e32 v153, 14, v153
	v_lshlrev_b32_e32 v154, 2, v154
	v_add3_u32 v153, 0, v153, v154
	v_fmac_f32_e32 v117, v116, v152
	v_lshl_add_u32 v116, v155, 8, v153
	ds_write_b32 v116, v117 offset:58368
	v_fmac_f32_e32 v119, v118, v117
	v_lshl_add_u32 v116, v157, 8, v153
	ds_write_b32 v116, v119 offset:58368
	v_fmac_f32_e32 v121, v120, v119
	v_lshl_add_u32 v116, v158, 8, v153
	ds_write_b32 v116, v121 offset:58368
	v_fmac_f32_e32 v123, v122, v121
	v_lshl_add_u32 v116, v159, 8, v153
	ds_write_b32 v116, v123 offset:58368
	v_fmac_f32_e32 v125, v124, v123
	v_lshl_add_u32 v116, v160, 8, v153
	ds_write_b32 v116, v125 offset:58368
	v_fmac_f32_e32 v127, v126, v125
	v_lshl_add_u32 v116, v161, 8, v153
	ds_write_b32 v116, v127 offset:58368
	v_fmac_f32_e32 v129, v128, v127
	v_lshl_add_u32 v116, v162, 8, v153
	ds_write_b32 v116, v129 offset:58368
	v_fmac_f32_e32 v131, v130, v129
	v_lshl_add_u32 v116, v163, 8, v153
	ds_write_b32 v116, v131 offset:58368
	v_fmac_f32_e32 v133, v132, v131
	v_lshl_add_u32 v116, v164, 8, v153
	ds_write_b32 v116, v133 offset:58368
	v_fmac_f32_e32 v135, v134, v133
	v_lshl_add_u32 v116, v165, 8, v153
	ds_write_b32 v116, v135 offset:58368
	v_fmac_f32_e32 v137, v136, v135
	v_lshl_add_u32 v116, v166, 8, v153
	ds_write_b32 v116, v137 offset:58368
	v_fmac_f32_e32 v139, v138, v137
	v_lshl_add_u32 v116, v167, 8, v153
	ds_write_b32 v116, v139 offset:58368
	v_fmac_f32_e32 v141, v140, v139
	v_lshl_add_u32 v116, v168, 8, v153
	ds_write_b32 v116, v141 offset:58368
	v_fmac_f32_e32 v143, v142, v141
	v_lshl_add_u32 v116, v169, 8, v153
	ds_write_b32 v116, v143 offset:58368
	v_fmac_f32_e32 v145, v144, v143
	v_lshl_add_u32 v116, v170, 8, v153
	ds_write_b32 v116, v145 offset:58368
	v_fmac_f32_e32 v147, v146, v145
	v_lshl_add_u32 v116, v171, 8, v153
	v_lshlrev_b32_e32 v132, 16, v112
	ds_write_b32 v116, v147 offset:58368
	v_mul_f32_e32 v116, 0x3d372713, v132
	v_mul_f32_e32 v116, v116, v132
	v_mov_b32_e32 v117, v132
	v_fmac_f32_e32 v117, v116, v117
	v_mul_f32_e32 v116, 0x3f4c422a, v117
	v_lshlrev_b32_e32 v117, 2, v1
	v_and_b32_e32 v133, 0xffff0000, v112
	v_add3_u32 v128, v151, v117, s46
	v_mul_f32_e32 v117, 0x3d372713, v133
	v_mul_f32_e32 v117, v117, v133
	v_mov_b32_e32 v118, v133
	v_fmac_f32_e32 v118, v117, v118
	v_add_f32_e32 v116, v116, v116
	v_mul_f32_e32 v117, 0x3f4c422a, v118
	v_mul_f32_e32 v116, 0x3fb8aa3b, v116
	v_add_f32_e32 v117, v117, v117
	v_exp_f32_e32 v116, v116
	v_mul_f32_e32 v117, 0x3fb8aa3b, v117
	v_exp_f32_e32 v124, v117
	s_waitcnt lgkmcnt(0)
	v_add_f32_e32 v116, 1.0, v116
	s_barrier
	v_rcp_f32_e32 v134, v116
	ds_read_b128 v[116:119], v3 offset:58368
	ds_read_b128 v[120:123], v128 offset:16384
	v_add_f32_e32 v124, 1.0, v124
	v_rcp_f32_e32 v135, v124
	ds_read_b128 v[124:127], v3 offset:58384
	ds_read_b128 v[128:131], v128 offset:16400
	v_pk_mul_f32 v[132:133], v[132:133], 0.5 op_sel_hi:[1,0]
	s_waitcnt lgkmcnt(2)
	v_pk_add_f32 v[116:117], v[116:117], v[120:121]
	v_pk_fma_f32 v[120:121], v[134:135], 2.0, 1.0 op_sel_hi:[1,0,0] neg_lo:[1,0,0] neg_hi:[1,0,0]
	v_lshlrev_b32_e32 v134, 16, v113
	v_mul_f32_e32 v3, 0x3d372713, v134
	v_mul_f32_e32 v3, v3, v134
	v_mov_b32_e32 v136, v134
	v_and_b32_e32 v135, 0xffff0000, v113
	v_fmac_f32_e32 v136, v3, v136
	v_mul_f32_e32 v3, 0x3f4c422a, v136
	v_mul_f32_e32 v136, 0x3d372713, v135
	v_mul_f32_e32 v136, v136, v135
	v_mov_b32_e32 v137, v135
	v_fmac_f32_e32 v137, v136, v137
	v_add_f32_e32 v3, v3, v3
	v_mul_f32_e32 v136, 0x3f4c422a, v137
	v_mul_f32_e32 v3, 0x3fb8aa3b, v3
	v_add_f32_e32 v136, v136, v136
	v_exp_f32_e32 v3, v3
	v_mul_f32_e32 v136, 0x3fb8aa3b, v136
	v_exp_f32_e32 v137, v136
	v_pk_add_f32 v[120:121], v[120:121], 1.0 op_sel_hi:[1,0]
	v_add_f32_e32 v3, 1.0, v3
	v_rcp_f32_e32 v136, v3
	v_add_f32_e32 v3, 1.0, v137
	v_pk_mul_f32 v[120:121], v[132:133], v[120:121]
	v_lshlrev_b32_e32 v132, 16, v114
	v_rcp_f32_e32 v137, v3
	v_mul_f32_e32 v3, 0x3d372713, v132
	v_pk_add_f32 v[118:119], v[118:119], v[122:123]
	v_pk_mul_f32 v[122:123], v[134:135], 0.5 op_sel_hi:[1,0]
	v_mul_f32_e32 v3, v3, v132
	v_mov_b32_e32 v134, v132
	v_and_b32_e32 v133, 0xffff0000, v114
	v_fmac_f32_e32 v134, v3, v134
	v_mul_f32_e32 v3, 0x3f4c422a, v134
	v_mul_f32_e32 v134, 0x3d372713, v133
	v_mul_f32_e32 v134, v134, v133
	v_mov_b32_e32 v135, v133
	v_fmac_f32_e32 v135, v134, v135
	v_add_f32_e32 v3, v3, v3
	v_mul_f32_e32 v134, 0x3f4c422a, v135
	v_mul_f32_e32 v3, 0x3fb8aa3b, v3
	v_add_f32_e32 v134, v134, v134
	v_exp_f32_e32 v3, v3
	v_mul_f32_e32 v134, 0x3fb8aa3b, v134
	v_exp_f32_e32 v135, v134
	v_pk_mul_f32 v[116:117], v[120:121], v[116:117]
	v_pk_fma_f32 v[120:121], v[136:137], 2.0, 1.0 op_sel_hi:[1,0,0] neg_lo:[1,0,0] neg_hi:[1,0,0]
	v_add_f32_e32 v3, 1.0, v3
	v_pk_add_f32 v[120:121], v[120:121], 1.0 op_sel_hi:[1,0]
	v_rcp_f32_e32 v134, v3
	v_pk_mul_f32 v[120:121], v[122:123], v[120:121]
	v_add_f32_e32 v3, 1.0, v135
	v_pk_mul_f32 v[118:119], v[120:121], v[118:119]
	s_waitcnt lgkmcnt(0)
	v_pk_add_f32 v[120:121], v[124:125], v[128:129]
	v_lshlrev_b32_e32 v128, 16, v115
	v_rcp_f32_e32 v135, v3
	v_mul_f32_e32 v3, 0x3d372713, v128
	v_pk_mul_f32 v[124:125], v[132:133], 0.5 op_sel_hi:[1,0]
	v_mul_f32_e32 v3, v3, v128
	v_mov_b32_e32 v132, v128
	v_and_b32_e32 v129, 0xffff0000, v115
	v_fmac_f32_e32 v132, v3, v132
	v_mul_f32_e32 v3, 0x3f4c422a, v132
	v_mul_f32_e32 v132, 0x3d372713, v129
	v_mul_f32_e32 v132, v132, v129
	v_mov_b32_e32 v133, v129
	v_fmac_f32_e32 v133, v132, v133
	v_add_f32_e32 v3, v3, v3
	v_mul_f32_e32 v132, 0x3f4c422a, v133
	v_mul_f32_e32 v3, 0x3fb8aa3b, v3
	v_add_f32_e32 v132, v132, v132
	v_exp_f32_e32 v3, v3
	v_mul_f32_e32 v132, 0x3fb8aa3b, v132
	v_exp_f32_e32 v133, v132
	s_ashr_i32 s6, s50, 9
	v_add_f32_e32 v3, 1.0, v3
	v_rcp_f32_e32 v132, v3
	v_add_f32_e32 v3, 1.0, v133
	v_rcp_f32_e32 v133, v3
	s_ashr_i32 s7, s6, 31
	s_add_i32 s8, s83, s12
	v_pk_fma_f32 v[122:123], v[134:135], 2.0, 1.0 op_sel_hi:[1,0,0] neg_lo:[1,0,0] neg_hi:[1,0,0]
	s_lshl_b64 s[6:7], s[6:7], 12
	s_and_b32 s8, s8, 0xfc0
	v_pk_add_f32 v[122:123], v[122:123], 1.0 op_sel_hi:[1,0]
	s_or_b32 s6, s6, s8
	v_ashrrev_i32_e32 v3, 31, v2
	v_pk_mul_f32 v[122:123], v[124:125], v[122:123]
	v_pk_fma_f32 v[124:125], v[132:133], 2.0, 1.0 op_sel_hi:[1,0,0] neg_lo:[1,0,0] neg_hi:[1,0,0]
	v_lshl_add_u64 v[2:3], s[6:7], 0, v[2:3]
	s_add_i32 s6, s90, s13
	v_pk_mul_f32 v[120:121], v[122:123], v[120:121]
	v_pk_add_f32 v[122:123], v[126:127], v[130:131]
	v_pk_mul_f32 v[126:127], v[128:129], 0.5 op_sel_hi:[1,0]
	v_pk_add_f32 v[124:125], v[124:125], 1.0 op_sel_hi:[1,0]
	s_and_b32 s6, s6, 0x1c0
	s_add_i32 s2, s50, s22
	v_pk_mul_f32 v[124:125], v[126:127], v[124:125]
	v_or_b32_e32 v1, s6, v1
	v_lshlrev_b64 v[2:3], 11, v[2:3]
	s_add_i32 s13, s13, s88
	s_add_i32 s12, s12, s47
	v_pk_mul_f32 v[122:123], v[124:125], v[122:123]
	v_cvt_pk_bf16_f32 v116, v116, v117
	v_cvt_pk_bf16_f32 v117, v118, v119
	v_cvt_pk_bf16_f32 v118, v120, v121
	v_lshl_add_u64 v[2:3], s[16:17], 0, v[2:3]
	v_lshlrev_b32_e32 v120, 1, v1
	v_mov_b32_e32 v121, v0
	s_cmpk_gt_i32 s2, 0xfff
	v_cvt_pk_bf16_f32 v119, v122, v123
	v_lshl_add_u64 v[2:3], v[2:3], 0, v[120:121]
	s_cselect_b64 s[8:9], -1, 0
	s_waitcnt vmcnt(0)
	global_store_dwordx4 v[2:3], v[116:119], off
	s_barrier

.LBB0_622:
	v_cndmask_b32_e64 v1, 0, 1, s[30:31]
	v_cmp_ne_u32_e64 s[6:7], 1, v1
	s_andn2_b64 vcc, exec, s[30:31]
	s_cbranch_vccnz .LBB0_624
	v_mov_b32_e32 v1, v204
	s_and_b32 s8, s2, 7
	s_lshl_b32 s62, s8, 8
	v_lshlrev_b32_e32 v2, 5, v1
	v_and_b32_e32 v2, 0xe0, v2
	v_or_b32_e32 v2, s62, v2
	v_mov_b32_e32 v3, v0
	s_waitcnt vmcnt(17)
	v_lshl_add_u64 v[12:13], s[24:25], 0, v[2:3]
	s_waitcnt vmcnt(13)
	v_add_co_u32_e32 v24, vcc, s48, v12
	global_load_dwordx4 v[4:7], v2, s[24:25] offset:2064
	global_load_dwordx4 v[8:11], v2, s[24:25] offset:2048
	v_addc_co_u32_e32 v25, vcc, 0, v13, vcc
	global_load_dwordx4 v[12:15], v2, s[54:55]
	global_load_dwordx4 v[16:19], v2, s[56:57]
	global_load_dwordx4 v[20:23], v[24:25], off offset:16
	global_load_dwordx4 v[32:35], v[24:25], off offset:2064
	s_nop 0
	global_load_dwordx4 v[24:27], v2, s[24:25] offset:16
	global_load_dwordx4 v[44:47], v2, s[26:27] offset:16
	global_load_dwordx4 v[36:39], v2, s[24:25]
	global_load_dwordx4 v[48:51], v2, s[26:27]
	s_waitcnt vmcnt(19)
	v_ashrrev_i32_e32 v56, 7, v1
	v_lshrrev_b32_e32 v2, 1, v1
	s_waitcnt vmcnt(15)
	v_and_b32_e32 v82, 32, v2
	v_lshl_or_b32 v2, v56, 3, s8
	v_lshlrev_b32_e32 v56, 11, v56
	v_ashrrev_i32_e32 v3, 31, v2
	v_and_b32_e32 v74, 0x800, v56
	v_mov_b32_e32 v75, v0
	v_lshlrev_b64 v[2:3], 13, v[2:3]
	v_lshl_add_u64 v[56:57], s[52:53], 0, v[74:75]
	v_lshl_add_u64 v[2:3], s[58:59], 0, v[2:3]
	v_and_b32_e32 v72, 48, v1
	v_mov_b32_e32 v73, v0
	v_lshl_add_u64 v[76:77], v[56:57], 0, s[62:63]
	v_and_or_b32 v56, v1, 15, v82
	v_lshl_add_u64 v[2:3], v[2:3], 0, v[72:73]
	v_lshlrev_b32_e32 v78, 7, v56
	v_mov_b32_e32 v79, v0
	v_lshl_add_u64 v[64:65], v[2:3], 0, v[78:79]
	v_mov_b32_e32 v73, s37
	v_mov_b32_e32 v79, s15
	v_cmp_gt_u32_e32 vcc, s49, v1
	v_mov_b32_e32 v1, s36
	v_lshl_or_b32 v72, v82, 2, v72
	v_cndmask_b32_e32 v81, v73, v79, vcc
	v_mov_b32_e32 v73, s14
	v_cndmask_b32_e32 v80, v1, v73, vcc
	v_lshl_add_u64 v[74:75], v[80:81], 0, v[74:75]
	v_lshl_add_u64 v[74:75], v[74:75], 0, s[62:63]
	v_mov_b32_e32 v73, v0
	s_waitcnt vmcnt(14)
	v_lshl_add_u64 v[84:85], v[74:75], 0, v[72:73]
	s_waitcnt vmcnt(12)
	v_lshl_add_u64 v[92:93], v[76:77], 0, v[72:73]
	v_or_b32_e32 v72, 0x800, v78
	v_lshl_add_u64 v[2:3], v[2:3], 0, v[72:73]
	global_load_dwordx4 v[56:59], v[64:65], off
	s_nop 0
	global_load_dwordx4 v[64:67], v[64:65], off offset:64
	s_nop 0
	global_load_dwordx4 v[72:75], v[2:3], off
	global_load_dwordx4 v[76:79], v[2:3], off offset:64
	global_load_dwordx4 v[80:83], v[84:85], off
	s_nop 0
	global_load_dwordx4 v[84:87], v[84:85], off offset:64
	s_nop 0
	global_load_dwordx4 v[88:91], v[92:93], off
	s_nop 0
	global_load_dwordx4 v[92:95], v[92:93], off offset:64
	s_waitcnt vmcnt(0)
.LBB0_624:
	s_nop 0
	v_lshlrev_b32_e32 v2, 16, v40
	v_and_b32_e32 v3, 0xffff0000, v40
	v_pk_fma_f32 v[2:3], v[36:37], v[2:3], v[48:49]
	v_lshlrev_b32_e32 v116, 16, v28
	v_and_b32_e32 v117, 0xffff0000, v28
	v_pk_fma_f32 v[2:3], v[8:9], v[116:117], v[2:3]
	v_lshlrev_b32_e32 v116, 16, v52
	v_and_b32_e32 v117, 0xffff0000, v52
	v_pk_fma_f32 v[2:3], v[12:13], v[116:117], v[2:3]
	v_lshlrev_b32_e32 v116, 16, v60
	v_and_b32_e32 v117, 0xffff0000, v60
	v_pk_fma_f32 v[116:117], v[16:17], v[116:117], v[2:3]
	v_lshlrev_b32_e32 v2, 16, v42
	v_and_b32_e32 v3, 0xffff0000, v42
	v_pk_fma_f32 v[2:3], v[24:25], v[2:3], v[44:45]
	v_lshlrev_b32_e32 v118, 16, v30
	v_and_b32_e32 v119, 0xffff0000, v30
	v_pk_fma_f32 v[2:3], v[4:5], v[118:119], v[2:3]
	v_lshlrev_b32_e32 v118, 16, v54
	v_and_b32_e32 v119, 0xffff0000, v54
	v_pk_fma_f32 v[2:3], v[20:21], v[118:119], v[2:3]
	v_lshlrev_b32_e32 v118, 16, v62
	v_and_b32_e32 v119, 0xffff0000, v62
	v_pk_fma_f32 v[120:121], v[32:33], v[118:119], v[2:3]
	v_lshlrev_b32_e32 v2, 16, v41
	v_and_b32_e32 v3, 0xffff0000, v41
	v_pk_fma_f32 v[2:3], v[38:39], v[2:3], v[50:51]
	v_lshlrev_b32_e32 v118, 16, v29
	v_and_b32_e32 v119, 0xffff0000, v29
	v_pk_fma_f32 v[2:3], v[10:11], v[118:119], v[2:3]
	v_lshlrev_b32_e32 v118, 16, v53
	v_and_b32_e32 v119, 0xffff0000, v53
	v_pk_fma_f32 v[2:3], v[14:15], v[118:119], v[2:3]
	v_lshlrev_b32_e32 v118, 16, v61
	v_and_b32_e32 v119, 0xffff0000, v61
	v_pk_fma_f32 v[118:119], v[18:19], v[118:119], v[2:3]
	v_lshlrev_b32_e32 v2, 16, v43
	v_and_b32_e32 v3, 0xffff0000, v43
	v_pk_fma_f32 v[2:3], v[26:27], v[2:3], v[46:47]
	v_lshlrev_b32_e32 v122, 16, v31
	v_and_b32_e32 v123, 0xffff0000, v31
	v_pk_fma_f32 v[2:3], v[6:7], v[122:123], v[2:3]
	v_lshlrev_b32_e32 v122, 16, v55
	v_and_b32_e32 v123, 0xffff0000, v55
	v_mov_b32_e32 v152, v204
	v_pk_fma_f32 v[2:3], v[22:23], v[122:123], v[2:3]
	v_lshlrev_b32_e32 v122, 16, v63
	v_and_b32_e32 v123, 0xffff0000, v63
	v_pk_fma_f32 v[122:123], v[34:35], v[122:123], v[2:3]
	v_lshlrev_b32_e32 v1, 3, v152
	v_ashrrev_i32_e32 v2, 3, v152
	v_and_b32_e32 v1, 56, v1
	v_lshl_add_u32 v151, v2, 8, 0
	v_lshl_add_u32 v3, v1, 2, v151
	ds_write_b128 v3, v[116:119]
	ds_write_b128 v3, v[120:123] offset:16
	v_cvt_pk_bf16_f32 v116, v116, v117
	v_cvt_pk_bf16_f32 v117, v118, v119
	v_cvt_pk_bf16_f32 v118, v120, v121
	v_mul_lo_u32 v120, v2, s1
	v_lshlrev_b32_e32 v121, 1, v1
	v_and_b32_e32 v162, 15, v152
	v_cvt_pk_bf16_f32 v119, v122, v123
	v_add3_u32 v120, v151, v120, v121
	v_and_b32_e32 v153, 48, v152
	ds_write_b128 v120, v[116:119] offset:16384
	v_mul_u32_u24_e32 v116, 0x90, v162
	v_add3_u32 v163, 0, v153, v116
	s_waitcnt lgkmcnt(0)
	s_barrier
	ds_read_b128 v[128:131], v163 offset:20992
	s_waitcnt lgkmcnt(0)
	v_mfma_f32_16x16x32_bf16 v[136:139], v[56:59], v[128:131], 0
	ds_read_b128 v[116:119], v163 offset:16384
	ds_read_b128 v[124:127], v163 offset:18688
	s_add_i32 s51, 0, 0xe400
	v_mfma_f32_16x16x32_bf16 v[140:143], v[72:75], v[128:131], 0
	ds_read_b128 v[128:131], v163 offset:23296
	v_cmp_gt_u32_e32 vcc, s49, v152
	s_waitcnt lgkmcnt(0)
	v_mfma_f32_16x16x32_bf16 v[144:147], v[56:59], v[128:131], 0
	v_mfma_f32_16x16x32_bf16 v[154:157], v[72:75], v[128:131], 0
	ds_read_b128 v[128:131], v163 offset:16448
	v_mfma_f32_16x16x32_bf16 v[120:123], v[56:59], v[116:119], 0
	v_mfma_f32_16x16x32_bf16 v[116:119], v[72:75], v[116:119], 0
	s_waitcnt lgkmcnt(0)
	v_mfma_f32_16x16x32_bf16 v[158:161], v[64:67], v[128:131], v[120:123]
	v_mfma_f32_16x16x32_bf16 v[128:131], v[76:79], v[128:131], v[116:119]
	s_nop 4
	ds_read_b128 v[116:119], v163 offset:18752
	v_mfma_f32_16x16x32_bf16 v[132:135], v[56:59], v[124:127], 0
	s_nop 0
	v_add_f32_e32 v128, v84, v128
	v_mul_f32_e32 v128, 0xbfb8aa3b, v128
	v_exp_f32_e32 v128, v128
	v_mfma_f32_16x16x32_bf16 v[124:127], v[72:75], v[124:127], 0
	v_add_f32_e32 v129, v85, v129
	v_mul_f32_e32 v129, 0xbfb8aa3b, v129
	v_exp_f32_e32 v129, v129
	s_waitcnt lgkmcnt(0)
	v_mfma_f32_16x16x32_bf16 v[132:135], v[64:67], v[116:119], v[132:135]
	v_add_f32_e32 v130, v86, v130
	v_mul_f32_e32 v130, 0xbfb8aa3b, v130
	v_add_f32_e32 v128, 1.0, v128
	v_mfma_f32_16x16x32_bf16 v[124:127], v[76:79], v[116:119], v[124:127]
	ds_read_b128 v[116:119], v163 offset:21056
	s_nop 2
	v_add_f32_e32 v132, v80, v132
	v_mul_f32_e32 v132, 0xbfb8aa3b, v132
	s_waitcnt lgkmcnt(0)
	v_mfma_f32_16x16x32_bf16 v[136:139], v[64:67], v[116:119], v[136:139]
	v_exp_f32_e32 v132, v132
	v_add_f32_e32 v133, v81, v133
	v_mul_f32_e32 v133, 0xbfb8aa3b, v133
	v_mfma_f32_16x16x32_bf16 v[120:123], v[76:79], v[116:119], v[140:143]
	ds_read_b128 v[116:119], v163 offset:23360
	v_exp_f32_e32 v133, v133
	v_add_f32_e32 v134, v82, v134
	s_waitcnt lgkmcnt(0)
	v_mfma_f32_16x16x32_bf16 v[140:143], v[64:67], v[116:119], v[144:147]
	v_mul_f32_e32 v134, 0xbfb8aa3b, v134
	s_nop 1
	v_mov_b32_e32 v144, s51
	v_mov_b32_e32 v145, s81
	v_cndmask_b32_e32 v144, v144, v145, vcc
	v_lshlrev_b32_e32 v145, 7, v152
	v_and_b32_e32 v145, 0x4000, v145
	v_lshlrev_b32_e32 v146, 8, v162
	v_add3_u32 v144, v144, v145, v146
	v_add_f32_e32 v146, v80, v158
	v_mul_f32_e32 v146, 0xbfb8aa3b, v146
	v_add_f32_e32 v147, v81, v159
	v_exp_f32_e32 v146, v146
	v_mul_f32_e32 v147, 0xbfb8aa3b, v147
	v_exp_f32_e32 v147, v147
	v_lshlrev_b32_e32 v145, 1, v152
	v_and_b32_e32 v145, 0x80, v145
	v_add_f32_e32 v146, 1.0, v146
	v_rcp_f32_e32 v146, v146
	v_add3_u32 v153, v144, v145, v153
	v_add_f32_e32 v144, 1.0, v147
	v_add_f32_e32 v147, v82, v160
	v_mul_f32_e32 v147, 0xbfb8aa3b, v147
	v_mfma_f32_16x16x32_bf16 v[116:119], v[76:79], v[116:119], v[154:157]
	v_rcp_f32_e32 v145, v144
	v_exp_f32_e32 v147, v147
	v_mul_f32_e32 v144, 0xc1000000, v146
	v_add_f32_e32 v154, v83, v161
	v_mul_f32_e32 v154, 0xbfb8aa3b, v154
	v_exp_f32_e32 v154, v154
	s_nop 0
	v_mul_f32_e32 v144, v88, v144
	v_cndmask_b32_e32 v144, v146, v144, vcc
	v_mul_f32_e32 v146, 0xc1000000, v145
	v_add_f32_e32 v147, 1.0, v147
	v_mul_f32_e32 v146, v89, v146
	v_rcp_f32_e32 v147, v147
	v_cndmask_b32_e32 v145, v145, v146, vcc
	v_add_f32_e32 v146, 1.0, v154
	v_rcp_f32_e32 v154, v146
	v_mul_f32_e32 v146, 0xc1000000, v147
	v_add_f32_e32 v132, 1.0, v132
	v_exp_f32_e32 v134, v134
	v_add_f32_e32 v135, v83, v135
	v_mul_f32_e32 v146, v90, v146
	v_rcp_f32_e32 v132, v132
	v_mul_f32_e32 v135, 0xbfb8aa3b, v135
	v_cndmask_b32_e32 v146, v147, v146, vcc
	v_mul_f32_e32 v147, 0xc1000000, v154
	v_add_f32_e32 v133, 1.0, v133
	v_exp_f32_e32 v135, v135
	v_mul_f32_e32 v147, v91, v147
	v_rcp_f32_e32 v133, v133
	v_cndmask_b32_e32 v147, v154, v147, vcc
	v_add_f32_e32 v134, 1.0, v134
	v_add_f32_e32 v136, v80, v136
	ds_write_b128 v153, v[144:147]
	v_mul_f32_e32 v144, 0xc1000000, v132
	v_rcp_f32_e32 v134, v134
	v_mul_f32_e32 v136, 0xbfb8aa3b, v136
	v_mul_f32_e32 v144, v88, v144
	v_add_f32_e32 v135, 1.0, v135
	v_exp_f32_e32 v136, v136
	v_cndmask_b32_e32 v132, v132, v144, vcc
	v_mul_f32_e32 v144, 0xc1000000, v133
	v_rcp_f32_e32 v135, v135
	v_mul_f32_e32 v144, v89, v144
	v_add_f32_e32 v137, v81, v137
	v_cndmask_b32_e32 v133, v133, v144, vcc
	v_mul_f32_e32 v144, 0xc1000000, v134
	v_mul_f32_e32 v137, 0xbfb8aa3b, v137
	v_mul_f32_e32 v144, v90, v144
	v_exp_f32_e32 v137, v137
	v_add_f32_e32 v136, 1.0, v136
	v_cndmask_b32_e32 v134, v134, v144, vcc
	v_mul_f32_e32 v144, 0xc1000000, v135
	v_rcp_f32_e32 v136, v136
	v_mul_f32_e32 v144, v91, v144
	v_cndmask_b32_e32 v135, v135, v144, vcc
	ds_write_b128 v153, v[132:135] offset:4096
	v_add_f32_e32 v132, 1.0, v137
	v_rcp_f32_e32 v133, v132
	v_mul_f32_e32 v132, 0xc1000000, v136
	v_add_f32_e32 v135, v82, v138
	v_mul_f32_e32 v132, v88, v132
	v_mul_f32_e32 v135, 0xbfb8aa3b, v135
	v_cndmask_b32_e32 v132, v136, v132, vcc
	v_exp_f32_e32 v135, v135
	v_add_f32_e32 v136, v83, v139
	v_mul_f32_e32 v136, 0xbfb8aa3b, v136
	v_exp_f32_e32 v136, v136
	v_mul_f32_e32 v134, 0xc1000000, v133
	v_add_f32_e32 v135, 1.0, v135
	v_mul_f32_e32 v134, v89, v134
	v_rcp_f32_e32 v135, v135
	v_cndmask_b32_e32 v133, v133, v134, vcc
	v_add_f32_e32 v134, 1.0, v136
	v_rcp_f32_e32 v136, v134
	v_mul_f32_e32 v134, 0xc1000000, v135
	v_mul_f32_e32 v134, v90, v134
	v_cndmask_b32_e32 v134, v135, v134, vcc
	v_mul_f32_e32 v135, 0xc1000000, v136
	v_mul_f32_e32 v135, v91, v135
	v_cndmask_b32_e32 v135, v136, v135, vcc
	v_add_f32_e32 v136, v80, v140
	v_mul_f32_e32 v136, 0xbfb8aa3b, v136
	v_exp_f32_e32 v136, v136
	v_add_f32_e32 v137, v81, v141
	v_mul_f32_e32 v137, 0xbfb8aa3b, v137
	v_exp_f32_e32 v137, v137
	v_add_f32_e32 v136, 1.0, v136
	v_rcp_f32_e32 v136, v136
	ds_write_b128 v153, v[132:135] offset:8192
	v_add_f32_e32 v132, 1.0, v137
	v_rcp_f32_e32 v133, v132
	v_mul_f32_e32 v132, 0xc1000000, v136
	v_add_f32_e32 v135, v82, v142
	v_mul_f32_e32 v132, v88, v132
	v_mul_f32_e32 v135, 0xbfb8aa3b, v135
	v_cndmask_b32_e32 v132, v136, v132, vcc
	v_exp_f32_e32 v135, v135
	v_add_f32_e32 v136, v83, v143
	v_mul_f32_e32 v136, 0xbfb8aa3b, v136
	v_exp_f32_e32 v136, v136
	v_mul_f32_e32 v134, 0xc1000000, v133
	v_add_f32_e32 v135, 1.0, v135
	v_mul_f32_e32 v134, v89, v134
	v_rcp_f32_e32 v135, v135
	v_cndmask_b32_e32 v133, v133, v134, vcc
	v_add_f32_e32 v134, 1.0, v136
	v_rcp_f32_e32 v136, v134
	v_mul_f32_e32 v134, 0xc1000000, v135
	v_exp_f32_e32 v130, v130
	v_add_f32_e32 v131, v87, v131
	v_mul_f32_e32 v134, v90, v134
	v_rcp_f32_e32 v128, v128
	v_mul_f32_e32 v131, 0xbfb8aa3b, v131
	v_cndmask_b32_e32 v134, v135, v134, vcc
	v_mul_f32_e32 v135, 0xc1000000, v136
	v_add_f32_e32 v129, 1.0, v129
	v_exp_f32_e32 v131, v131
	v_mul_f32_e32 v135, v91, v135
	v_rcp_f32_e32 v129, v129
	v_add_f32_e32 v124, v84, v124
	v_cndmask_b32_e32 v135, v136, v135, vcc
	v_add_f32_e32 v130, 1.0, v130
	v_mul_f32_e32 v124, 0xbfb8aa3b, v124
	ds_write_b128 v153, v[132:135] offset:12288
	v_mul_f32_e32 v132, 0xc1000000, v128
	v_rcp_f32_e32 v130, v130
	v_exp_f32_e32 v124, v124
	v_add_f32_e32 v125, v85, v125
	s_nop 0
	v_mul_f32_e32 v132, v92, v132
	v_add_f32_e32 v131, 1.0, v131
	v_mul_f32_e32 v125, 0xbfb8aa3b, v125
	v_cndmask_b32_e32 v128, v128, v132, vcc
	v_mul_f32_e32 v132, 0xc1000000, v129
	v_rcp_f32_e32 v131, v131
	v_exp_f32_e32 v125, v125
	v_add_f32_e32 v126, v86, v126
	v_mul_f32_e32 v132, v93, v132
	v_mul_f32_e32 v126, 0xbfb8aa3b, v126
	v_cndmask_b32_e32 v129, v129, v132, vcc
	v_mul_f32_e32 v132, 0xc1000000, v130
	v_add_f32_e32 v124, 1.0, v124
	v_exp_f32_e32 v126, v126
	v_add_f32_e32 v127, v87, v127
	v_mul_f32_e32 v132, v94, v132
	v_rcp_f32_e32 v124, v124
	v_mul_f32_e32 v127, 0xbfb8aa3b, v127
	v_cndmask_b32_e32 v130, v130, v132, vcc
	v_mul_f32_e32 v132, 0xc1000000, v131
	v_add_f32_e32 v125, 1.0, v125
	v_exp_f32_e32 v127, v127
	v_mul_f32_e32 v132, v95, v132
	v_rcp_f32_e32 v125, v125
	v_add_f32_e32 v120, v84, v120
	v_cndmask_b32_e32 v131, v131, v132, vcc
	v_add_f32_e32 v126, 1.0, v126
	v_mul_f32_e32 v120, 0xbfb8aa3b, v120
	ds_write_b128 v153, v[128:131] offset:64
	v_mul_f32_e32 v128, 0xc1000000, v124
	v_rcp_f32_e32 v126, v126
	v_exp_f32_e32 v120, v120
	v_add_f32_e32 v121, v85, v121
	v_mul_f32_e32 v128, v92, v128
	v_add_f32_e32 v127, 1.0, v127
	v_mul_f32_e32 v121, 0xbfb8aa3b, v121
	v_cndmask_b32_e32 v124, v124, v128, vcc
	v_mul_f32_e32 v128, 0xc1000000, v125
	v_rcp_f32_e32 v127, v127
	v_exp_f32_e32 v121, v121
	v_add_f32_e32 v122, v86, v122
	v_mul_f32_e32 v128, v93, v128
	v_mul_f32_e32 v122, 0xbfb8aa3b, v122
	v_cndmask_b32_e32 v125, v125, v128, vcc
	v_mul_f32_e32 v128, 0xc1000000, v126
	v_add_f32_e32 v120, 1.0, v120
	v_exp_f32_e32 v122, v122
	v_add_f32_e32 v123, v87, v123
	v_mul_f32_e32 v128, v94, v128
	v_rcp_f32_e32 v120, v120
	v_mul_f32_e32 v123, 0xbfb8aa3b, v123
	v_cndmask_b32_e32 v126, v126, v128, vcc
	v_mul_f32_e32 v128, 0xc1000000, v127
	v_add_f32_e32 v121, 1.0, v121
	v_exp_f32_e32 v123, v123
	v_mul_f32_e32 v128, v95, v128
	v_rcp_f32_e32 v121, v121
	v_add_f32_e32 v116, v84, v116
	v_cndmask_b32_e32 v127, v127, v128, vcc
	v_add_f32_e32 v122, 1.0, v122
	v_mul_f32_e32 v116, 0xbfb8aa3b, v116
	ds_write_b128 v153, v[124:127] offset:4160
	v_mul_f32_e32 v124, 0xc1000000, v120
	v_rcp_f32_e32 v122, v122
	v_exp_f32_e32 v116, v116
	v_add_f32_e32 v117, v85, v117
	v_mul_f32_e32 v124, v92, v124
	v_add_f32_e32 v123, 1.0, v123
	v_mul_f32_e32 v117, 0xbfb8aa3b, v117
	v_cndmask_b32_e32 v120, v120, v124, vcc
	v_mul_f32_e32 v124, 0xc1000000, v121
	v_rcp_f32_e32 v123, v123
	v_exp_f32_e32 v117, v117
	v_add_f32_e32 v118, v86, v118
	v_mul_f32_e32 v124, v93, v124
	v_mul_f32_e32 v118, 0xbfb8aa3b, v118
	v_cndmask_b32_e32 v121, v121, v124, vcc
	v_mul_f32_e32 v124, 0xc1000000, v122
	v_add_f32_e32 v116, 1.0, v116
	v_exp_f32_e32 v118, v118
	v_add_f32_e32 v119, v87, v119
	v_mul_f32_e32 v124, v94, v124
	v_rcp_f32_e32 v116, v116
	v_mul_f32_e32 v119, 0xbfb8aa3b, v119
	v_cndmask_b32_e32 v122, v122, v124, vcc
	v_mul_f32_e32 v124, 0xc1000000, v123
	v_add_f32_e32 v117, 1.0, v117
	v_exp_f32_e32 v119, v119
	v_mul_f32_e32 v124, v95, v124
	v_rcp_f32_e32 v117, v117
	v_cndmask_b32_e32 v123, v123, v124, vcc
	v_add_f32_e32 v118, 1.0, v118
	ds_write_b128 v153, v[120:123] offset:8256
	v_mul_f32_e32 v120, 0xc1000000, v116
	v_rcp_f32_e32 v118, v118
	v_mul_f32_e32 v120, v92, v120
	v_add_f32_e32 v119, 1.0, v119
	v_cndmask_b32_e32 v116, v116, v120, vcc
	v_mul_f32_e32 v120, 0xc1000000, v117
	v_rcp_f32_e32 v119, v119
	v_mul_f32_e32 v120, v93, v120
	v_cndmask_b32_e32 v117, v117, v120, vcc
	v_mul_f32_e32 v120, 0xc1000000, v118
	v_mul_f32_e32 v120, v94, v120
	v_cndmask_b32_e32 v118, v118, v120, vcc
	v_mul_f32_e32 v120, 0xc1000000, v119
	v_mul_f32_e32 v120, v95, v120
	v_cndmask_b32_e32 v119, v119, v120, vcc
	v_lshlrev_b32_e32 v133, 2, v152
	ds_write_b128 v153, v[116:119] offset:12352
	v_and_b32_e32 v116, 60, v133
	v_lshlrev_b32_e32 v132, 2, v116
	v_lshlrev_b32_e32 v116, 4, v152
	v_and_b32_e32 v117, 0xffffc000, v116
	v_add_u32_e32 v117, 0, v117
	v_and_b32_e32 v116, 0x3f00, v116
	v_add3_u32 v135, v117, v116, v132
	s_waitcnt lgkmcnt(0)
	s_barrier
	ds_read_b128 v[128:131], v135 offset:25600
	ds_read_b128 v[120:123], v135 offset:58368
	v_add_u32_e32 v134, 0, v132
	v_add_u32_e32 v136, v134, v116
	ds_read_b128 v[124:127], v136
	s_waitcnt lgkmcnt(2)
	v_mul_f32_e32 v116, 0x3fb8aa3b, v128
	v_exp_f32_e32 v116, v116
	v_add_f32_e32 v117, v128, v128
	v_cmp_nlt_f32_e32 vcc, s79, v117
	s_and_saveexec_b64 s[8:9], vcc
	s_xor_b64 s[8:9], exec, s[8:9]
	v_fma_f32 v128, -v116, v116, 1.0
	s_andn2_saveexec_b64 s[8:9], s[8:9]
	v_fmamk_f32 v118, v117, 0x3c088889, v148
	v_fmaak_f32 v118, v117, v118, 0x3e2aaaab
	v_fma_f32 v118, v117, v118, 0.5
	v_fma_f32 v118, v117, v118, 1.0
	v_mul_f32_e64 v128, v118, -v117
	s_or_b64 exec, exec, s[8:9]
	v_mul_f32_e32 v117, 0x3fb8aa3b, v129
	v_exp_f32_e32 v117, v117
	v_add_f32_e32 v118, v129, v129
	v_cmp_nlt_f32_e32 vcc, s79, v118
	s_and_saveexec_b64 s[8:9], vcc
	s_xor_b64 s[8:9], exec, s[8:9]
	v_fma_f32 v129, -v117, v117, 1.0
	s_andn2_saveexec_b64 s[8:9], s[8:9]
	v_fmamk_f32 v119, v118, 0x3c088889, v148
	v_fmaak_f32 v119, v118, v119, 0x3e2aaaab
	v_fma_f32 v119, v118, v119, 0.5
	v_fma_f32 v119, v118, v119, 1.0
	v_mul_f32_e64 v129, v119, -v118
	s_or_b64 exec, exec, s[8:9]
	v_mul_f32_e32 v118, 0x3fb8aa3b, v130
	v_exp_f32_e32 v118, v118
	v_add_f32_e32 v119, v130, v130
	v_cmp_nlt_f32_e32 vcc, s79, v119
	s_and_saveexec_b64 s[8:9], vcc
	s_xor_b64 s[8:9], exec, s[8:9]
	v_fma_f32 v130, -v118, v118, 1.0
	s_andn2_saveexec_b64 s[8:9], s[8:9]
	v_fmamk_f32 v130, v119, 0x3c088889, v148
	v_fmaak_f32 v130, v119, v130, 0x3e2aaaab
	v_fma_f32 v130, v119, v130, 0.5
	v_fma_f32 v130, v119, v130, 1.0
	v_mul_f32_e64 v130, v130, -v119
	s_or_b64 exec, exec, s[8:9]
	v_mul_f32_e32 v119, 0x3fb8aa3b, v131
	v_exp_f32_e32 v119, v119
	v_add_f32_e32 v137, v131, v131
	v_cmp_nlt_f32_e32 vcc, s79, v137
	s_and_saveexec_b64 s[8:9], vcc
	s_xor_b64 s[8:9], exec, s[8:9]
	v_fma_f32 v131, -v119, v119, 1.0
	s_andn2_saveexec_b64 s[8:9], s[8:9]
	v_fmamk_f32 v131, v137, 0x3c088889, v148
	v_fmaak_f32 v131, v137, v131, 0x3e2aaaab
	v_fma_f32 v131, v137, v131, 0.5
	v_fma_f32 v131, v137, v131, 1.0
	v_mul_f32_e64 v131, v131, -v137
	s_or_b64 exec, exec, s[8:9]
	v_max_f32_e32 v128, v128, v128
	v_max_f32_e32 v128, 0, v128
	v_sqrt_f32_e32 v128, v128
	v_max_f32_e32 v129, v129, v129
	v_max_f32_e32 v129, 0, v129
	v_sqrt_f32_e32 v129, v129
	s_waitcnt lgkmcnt(1)
	v_mul_f32_e32 v120, v120, v128
	s_waitcnt lgkmcnt(0)
	v_mul_f32_e32 v120, v124, v120
	v_max_f32_e32 v124, v130, v130
	v_max_f32_e32 v128, v131, v131
	v_max_f32_e32 v124, 0, v124
	v_max_f32_e32 v128, 0, v128
	v_sqrt_f32_e32 v124, v124
	v_sqrt_f32_e32 v128, v128
	v_mul_f32_e32 v121, v121, v129
	v_mul_f32_e32 v121, v125, v121
	v_mul_f32_e32 v122, v122, v124
	v_mul_f32_e32 v123, v123, v128
	v_mul_f32_e32 v122, v126, v122
	v_mul_f32_e32 v123, v127, v123
	ds_write_b128 v135, v[116:119] offset:25600
	ds_write_b128 v135, v[120:123] offset:58368
	v_add_u32_e32 v116, 0x800, v133
	v_and_b32_e32 v117, 0x3ffff000, v116
	v_and_b32_e32 v116, 0xfc0, v116
	v_lshl_add_u32 v117, v117, 2, 0
	v_lshlrev_b32_e32 v116, 2, v116
	v_add3_u32 v137, v117, v116, v132
	ds_read_b128 v[128:131], v137 offset:25600
	ds_read_b128 v[120:123], v137 offset:58368
	v_add_u32_e32 v116, v134, v116
	ds_read_b128 v[124:127], v116
	s_waitcnt lgkmcnt(2)
	v_mul_f32_e32 v116, 0x3fb8aa3b, v128
	v_exp_f32_e32 v116, v116
	v_add_f32_e32 v117, v128, v128
	v_cmp_nlt_f32_e32 vcc, s79, v117
	s_and_saveexec_b64 s[8:9], vcc
	s_xor_b64 s[8:9], exec, s[8:9]
	v_fma_f32 v128, -v116, v116, 1.0
	s_andn2_saveexec_b64 s[8:9], s[8:9]
	v_fmamk_f32 v118, v117, 0x3c088889, v148
	v_fmaak_f32 v118, v117, v118, 0x3e2aaaab
	v_fma_f32 v118, v117, v118, 0.5
	v_fma_f32 v118, v117, v118, 1.0
	v_mul_f32_e64 v128, v118, -v117
	s_or_b64 exec, exec, s[8:9]
	v_mul_f32_e32 v117, 0x3fb8aa3b, v129
	v_exp_f32_e32 v117, v117
	v_add_f32_e32 v118, v129, v129
	v_cmp_nlt_f32_e32 vcc, s79, v118
	s_and_saveexec_b64 s[8:9], vcc
	s_xor_b64 s[8:9], exec, s[8:9]
	v_fma_f32 v129, -v117, v117, 1.0
	s_andn2_saveexec_b64 s[8:9], s[8:9]
	v_fmamk_f32 v119, v118, 0x3c088889, v148
	v_fmaak_f32 v119, v118, v119, 0x3e2aaaab
	v_fma_f32 v119, v118, v119, 0.5
	v_fma_f32 v119, v118, v119, 1.0
	v_mul_f32_e64 v129, v119, -v118
	s_or_b64 exec, exec, s[8:9]
	v_mul_f32_e32 v118, 0x3fb8aa3b, v130
	v_exp_f32_e32 v118, v118
	v_add_f32_e32 v119, v130, v130
	v_cmp_nlt_f32_e32 vcc, s79, v119
	s_and_saveexec_b64 s[8:9], vcc
	s_xor_b64 s[8:9], exec, s[8:9]
	v_fma_f32 v130, -v118, v118, 1.0
	s_andn2_saveexec_b64 s[8:9], s[8:9]
	v_fmamk_f32 v130, v119, 0x3c088889, v148
	v_fmaak_f32 v130, v119, v130, 0x3e2aaaab
	v_fma_f32 v130, v119, v130, 0.5
	v_fma_f32 v130, v119, v130, 1.0
	v_mul_f32_e64 v130, v130, -v119
	s_or_b64 exec, exec, s[8:9]
	v_mul_f32_e32 v119, 0x3fb8aa3b, v131
	v_exp_f32_e32 v119, v119
	v_add_f32_e32 v138, v131, v131
	v_cmp_nlt_f32_e32 vcc, s79, v138
	s_and_saveexec_b64 s[8:9], vcc
	s_xor_b64 s[8:9], exec, s[8:9]
	v_fma_f32 v131, -v119, v119, 1.0
	s_andn2_saveexec_b64 s[8:9], s[8:9]
	v_fmamk_f32 v131, v138, 0x3c088889, v148
	v_fmaak_f32 v131, v138, v131, 0x3e2aaaab
	v_fma_f32 v131, v138, v131, 0.5
	v_fma_f32 v131, v138, v131, 1.0
	v_mul_f32_e64 v131, v131, -v138
	s_or_b64 exec, exec, s[8:9]
	v_max_f32_e32 v128, v128, v128
	v_max_f32_e32 v128, 0, v128
	v_sqrt_f32_e32 v128, v128
	v_max_f32_e32 v129, v129, v129
	v_max_f32_e32 v129, 0, v129
	v_sqrt_f32_e32 v129, v129
	s_waitcnt lgkmcnt(1)
	v_mul_f32_e32 v120, v120, v128
	s_waitcnt lgkmcnt(0)
	v_mul_f32_e32 v120, v124, v120
	v_max_f32_e32 v124, v130, v130
	v_max_f32_e32 v128, v131, v131
	v_max_f32_e32 v124, 0, v124
	v_max_f32_e32 v128, 0, v128
	v_sqrt_f32_e32 v124, v124
	v_sqrt_f32_e32 v128, v128
	v_mul_f32_e32 v121, v121, v129
	v_mul_f32_e32 v121, v125, v121
	v_mul_f32_e32 v122, v122, v124
	v_mul_f32_e32 v123, v123, v128
	v_mul_f32_e32 v122, v126, v122
	v_mul_f32_e32 v123, v127, v123
	ds_write_b128 v137, v[116:119] offset:25600
	ds_write_b128 v137, v[120:123] offset:58368
	ds_read_b128 v[128:131], v135 offset:41984
	v_add_u32_e32 v137, 0xe400, v135
	ds_read_b128 v[120:123], v137 offset:16384
	ds_read_b128 v[124:127], v136
	s_waitcnt lgkmcnt(2)
	v_mul_f32_e32 v116, 0x3fb8aa3b, v128
	v_exp_f32_e32 v116, v116
	v_add_f32_e32 v117, v128, v128
	v_cmp_nlt_f32_e32 vcc, s79, v117
	s_and_saveexec_b64 s[8:9], vcc
	s_xor_b64 s[8:9], exec, s[8:9]
	v_fma_f32 v128, -v116, v116, 1.0
	s_andn2_saveexec_b64 s[8:9], s[8:9]
	v_fmamk_f32 v118, v117, 0x3c088889, v148
	v_fmaak_f32 v118, v117, v118, 0x3e2aaaab
	v_fma_f32 v118, v117, v118, 0.5
	v_fma_f32 v118, v117, v118, 1.0
	v_mul_f32_e64 v128, v118, -v117
	s_or_b64 exec, exec, s[8:9]
	v_mul_f32_e32 v117, 0x3fb8aa3b, v129
	v_exp_f32_e32 v117, v117
	v_add_f32_e32 v118, v129, v129
	v_cmp_nlt_f32_e32 vcc, s79, v118
	s_and_saveexec_b64 s[8:9], vcc
	s_xor_b64 s[8:9], exec, s[8:9]
	v_fma_f32 v129, -v117, v117, 1.0
	s_andn2_saveexec_b64 s[8:9], s[8:9]
	v_fmamk_f32 v119, v118, 0x3c088889, v148
	v_fmaak_f32 v119, v118, v119, 0x3e2aaaab
	v_fma_f32 v119, v118, v119, 0.5
	v_fma_f32 v119, v118, v119, 1.0
	v_mul_f32_e64 v129, v119, -v118
	s_or_b64 exec, exec, s[8:9]
	v_mul_f32_e32 v118, 0x3fb8aa3b, v130
	v_exp_f32_e32 v118, v118
	v_add_f32_e32 v119, v130, v130
	v_cmp_nlt_f32_e32 vcc, s79, v119
	s_and_saveexec_b64 s[8:9], vcc
	s_xor_b64 s[8:9], exec, s[8:9]
	v_fma_f32 v130, -v118, v118, 1.0
	s_andn2_saveexec_b64 s[8:9], s[8:9]
	v_fmamk_f32 v130, v119, 0x3c088889, v148
	v_fmaak_f32 v130, v119, v130, 0x3e2aaaab
	v_fma_f32 v130, v119, v130, 0.5
	v_fma_f32 v130, v119, v130, 1.0
	v_mul_f32_e64 v130, v130, -v119
	s_or_b64 exec, exec, s[8:9]
	v_mul_f32_e32 v119, 0x3fb8aa3b, v131
	v_exp_f32_e32 v119, v119
	v_add_f32_e32 v136, v131, v131
	v_cmp_nlt_f32_e32 vcc, s79, v136
	s_and_saveexec_b64 s[8:9], vcc
	s_xor_b64 s[8:9], exec, s[8:9]
	v_fma_f32 v131, -v119, v119, 1.0
	s_andn2_saveexec_b64 s[8:9], s[8:9]
	v_fmamk_f32 v131, v136, 0x3c088889, v148
	v_fmaak_f32 v131, v136, v131, 0x3e2aaaab
	v_fma_f32 v131, v136, v131, 0.5
	v_fma_f32 v131, v136, v131, 1.0
	v_mul_f32_e64 v131, v131, -v136
	s_or_b64 exec, exec, s[8:9]
	v_max_f32_e32 v128, v128, v128
	v_max_f32_e32 v128, 0, v128
	v_sqrt_f32_e32 v128, v128
	v_max_f32_e32 v129, v129, v129
	v_max_f32_e32 v129, 0, v129
	v_sqrt_f32_e32 v129, v129
	s_waitcnt lgkmcnt(1)
	v_mul_f32_e32 v120, v120, v128
	s_waitcnt lgkmcnt(0)
	v_mul_f32_e32 v120, v124, v120
	v_max_f32_e32 v124, v130, v130
	v_max_f32_e32 v128, v131, v131
	v_max_f32_e32 v124, 0, v124
	v_max_f32_e32 v128, 0, v128
	v_sqrt_f32_e32 v124, v124
	v_sqrt_f32_e32 v128, v128
	v_mul_f32_e32 v121, v121, v129
	v_mul_f32_e32 v121, v125, v121
	v_mul_f32_e32 v122, v122, v124
	v_mul_f32_e32 v123, v123, v128
	v_mul_f32_e32 v122, v126, v122
	v_mul_f32_e32 v123, v127, v123
	ds_write_b128 v135, v[116:119] offset:41984
	ds_write_b128 v137, v[120:123] offset:16384
	v_add_u32_e32 v116, 0x1800, v133
	v_and_b32_e32 v117, 0x3ffff000, v116
	v_and_b32_e32 v116, 0xfc0, v116
	v_lshl_add_u32 v117, v117, 2, 0
	v_lshlrev_b32_e32 v116, 2, v116
	v_add3_u32 v132, v117, v116, v132
	ds_read_b128 v[128:131], v132 offset:25600
	ds_read_b128 v[120:123], v132 offset:58368
	v_add_u32_e32 v116, v134, v116
	ds_read_b128 v[124:127], v116
	s_waitcnt lgkmcnt(2)
	v_mul_f32_e32 v116, 0x3fb8aa3b, v128
	v_exp_f32_e32 v116, v116
	v_add_f32_e32 v117, v128, v128
	v_cmp_nlt_f32_e32 vcc, s79, v117
	s_and_saveexec_b64 s[8:9], vcc
	s_xor_b64 s[8:9], exec, s[8:9]
	v_fma_f32 v128, -v116, v116, 1.0
	s_andn2_saveexec_b64 s[8:9], s[8:9]
	v_fmamk_f32 v118, v117, 0x3c088889, v148
	v_fmaak_f32 v118, v117, v118, 0x3e2aaaab
	v_fma_f32 v118, v117, v118, 0.5
	v_fma_f32 v118, v117, v118, 1.0
	v_mul_f32_e64 v128, v118, -v117
	s_or_b64 exec, exec, s[8:9]
	v_mul_f32_e32 v117, 0x3fb8aa3b, v129
	v_exp_f32_e32 v117, v117
	v_add_f32_e32 v118, v129, v129
	v_cmp_nlt_f32_e32 vcc, s79, v118
	s_and_saveexec_b64 s[8:9], vcc
	s_xor_b64 s[8:9], exec, s[8:9]
	v_fma_f32 v129, -v117, v117, 1.0
	s_andn2_saveexec_b64 s[8:9], s[8:9]
	v_fmamk_f32 v119, v118, 0x3c088889, v148
	v_fmaak_f32 v119, v118, v119, 0x3e2aaaab
	v_fma_f32 v119, v118, v119, 0.5
	v_fma_f32 v119, v118, v119, 1.0
	v_mul_f32_e64 v129, v119, -v118
	s_or_b64 exec, exec, s[8:9]
	v_mul_f32_e32 v118, 0x3fb8aa3b, v130
	v_exp_f32_e32 v118, v118
	v_add_f32_e32 v119, v130, v130
	v_cmp_nlt_f32_e32 vcc, s79, v119
	s_and_saveexec_b64 s[8:9], vcc
	s_xor_b64 s[8:9], exec, s[8:9]
	v_fma_f32 v130, -v118, v118, 1.0
	s_andn2_saveexec_b64 s[8:9], s[8:9]
	v_fmamk_f32 v130, v119, 0x3c088889, v148
	v_fmaak_f32 v130, v119, v130, 0x3e2aaaab
	v_fma_f32 v130, v119, v130, 0.5
	v_fma_f32 v130, v119, v130, 1.0
	v_mul_f32_e64 v130, v130, -v119
	s_or_b64 exec, exec, s[8:9]
	v_mul_f32_e32 v119, 0x3fb8aa3b, v131
	v_exp_f32_e32 v119, v119
	v_add_f32_e32 v133, v131, v131
	v_cmp_nlt_f32_e32 vcc, s79, v133
	s_and_saveexec_b64 s[8:9], vcc
	s_xor_b64 s[8:9], exec, s[8:9]
	v_fma_f32 v131, -v119, v119, 1.0
	s_andn2_saveexec_b64 s[8:9], s[8:9]
	v_fmamk_f32 v131, v133, 0x3c088889, v148
	v_fmaak_f32 v131, v133, v131, 0x3e2aaaab
	v_fma_f32 v131, v133, v131, 0.5
	v_fma_f32 v131, v133, v131, 1.0
	v_mul_f32_e64 v131, v131, -v133
	s_or_b64 exec, exec, s[8:9]
	v_max_f32_e32 v128, v128, v128
	v_max_f32_e32 v128, 0, v128
	v_sqrt_f32_e32 v128, v128
	v_max_f32_e32 v129, v129, v129
	v_max_f32_e32 v129, 0, v129
	v_sqrt_f32_e32 v129, v129
	s_waitcnt lgkmcnt(1)
	v_mul_f32_e32 v120, v120, v128
	v_max_f32_e32 v128, v130, v130
	s_waitcnt lgkmcnt(0)
	v_mul_f32_e32 v120, v124, v120
	v_max_f32_e32 v124, v131, v131
	v_max_f32_e32 v128, 0, v128
	v_max_f32_e32 v124, 0, v124
	v_sqrt_f32_e32 v128, v128
	v_sqrt_f32_e32 v124, v124
	v_ashrrev_i32_e32 v156, 7, v152
	v_mul_f32_e32 v121, v121, v129
	v_mul_f32_e32 v122, v122, v128
	v_and_b32_e32 v172, 0x7f, v152
	v_mul_f32_e32 v123, v123, v124
	v_lshlrev_b32_e32 v146, 4, v156
	v_mul_f32_e32 v121, v125, v121
	v_mul_f32_e32 v122, v126, v122
	v_bfe_u32 v153, v152, 6, 1
	v_mul_f32_e32 v123, v127, v123
	ds_write_b128 v132, v[116:119] offset:25600
	ds_write_b128 v132, v[120:123] offset:58368
	v_and_b32_e32 v154, 63, v152
	v_sub_u32_e32 v116, 63, v146
	v_cmp_gt_u32_e32 vcc, 64, v172
	v_or_b32_e32 v118, 1, v146
	v_lshl_or_b32 v147, v153, 12, v154
	v_cndmask_b32_e32 v155, v116, v146, vcc
	v_sub_u32_e32 v119, 63, v118
	v_or_b32_e32 v120, 2, v146
	v_lshl_add_u32 v116, v155, 6, v147
	v_cndmask_b32_e32 v157, v119, v118, vcc
	v_sub_u32_e32 v121, 63, v120
	v_or_b32_e32 v122, 3, v146
	v_lshl_add_u32 v116, v116, 2, 0
	v_lshl_add_u32 v118, v157, 6, v147
	v_cndmask_b32_e32 v158, v121, v120, vcc
	v_sub_u32_e32 v123, 63, v122
	v_or_b32_e32 v124, 4, v146
	s_waitcnt lgkmcnt(0)
	s_barrier
	ds_read2st64_b32 v[116:117], v116 offset0:100 offset1:228
	v_lshl_add_u32 v118, v118, 2, 0
	v_lshl_add_u32 v120, v158, 6, v147
	v_cndmask_b32_e32 v159, v123, v122, vcc
	v_sub_u32_e32 v125, 63, v124
	v_or_b32_e32 v126, 5, v146
	ds_read2st64_b32 v[118:119], v118 offset0:100 offset1:228
	v_lshl_add_u32 v120, v120, 2, 0
	v_lshl_add_u32 v122, v159, 6, v147
	v_cndmask_b32_e32 v160, v125, v124, vcc
	v_sub_u32_e32 v127, 63, v126
	v_or_b32_e32 v128, 6, v146
	ds_read2st64_b32 v[120:121], v120 offset0:100 offset1:228
	v_lshl_add_u32 v122, v122, 2, 0
	v_lshl_add_u32 v124, v160, 6, v147
	v_cndmask_b32_e32 v161, v127, v126, vcc
	v_sub_u32_e32 v129, 63, v128
	v_or_b32_e32 v130, 7, v146
	ds_read2st64_b32 v[122:123], v122 offset0:100 offset1:228
	v_lshl_add_u32 v124, v124, 2, 0
	v_lshl_add_u32 v126, v161, 6, v147
	v_cndmask_b32_e32 v162, v129, v128, vcc
	v_sub_u32_e32 v131, 63, v130
	v_or_b32_e32 v132, 8, v146
	ds_read2st64_b32 v[124:125], v124 offset0:100 offset1:228
	v_lshl_add_u32 v126, v126, 2, 0
	v_lshl_add_u32 v128, v162, 6, v147
	v_cndmask_b32_e32 v163, v131, v130, vcc
	v_sub_u32_e32 v133, 63, v132
	v_or_b32_e32 v134, 9, v146
	ds_read2st64_b32 v[126:127], v126 offset0:100 offset1:228
	v_lshl_add_u32 v128, v128, 2, 0
	v_lshl_add_u32 v130, v163, 6, v147
	v_cndmask_b32_e32 v164, v133, v132, vcc
	v_sub_u32_e32 v135, 63, v134
	v_or_b32_e32 v136, 10, v146
	s_waitcnt lgkmcnt(5)
	v_fma_f32 v173, 0, v116, v117
	ds_read2st64_b32 v[128:129], v128 offset0:100 offset1:228
	v_lshl_add_u32 v130, v130, 2, 0
	v_lshl_add_u32 v132, v164, 6, v147
	v_cndmask_b32_e32 v165, v135, v134, vcc
	v_sub_u32_e32 v137, 63, v136
	v_or_b32_e32 v138, 11, v146
	s_waitcnt lgkmcnt(5)
	v_fma_f32 v173, v173, v118, v119
	ds_read2st64_b32 v[130:131], v130 offset0:100 offset1:228
	v_lshl_add_u32 v132, v132, 2, 0
	v_lshl_add_u32 v134, v165, 6, v147
	v_cndmask_b32_e32 v166, v137, v136, vcc
	v_sub_u32_e32 v139, 63, v138
	v_or_b32_e32 v140, 12, v146
	v_mul_f32_e32 v174, v116, v118
	s_waitcnt lgkmcnt(5)
	v_fma_f32 v173, v173, v120, v121
	ds_read2st64_b32 v[132:133], v132 offset0:100 offset1:228
	v_lshl_add_u32 v134, v134, 2, 0
	v_lshl_add_u32 v136, v166, 6, v147
	v_cndmask_b32_e32 v167, v139, v138, vcc
	v_sub_u32_e32 v141, 63, v140
	v_or_b32_e32 v142, 13, v146
	v_mul_f32_e32 v174, v174, v120
	s_waitcnt lgkmcnt(5)
	v_fma_f32 v173, v173, v122, v123
	ds_read2st64_b32 v[134:135], v134 offset0:100 offset1:228
	v_lshl_add_u32 v136, v136, 2, 0
	v_lshl_add_u32 v138, v167, 6, v147
	v_cndmask_b32_e32 v168, v141, v140, vcc
	v_sub_u32_e32 v143, 63, v142
	v_or_b32_e32 v144, 14, v146
	v_mul_f32_e32 v174, v174, v122
	s_waitcnt lgkmcnt(5)
	v_fma_f32 v173, v173, v124, v125
	ds_read2st64_b32 v[136:137], v136 offset0:100 offset1:228
	v_lshl_add_u32 v138, v138, 2, 0
	v_lshl_add_u32 v140, v168, 6, v147
	v_cndmask_b32_e32 v169, v143, v142, vcc
	v_sub_u32_e32 v145, 63, v144
	v_or_b32_e32 v146, 15, v146
	v_mul_f32_e32 v174, v174, v124
	s_waitcnt lgkmcnt(5)
	v_fma_f32 v173, v173, v126, v127
	ds_read2st64_b32 v[138:139], v138 offset0:100 offset1:228
	v_lshl_add_u32 v140, v140, 2, 0
	v_lshl_add_u32 v142, v169, 6, v147
	v_cndmask_b32_e32 v170, v145, v144, vcc
	v_sub_u32_e32 v171, 63, v146
	v_mul_f32_e32 v174, v174, v126
	s_waitcnt lgkmcnt(5)
	v_fma_f32 v173, v173, v128, v129
	ds_read2st64_b32 v[140:141], v140 offset0:100 offset1:228
	v_lshl_add_u32 v142, v142, 2, 0
	v_lshl_add_u32 v144, v170, 6, v147
	v_cndmask_b32_e32 v171, v171, v146, vcc
	v_mul_f32_e32 v174, v174, v128
	s_waitcnt lgkmcnt(5)
	v_fma_f32 v173, v173, v130, v131
	ds_read2st64_b32 v[142:143], v142 offset0:100 offset1:228
	v_lshl_add_u32 v144, v144, 2, 0
	v_lshl_add_u32 v146, v171, 6, v147
	v_mul_f32_e32 v174, v174, v130
	s_waitcnt lgkmcnt(5)
	v_fma_f32 v173, v173, v132, v133
	ds_read2st64_b32 v[144:145], v144 offset0:100 offset1:228
	v_lshl_add_u32 v146, v146, 2, 0
	v_mul_f32_e32 v174, v174, v132
	s_waitcnt lgkmcnt(5)
	v_fma_f32 v173, v173, v134, v135
	ds_read2st64_b32 v[146:147], v146 offset0:100 offset1:228
	v_mul_f32_e32 v174, v174, v134
	s_waitcnt lgkmcnt(5)
	v_fma_f32 v173, v173, v136, v137
	v_mul_f32_e32 v174, v174, v136
	s_waitcnt lgkmcnt(4)
	v_fma_f32 v173, v173, v138, v139
	v_mul_f32_e32 v174, v174, v138
	s_waitcnt lgkmcnt(3)
	v_fma_f32 v173, v173, v140, v141
	v_mul_f32_e32 v174, v174, v140
	s_waitcnt lgkmcnt(2)
	v_fma_f32 v173, v173, v142, v143
	v_mul_f32_e32 v174, v174, v142
	s_waitcnt lgkmcnt(1)
	v_fma_f32 v173, v173, v144, v145
	v_lshl_add_u32 v152, v152, 2, 0
	v_mul_f32_e32 v174, v174, v144
	s_waitcnt lgkmcnt(0)
	v_fma_f32 v173, v173, v146, v147
	v_add_u32_e32 v175, 0x16400, v152
	v_add_u32_e32 v152, 0x16c00, v152
	v_mul_f32_e32 v174, v174, v146
	ds_write_b32 v152, v173
	v_cmp_lt_i32_e32 vcc, 0, v156
	v_lshl_add_u32 v172, v172, 2, 0
	v_mov_b32_e32 v152, v149
	ds_write_b32 v175, v174
	s_waitcnt lgkmcnt(0)
	s_barrier
	s_and_saveexec_b64 s[8:9], vcc
	s_cbranch_execnz .LBB0_772
	s_or_b64 exec, exec, s[8:9]
	v_cmp_lt_i32_e32 vcc, 1, v156
	s_and_saveexec_b64 s[8:9], vcc
	s_cbranch_execnz .LBB0_773

.LBB0_692:
	s_or_b64 exec, exec, s[8:9]
	v_lshlrev_b32_e32 v153, 14, v153
	v_lshlrev_b32_e32 v154, 2, v154
	v_add3_u32 v153, 0, v153, v154
	v_fmac_f32_e32 v117, v116, v152
	v_lshl_add_u32 v116, v155, 8, v153
	ds_write_b32 v116, v117 offset:58368
	v_fmac_f32_e32 v119, v118, v117
	v_lshl_add_u32 v116, v157, 8, v153
	ds_write_b32 v116, v119 offset:58368
	v_fmac_f32_e32 v121, v120, v119
	v_lshl_add_u32 v116, v158, 8, v153
	ds_write_b32 v116, v121 offset:58368
	v_fmac_f32_e32 v123, v122, v121
	v_lshl_add_u32 v116, v159, 8, v153
	ds_write_b32 v116, v123 offset:58368
	v_fmac_f32_e32 v125, v124, v123
	v_lshl_add_u32 v116, v160, 8, v153
	ds_write_b32 v116, v125 offset:58368
	v_fmac_f32_e32 v127, v126, v125
	v_lshl_add_u32 v116, v161, 8, v153
	ds_write_b32 v116, v127 offset:58368
	v_fmac_f32_e32 v129, v128, v127
	v_lshl_add_u32 v116, v162, 8, v153
	ds_write_b32 v116, v129 offset:58368
	v_fmac_f32_e32 v131, v130, v129
	v_lshl_add_u32 v116, v163, 8, v153
	ds_write_b32 v116, v131 offset:58368
	v_fmac_f32_e32 v133, v132, v131
	v_lshl_add_u32 v116, v164, 8, v153
	ds_write_b32 v116, v133 offset:58368
	v_fmac_f32_e32 v135, v134, v133
	v_lshl_add_u32 v116, v165, 8, v153
	ds_write_b32 v116, v135 offset:58368
	v_fmac_f32_e32 v137, v136, v135
	v_lshl_add_u32 v116, v166, 8, v153
	ds_write_b32 v116, v137 offset:58368
	v_fmac_f32_e32 v139, v138, v137
	v_lshl_add_u32 v116, v167, 8, v153
	ds_write_b32 v116, v139 offset:58368
	v_fmac_f32_e32 v141, v140, v139
	v_lshl_add_u32 v116, v168, 8, v153
	ds_write_b32 v116, v141 offset:58368
	v_fmac_f32_e32 v143, v142, v141
	v_lshl_add_u32 v116, v169, 8, v153
	ds_write_b32 v116, v143 offset:58368
	v_fmac_f32_e32 v145, v144, v143
	v_lshl_add_u32 v116, v170, 8, v153
	ds_write_b32 v116, v145 offset:58368
	v_fmac_f32_e32 v147, v146, v145
	v_lshl_add_u32 v116, v171, 8, v153
	v_lshlrev_b32_e32 v132, 16, v100
	ds_write_b32 v116, v147 offset:58368
	v_mul_f32_e32 v116, 0x3d372713, v132
	v_mul_f32_e32 v116, v116, v132
	v_mov_b32_e32 v117, v132
	v_fmac_f32_e32 v117, v116, v117
	v_mul_f32_e32 v116, 0x3f4c422a, v117
	v_lshlrev_b32_e32 v117, 2, v1
	v_and_b32_e32 v133, 0xffff0000, v100
	v_add3_u32 v128, v151, v117, s46
	v_mul_f32_e32 v117, 0x3d372713, v133
	v_mul_f32_e32 v117, v117, v133
	v_mov_b32_e32 v118, v133
	v_fmac_f32_e32 v118, v117, v118
	v_add_f32_e32 v116, v116, v116
	v_mul_f32_e32 v117, 0x3f4c422a, v118
	v_mul_f32_e32 v116, 0x3fb8aa3b, v116
	v_add_f32_e32 v117, v117, v117
	v_exp_f32_e32 v116, v116
	v_mul_f32_e32 v117, 0x3fb8aa3b, v117
	v_exp_f32_e32 v124, v117
	s_waitcnt lgkmcnt(0)
	v_add_f32_e32 v116, 1.0, v116
	s_barrier
	v_rcp_f32_e32 v134, v116
	ds_read_b128 v[116:119], v3 offset:58368
	ds_read_b128 v[120:123], v128 offset:16384
	v_add_f32_e32 v124, 1.0, v124
	v_rcp_f32_e32 v135, v124
	ds_read_b128 v[124:127], v3 offset:58384
	ds_read_b128 v[128:131], v128 offset:16400
	v_pk_mul_f32 v[132:133], v[132:133], 0.5 op_sel_hi:[1,0]
	s_waitcnt lgkmcnt(2)
	v_pk_add_f32 v[116:117], v[116:117], v[120:121]
	v_pk_fma_f32 v[120:121], v[134:135], 2.0, 1.0 op_sel_hi:[1,0,0] neg_lo:[1,0,0] neg_hi:[1,0,0]
	v_lshlrev_b32_e32 v134, 16, v101
	v_mul_f32_e32 v3, 0x3d372713, v134
	v_mul_f32_e32 v3, v3, v134
	v_mov_b32_e32 v136, v134
	v_and_b32_e32 v135, 0xffff0000, v101
	v_fmac_f32_e32 v136, v3, v136
	v_mul_f32_e32 v3, 0x3f4c422a, v136
	v_mul_f32_e32 v136, 0x3d372713, v135
	v_mul_f32_e32 v136, v136, v135
	v_mov_b32_e32 v137, v135
	v_fmac_f32_e32 v137, v136, v137
	v_add_f32_e32 v3, v3, v3
	v_mul_f32_e32 v136, 0x3f4c422a, v137
	v_mul_f32_e32 v3, 0x3fb8aa3b, v3
	v_add_f32_e32 v136, v136, v136
	v_exp_f32_e32 v3, v3
	v_mul_f32_e32 v136, 0x3fb8aa3b, v136
	v_exp_f32_e32 v137, v136
	v_pk_add_f32 v[120:121], v[120:121], 1.0 op_sel_hi:[1,0]
	v_add_f32_e32 v3, 1.0, v3
	v_rcp_f32_e32 v136, v3
	v_add_f32_e32 v3, 1.0, v137
	v_pk_mul_f32 v[120:121], v[132:133], v[120:121]
	v_lshlrev_b32_e32 v132, 16, v102
	v_rcp_f32_e32 v137, v3
	v_mul_f32_e32 v3, 0x3d372713, v132
	v_pk_add_f32 v[118:119], v[118:119], v[122:123]
	v_pk_mul_f32 v[122:123], v[134:135], 0.5 op_sel_hi:[1,0]
	v_mul_f32_e32 v3, v3, v132
	v_mov_b32_e32 v134, v132
	v_and_b32_e32 v133, 0xffff0000, v102
	v_fmac_f32_e32 v134, v3, v134
	v_mul_f32_e32 v3, 0x3f4c422a, v134
	v_mul_f32_e32 v134, 0x3d372713, v133
	v_mul_f32_e32 v134, v134, v133
	v_mov_b32_e32 v135, v133
	v_fmac_f32_e32 v135, v134, v135
	v_add_f32_e32 v3, v3, v3
	v_mul_f32_e32 v134, 0x3f4c422a, v135
	v_mul_f32_e32 v3, 0x3fb8aa3b, v3
	v_add_f32_e32 v134, v134, v134
	v_exp_f32_e32 v3, v3
	v_mul_f32_e32 v134, 0x3fb8aa3b, v134
	v_exp_f32_e32 v135, v134
	v_pk_mul_f32 v[116:117], v[120:121], v[116:117]
	v_pk_fma_f32 v[120:121], v[136:137], 2.0, 1.0 op_sel_hi:[1,0,0] neg_lo:[1,0,0] neg_hi:[1,0,0]
	v_add_f32_e32 v3, 1.0, v3
	v_pk_add_f32 v[120:121], v[120:121], 1.0 op_sel_hi:[1,0]
	v_rcp_f32_e32 v134, v3
	v_pk_mul_f32 v[120:121], v[122:123], v[120:121]
	v_add_f32_e32 v3, 1.0, v135
	v_pk_mul_f32 v[118:119], v[120:121], v[118:119]
	s_waitcnt lgkmcnt(0)
	v_pk_add_f32 v[120:121], v[124:125], v[128:129]
	v_lshlrev_b32_e32 v128, 16, v103
	v_rcp_f32_e32 v135, v3
	v_mul_f32_e32 v3, 0x3d372713, v128
	v_pk_mul_f32 v[124:125], v[132:133], 0.5 op_sel_hi:[1,0]
	v_mul_f32_e32 v3, v3, v128
	v_mov_b32_e32 v132, v128
	v_and_b32_e32 v129, 0xffff0000, v103
	v_fmac_f32_e32 v132, v3, v132
	v_mul_f32_e32 v3, 0x3f4c422a, v132
	v_mul_f32_e32 v132, 0x3d372713, v129
	v_mul_f32_e32 v132, v132, v129
	v_mov_b32_e32 v133, v129
	v_fmac_f32_e32 v133, v132, v133
	v_add_f32_e32 v3, v3, v3
	v_mul_f32_e32 v132, 0x3f4c422a, v133
	v_mul_f32_e32 v3, 0x3fb8aa3b, v3
	v_add_f32_e32 v132, v132, v132
	v_exp_f32_e32 v3, v3
	v_mul_f32_e32 v132, 0x3fb8aa3b, v132
	v_exp_f32_e32 v133, v132
	s_ashr_i32 s8, s2, 9
	v_add_f32_e32 v3, 1.0, v3
	v_rcp_f32_e32 v132, v3
	v_add_f32_e32 v3, 1.0, v133
	v_rcp_f32_e32 v133, v3
	v_pk_fma_f32 v[122:123], v[134:135], 2.0, 1.0 op_sel_hi:[1,0,0] neg_lo:[1,0,0] neg_hi:[1,0,0]
	s_ashr_i32 s9, s8, 31
	v_pk_add_f32 v[122:123], v[122:123], 1.0 op_sel_hi:[1,0]
	s_lshl_b64 s[8:9], s[8:9], 12
	s_and_b32 s10, s12, 0xfc0
	v_pk_mul_f32 v[122:123], v[124:125], v[122:123]
	v_pk_fma_f32 v[124:125], v[132:133], 2.0, 1.0 op_sel_hi:[1,0,0] neg_lo:[1,0,0] neg_hi:[1,0,0]
	s_or_b32 s8, s8, s10
	v_ashrrev_i32_e32 v3, 31, v2
	v_pk_mul_f32 v[120:121], v[122:123], v[120:121]
	v_pk_add_f32 v[122:123], v[126:127], v[130:131]
	v_pk_mul_f32 v[126:127], v[128:129], 0.5 op_sel_hi:[1,0]
	v_pk_add_f32 v[124:125], v[124:125], 1.0 op_sel_hi:[1,0]
	v_lshl_add_u64 v[2:3], s[8:9], 0, v[2:3]
	s_and_b32 s8, s13, 0x1c0
	v_pk_mul_f32 v[124:125], v[126:127], v[124:125]
	v_or_b32_e32 v1, s8, v1
	v_lshlrev_b64 v[2:3], 11, v[2:3]
	v_pk_mul_f32 v[122:123], v[124:125], v[122:123]
	v_cvt_pk_bf16_f32 v116, v116, v117
	v_cvt_pk_bf16_f32 v117, v118, v119
	v_cvt_pk_bf16_f32 v118, v120, v121
	v_lshl_add_u64 v[2:3], s[16:17], 0, v[2:3]
	v_lshlrev_b32_e32 v120, 1, v1
	v_mov_b32_e32 v121, v0
	v_cvt_pk_bf16_f32 v119, v122, v123
	v_lshl_add_u64 v[2:3], v[2:3], 0, v[120:121]
	s_cmpk_gt_i32 s50, 0xfff
	s_mov_b64 s[8:9], -1
	s_waitcnt vmcnt(0)
	global_store_dwordx4 v[2:3], v[116:119], off
	s_barrier
	s_cbranch_scc1 .LBB0_611
	s_add_i32 s2, s89, s2
	s_cmpk_gt_i32 s2, 0xfff
	s_cbranch_scc1 .LBB0_703
	v_mov_b32_e32 v118, v204
	s_ashr_i32 s8, s2, 9
	s_bfe_u32 s2, s2, 0x60003
	s_add_i32 s9, s88, s13
	s_and_b32 s61, s9, 0x1c0
	v_ashrrev_i32_e32 v102, 3, v118
	v_lshlrev_b32_e32 v1, 3, v118
	s_lshl_b32 s62, s2, 6
	v_and_or_b32 v2, v1, 56, s61
	v_add_u32_e32 v60, s62, v102
	v_mov_b32_e32 v30, v0
	v_mov_b32_e32 v31, v0
	v_add_u32_e32 v1, -2, v60
	v_lshlrev_b32_e32 v100, 1, v2
	v_mov_b32_e32 v101, v0
	v_mov_b32_e32 v28, v0
	v_mov_b32_e32 v29, v0
	v_mov_b64_e32 v[42:43], v[30:31]
	s_lshl_b32 s9, s8, 12
	v_lshl_add_u64 v[116:117], s[66:67], 0, v[100:101]
	v_cmp_gt_u32_e32 vcc, s48, v1
	v_mov_b64_e32 v[40:41], v[28:29]
	s_and_saveexec_b64 s[10:11], vcc
	s_cbranch_execz .LBB0_696
	v_or_b32_e32 v1, s9, v1
	v_mad_i64_i32 v[2:3], s[64:65], v1, s0, v[116:117]
	global_load_dwordx4 v[40:43], v[2:3], off

.LBB0_703:
	s_and_b64 vcc, exec, s[6:7]
	s_cbranch_vccnz .LBB0_705
	v_mov_b32_e32 v1, v204
	s_and_b32 s2, s50, 7
	s_lshl_b32 s62, s2, 8
	v_lshlrev_b32_e32 v2, 5, v1
	v_and_b32_e32 v2, 0xe0, v2
	v_or_b32_e32 v2, s62, v2
	v_mov_b32_e32 v3, v0
	v_lshl_add_u64 v[12:13], s[24:25], 0, v[2:3]
	v_add_co_u32_e32 v24, vcc, s48, v12
	global_load_dwordx4 v[4:7], v2, s[24:25] offset:2064
	global_load_dwordx4 v[8:11], v2, s[24:25] offset:2048
	v_addc_co_u32_e32 v25, vcc, 0, v13, vcc
	global_load_dwordx4 v[12:15], v2, s[54:55]
	global_load_dwordx4 v[16:19], v2, s[56:57]
	global_load_dwordx4 v[20:23], v[24:25], off offset:16
	global_load_dwordx4 v[32:35], v[24:25], off offset:2064
	s_nop 0
	global_load_dwordx4 v[24:27], v2, s[24:25] offset:16
	global_load_dwordx4 v[44:47], v2, s[26:27] offset:16
	global_load_dwordx4 v[36:39], v2, s[24:25]
	global_load_dwordx4 v[48:51], v2, s[26:27]
	v_ashrrev_i32_e32 v56, 7, v1
	v_lshrrev_b32_e32 v2, 1, v1
	v_and_b32_e32 v82, 32, v2
	v_lshl_or_b32 v2, v56, 3, s2
	v_lshlrev_b32_e32 v56, 11, v56
	v_ashrrev_i32_e32 v3, 31, v2
	v_and_b32_e32 v74, 0x800, v56
	v_mov_b32_e32 v75, v0
	v_lshlrev_b64 v[2:3], 13, v[2:3]
	v_lshl_add_u64 v[56:57], s[52:53], 0, v[74:75]
	v_lshl_add_u64 v[2:3], s[58:59], 0, v[2:3]
	v_and_b32_e32 v72, 48, v1
	v_mov_b32_e32 v73, v0
	v_lshl_add_u64 v[76:77], v[56:57], 0, s[62:63]
	v_and_or_b32 v56, v1, 15, v82
	v_lshl_add_u64 v[2:3], v[2:3], 0, v[72:73]
	v_lshlrev_b32_e32 v78, 7, v56
	v_mov_b32_e32 v79, v0
	v_lshl_add_u64 v[64:65], v[2:3], 0, v[78:79]
	v_mov_b32_e32 v73, s37
	v_mov_b32_e32 v79, s15
	v_cmp_gt_u32_e32 vcc, s49, v1
	v_mov_b32_e32 v1, s36
	v_lshl_or_b32 v72, v82, 2, v72
	v_cndmask_b32_e32 v81, v73, v79, vcc
	v_mov_b32_e32 v73, s14
	v_cndmask_b32_e32 v80, v1, v73, vcc
	v_lshl_add_u64 v[74:75], v[80:81], 0, v[74:75]
	v_lshl_add_u64 v[74:75], v[74:75], 0, s[62:63]
	v_mov_b32_e32 v73, v0
	v_lshl_add_u64 v[84:85], v[74:75], 0, v[72:73]
	v_lshl_add_u64 v[92:93], v[76:77], 0, v[72:73]
	v_or_b32_e32 v72, 0x800, v78
	v_lshl_add_u64 v[2:3], v[2:3], 0, v[72:73]
	global_load_dwordx4 v[56:59], v[64:65], off
	s_nop 0
	global_load_dwordx4 v[64:67], v[64:65], off offset:64
	s_nop 0
	global_load_dwordx4 v[72:75], v[2:3], off
	global_load_dwordx4 v[76:79], v[2:3], off offset:64
	global_load_dwordx4 v[80:83], v[84:85], off
	s_nop 0
	global_load_dwordx4 v[84:87], v[84:85], off offset:64
	s_nop 0
	global_load_dwordx4 v[88:91], v[92:93], off
	s_nop 0
	global_load_dwordx4 v[92:95], v[92:93], off offset:64
	s_waitcnt vmcnt(0)
.LBB0_705:
	v_lshlrev_b32_e32 v2, 16, v68
	v_and_b32_e32 v3, 0xffff0000, v68
	s_nop 0
	v_pk_fma_f32 v[2:3], v[36:37], v[2:3], v[48:49]
	v_lshlrev_b32_e32 v116, 16, v96
	v_and_b32_e32 v117, 0xffff0000, v96
	v_pk_fma_f32 v[2:3], v[8:9], v[116:117], v[2:3]
	v_lshlrev_b32_e32 v116, 16, v104
	v_and_b32_e32 v117, 0xffff0000, v104
	v_pk_fma_f32 v[2:3], v[12:13], v[116:117], v[2:3]
	v_lshlrev_b32_e32 v116, 16, v108
	v_and_b32_e32 v117, 0xffff0000, v108
	v_pk_fma_f32 v[116:117], v[16:17], v[116:117], v[2:3]
	v_lshlrev_b32_e32 v2, 16, v70
	v_and_b32_e32 v3, 0xffff0000, v70
	v_pk_fma_f32 v[2:3], v[24:25], v[2:3], v[44:45]
	v_lshlrev_b32_e32 v118, 16, v98
	v_and_b32_e32 v119, 0xffff0000, v98
	v_pk_fma_f32 v[2:3], v[4:5], v[118:119], v[2:3]
	v_lshlrev_b32_e32 v118, 16, v106
	v_and_b32_e32 v119, 0xffff0000, v106
	v_pk_fma_f32 v[2:3], v[20:21], v[118:119], v[2:3]
	v_lshlrev_b32_e32 v118, 16, v110
	v_and_b32_e32 v119, 0xffff0000, v110
	v_pk_fma_f32 v[120:121], v[32:33], v[118:119], v[2:3]
	v_lshlrev_b32_e32 v2, 16, v69
	v_and_b32_e32 v3, 0xffff0000, v69
	v_pk_fma_f32 v[2:3], v[38:39], v[2:3], v[50:51]
	v_lshlrev_b32_e32 v118, 16, v97
	v_and_b32_e32 v119, 0xffff0000, v97
	v_pk_fma_f32 v[2:3], v[10:11], v[118:119], v[2:3]
	v_lshlrev_b32_e32 v118, 16, v105
	v_and_b32_e32 v119, 0xffff0000, v105
	v_pk_fma_f32 v[2:3], v[14:15], v[118:119], v[2:3]
	v_lshlrev_b32_e32 v118, 16, v109
	v_and_b32_e32 v119, 0xffff0000, v109
	v_pk_fma_f32 v[118:119], v[18:19], v[118:119], v[2:3]
	v_lshlrev_b32_e32 v2, 16, v71
	v_and_b32_e32 v3, 0xffff0000, v71
	v_pk_fma_f32 v[2:3], v[26:27], v[2:3], v[46:47]
	v_lshlrev_b32_e32 v122, 16, v99
	v_and_b32_e32 v123, 0xffff0000, v99
	v_pk_fma_f32 v[2:3], v[6:7], v[122:123], v[2:3]
	v_lshlrev_b32_e32 v122, 16, v107
	v_and_b32_e32 v123, 0xffff0000, v107
	v_mov_b32_e32 v152, v204
	v_pk_fma_f32 v[2:3], v[22:23], v[122:123], v[2:3]
	v_lshlrev_b32_e32 v122, 16, v111
	v_and_b32_e32 v123, 0xffff0000, v111
	v_pk_fma_f32 v[122:123], v[34:35], v[122:123], v[2:3]
	v_lshlrev_b32_e32 v1, 3, v152
	v_ashrrev_i32_e32 v2, 3, v152
	v_and_b32_e32 v1, 56, v1
	v_lshl_add_u32 v151, v2, 8, 0
	v_lshl_add_u32 v3, v1, 2, v151
	ds_write_b128 v3, v[116:119]
	ds_write_b128 v3, v[120:123] offset:16
	v_cvt_pk_bf16_f32 v116, v116, v117
	v_cvt_pk_bf16_f32 v117, v118, v119
	v_cvt_pk_bf16_f32 v118, v120, v121
	v_mul_lo_u32 v120, v2, s1
	v_lshlrev_b32_e32 v121, 1, v1
	v_and_b32_e32 v162, 15, v152
	v_cvt_pk_bf16_f32 v119, v122, v123
	v_add3_u32 v120, v151, v120, v121
	v_and_b32_e32 v153, 48, v152
	ds_write_b128 v120, v[116:119] offset:16384
	v_mul_u32_u24_e32 v116, 0x90, v162
	v_add3_u32 v163, 0, v153, v116
	s_waitcnt lgkmcnt(0)
	s_barrier
	ds_read_b128 v[128:131], v163 offset:20992
	s_waitcnt lgkmcnt(0)
	v_mfma_f32_16x16x32_bf16 v[136:139], v[56:59], v[128:131], 0
	ds_read_b128 v[116:119], v163 offset:16384
	ds_read_b128 v[124:127], v163 offset:18688
	v_cmp_gt_u32_e32 vcc, s49, v152
	s_nop 0
	v_mfma_f32_16x16x32_bf16 v[140:143], v[72:75], v[128:131], 0
	ds_read_b128 v[128:131], v163 offset:23296
	s_waitcnt lgkmcnt(0)
	v_mfma_f32_16x16x32_bf16 v[144:147], v[56:59], v[128:131], 0
	v_mfma_f32_16x16x32_bf16 v[154:157], v[72:75], v[128:131], 0
	ds_read_b128 v[128:131], v163 offset:16448
	v_mfma_f32_16x16x32_bf16 v[120:123], v[56:59], v[116:119], 0
	v_mfma_f32_16x16x32_bf16 v[116:119], v[72:75], v[116:119], 0
	s_waitcnt lgkmcnt(0)
	v_mfma_f32_16x16x32_bf16 v[158:161], v[64:67], v[128:131], v[120:123]
	s_nop 0
	v_mfma_f32_16x16x32_bf16 v[128:131], v[76:79], v[128:131], v[116:119]
	s_nop 3
	ds_read_b128 v[116:119], v163 offset:18752
	v_mfma_f32_16x16x32_bf16 v[132:135], v[56:59], v[124:127], 0
	s_nop 0
	s_nop 0
	v_add_f32_e32 v128, v84, v128
	v_mul_f32_e32 v128, 0xbfb8aa3b, v128
	v_exp_f32_e32 v128, v128
	v_mfma_f32_16x16x32_bf16 v[124:127], v[72:75], v[124:127], 0
	v_add_f32_e32 v129, v85, v129
	v_mul_f32_e32 v129, 0xbfb8aa3b, v129
	v_exp_f32_e32 v129, v129
	s_waitcnt lgkmcnt(0)
	v_mfma_f32_16x16x32_bf16 v[132:135], v[64:67], v[116:119], v[132:135]
	v_add_f32_e32 v130, v86, v130
	v_mul_f32_e32 v130, 0xbfb8aa3b, v130
	v_add_f32_e32 v128, 1.0, v128
	v_mfma_f32_16x16x32_bf16 v[124:127], v[76:79], v[116:119], v[124:127]
	ds_read_b128 v[116:119], v163 offset:21056
	s_nop 2
	v_add_f32_e32 v132, v80, v132
	v_mul_f32_e32 v132, 0xbfb8aa3b, v132
	s_waitcnt lgkmcnt(0)
	v_mfma_f32_16x16x32_bf16 v[136:139], v[64:67], v[116:119], v[136:139]
	v_exp_f32_e32 v132, v132
	v_add_f32_e32 v133, v81, v133
	v_mul_f32_e32 v133, 0xbfb8aa3b, v133
	v_mfma_f32_16x16x32_bf16 v[120:123], v[76:79], v[116:119], v[140:143]
	ds_read_b128 v[116:119], v163 offset:23360
	v_exp_f32_e32 v133, v133
	v_add_f32_e32 v134, v82, v134
	s_waitcnt lgkmcnt(0)
	v_mfma_f32_16x16x32_bf16 v[140:143], v[64:67], v[116:119], v[144:147]
	v_mul_f32_e32 v134, 0xbfb8aa3b, v134
	s_nop 1
	v_mov_b32_e32 v144, s51
	v_mov_b32_e32 v145, s81
	v_cndmask_b32_e32 v144, v144, v145, vcc
	v_lshlrev_b32_e32 v145, 7, v152
	v_and_b32_e32 v145, 0x4000, v145
	v_lshlrev_b32_e32 v146, 8, v162
	v_add3_u32 v144, v144, v145, v146
	v_add_f32_e32 v146, v80, v158
	v_mul_f32_e32 v146, 0xbfb8aa3b, v146
	v_add_f32_e32 v147, v81, v159
	v_exp_f32_e32 v146, v146
	v_mul_f32_e32 v147, 0xbfb8aa3b, v147
	v_exp_f32_e32 v147, v147
	v_lshlrev_b32_e32 v145, 1, v152
	v_and_b32_e32 v145, 0x80, v145
	v_add_f32_e32 v146, 1.0, v146
	v_rcp_f32_e32 v146, v146
	v_add3_u32 v153, v144, v145, v153
	v_add_f32_e32 v144, 1.0, v147
	v_add_f32_e32 v147, v82, v160
	v_mul_f32_e32 v147, 0xbfb8aa3b, v147
	v_mfma_f32_16x16x32_bf16 v[116:119], v[76:79], v[116:119], v[154:157]
	v_rcp_f32_e32 v145, v144
	v_exp_f32_e32 v147, v147
	v_mul_f32_e32 v144, 0xc1000000, v146
	v_add_f32_e32 v154, v83, v161
	v_mul_f32_e32 v154, 0xbfb8aa3b, v154
	v_exp_f32_e32 v154, v154
	s_nop 0
	v_mul_f32_e32 v144, v88, v144
	v_cndmask_b32_e32 v144, v146, v144, vcc
	v_mul_f32_e32 v146, 0xc1000000, v145
	v_add_f32_e32 v147, 1.0, v147
	v_mul_f32_e32 v146, v89, v146
	v_rcp_f32_e32 v147, v147
	v_cndmask_b32_e32 v145, v145, v146, vcc
	v_add_f32_e32 v146, 1.0, v154
	v_rcp_f32_e32 v154, v146
	v_mul_f32_e32 v146, 0xc1000000, v147
	v_add_f32_e32 v132, 1.0, v132
	v_exp_f32_e32 v134, v134
	v_add_f32_e32 v135, v83, v135
	v_mul_f32_e32 v146, v90, v146
	v_rcp_f32_e32 v132, v132
	v_mul_f32_e32 v135, 0xbfb8aa3b, v135
	v_cndmask_b32_e32 v146, v147, v146, vcc
	v_mul_f32_e32 v147, 0xc1000000, v154
	v_add_f32_e32 v133, 1.0, v133
	v_exp_f32_e32 v135, v135
	v_mul_f32_e32 v147, v91, v147
	v_rcp_f32_e32 v133, v133
	v_cndmask_b32_e32 v147, v154, v147, vcc
	v_add_f32_e32 v134, 1.0, v134
	v_add_f32_e32 v136, v80, v136
	ds_write_b128 v153, v[144:147]
	v_mul_f32_e32 v144, 0xc1000000, v132
	v_rcp_f32_e32 v134, v134
	v_mul_f32_e32 v136, 0xbfb8aa3b, v136
	v_mul_f32_e32 v144, v88, v144
	v_add_f32_e32 v135, 1.0, v135
	v_exp_f32_e32 v136, v136
	v_cndmask_b32_e32 v132, v132, v144, vcc
	v_mul_f32_e32 v144, 0xc1000000, v133
	v_rcp_f32_e32 v135, v135
	v_mul_f32_e32 v144, v89, v144
	v_add_f32_e32 v137, v81, v137
	v_cndmask_b32_e32 v133, v133, v144, vcc
	v_mul_f32_e32 v144, 0xc1000000, v134
	v_mul_f32_e32 v137, 0xbfb8aa3b, v137
	v_mul_f32_e32 v144, v90, v144
	v_exp_f32_e32 v137, v137
	v_add_f32_e32 v136, 1.0, v136
	v_cndmask_b32_e32 v134, v134, v144, vcc
	v_mul_f32_e32 v144, 0xc1000000, v135
	v_rcp_f32_e32 v136, v136
	v_mul_f32_e32 v144, v91, v144
	v_cndmask_b32_e32 v135, v135, v144, vcc
	ds_write_b128 v153, v[132:135] offset:4096
	v_add_f32_e32 v132, 1.0, v137
	v_rcp_f32_e32 v133, v132
	v_mul_f32_e32 v132, 0xc1000000, v136
	v_add_f32_e32 v135, v82, v138
	v_mul_f32_e32 v132, v88, v132
	v_mul_f32_e32 v135, 0xbfb8aa3b, v135
	v_cndmask_b32_e32 v132, v136, v132, vcc
	v_exp_f32_e32 v135, v135
	v_add_f32_e32 v136, v83, v139
	v_mul_f32_e32 v136, 0xbfb8aa3b, v136
	v_exp_f32_e32 v136, v136
	v_mul_f32_e32 v134, 0xc1000000, v133
	v_add_f32_e32 v135, 1.0, v135
	v_mul_f32_e32 v134, v89, v134
	v_rcp_f32_e32 v135, v135
	v_cndmask_b32_e32 v133, v133, v134, vcc
	v_add_f32_e32 v134, 1.0, v136
	v_rcp_f32_e32 v136, v134
	v_mul_f32_e32 v134, 0xc1000000, v135
	v_mul_f32_e32 v134, v90, v134
	v_cndmask_b32_e32 v134, v135, v134, vcc
	v_mul_f32_e32 v135, 0xc1000000, v136
	v_mul_f32_e32 v135, v91, v135
	v_cndmask_b32_e32 v135, v136, v135, vcc
	v_add_f32_e32 v136, v80, v140
	v_mul_f32_e32 v136, 0xbfb8aa3b, v136
	v_exp_f32_e32 v136, v136
	v_add_f32_e32 v137, v81, v141
	v_mul_f32_e32 v137, 0xbfb8aa3b, v137
	v_exp_f32_e32 v137, v137
	v_add_f32_e32 v136, 1.0, v136
	v_rcp_f32_e32 v136, v136
	ds_write_b128 v153, v[132:135] offset:8192
	v_add_f32_e32 v132, 1.0, v137
	v_rcp_f32_e32 v133, v132
	v_mul_f32_e32 v132, 0xc1000000, v136
	v_add_f32_e32 v135, v82, v142
	v_mul_f32_e32 v132, v88, v132
	v_mul_f32_e32 v135, 0xbfb8aa3b, v135
	v_cndmask_b32_e32 v132, v136, v132, vcc
	v_exp_f32_e32 v135, v135
	v_add_f32_e32 v136, v83, v143
	v_mul_f32_e32 v136, 0xbfb8aa3b, v136
	v_exp_f32_e32 v136, v136
	v_mul_f32_e32 v134, 0xc1000000, v133
	v_add_f32_e32 v135, 1.0, v135
	v_mul_f32_e32 v134, v89, v134
	v_rcp_f32_e32 v135, v135
	v_cndmask_b32_e32 v133, v133, v134, vcc
	v_add_f32_e32 v134, 1.0, v136
	v_rcp_f32_e32 v136, v134
	v_mul_f32_e32 v134, 0xc1000000, v135
	v_exp_f32_e32 v130, v130
	v_add_f32_e32 v131, v87, v131
	v_mul_f32_e32 v134, v90, v134
	v_rcp_f32_e32 v128, v128
	v_mul_f32_e32 v131, 0xbfb8aa3b, v131
	v_cndmask_b32_e32 v134, v135, v134, vcc
	v_mul_f32_e32 v135, 0xc1000000, v136
	v_add_f32_e32 v129, 1.0, v129
	v_exp_f32_e32 v131, v131
	v_mul_f32_e32 v135, v91, v135
	v_rcp_f32_e32 v129, v129
	v_add_f32_e32 v124, v84, v124
	v_cndmask_b32_e32 v135, v136, v135, vcc
	v_add_f32_e32 v130, 1.0, v130
	v_mul_f32_e32 v124, 0xbfb8aa3b, v124
	ds_write_b128 v153, v[132:135] offset:12288
	v_mul_f32_e32 v132, 0xc1000000, v128
	v_rcp_f32_e32 v130, v130
	v_exp_f32_e32 v124, v124
	v_add_f32_e32 v125, v85, v125
	s_nop 0
	v_mul_f32_e32 v132, v92, v132
	v_add_f32_e32 v131, 1.0, v131
	v_mul_f32_e32 v125, 0xbfb8aa3b, v125
	v_cndmask_b32_e32 v128, v128, v132, vcc
	v_mul_f32_e32 v132, 0xc1000000, v129
	v_rcp_f32_e32 v131, v131
	v_exp_f32_e32 v125, v125
	v_add_f32_e32 v126, v86, v126
	v_mul_f32_e32 v132, v93, v132
	v_mul_f32_e32 v126, 0xbfb8aa3b, v126
	v_cndmask_b32_e32 v129, v129, v132, vcc
	v_mul_f32_e32 v132, 0xc1000000, v130
	v_add_f32_e32 v124, 1.0, v124
	v_exp_f32_e32 v126, v126
	v_add_f32_e32 v127, v87, v127
	v_mul_f32_e32 v132, v94, v132
	v_rcp_f32_e32 v124, v124
	v_mul_f32_e32 v127, 0xbfb8aa3b, v127
	v_cndmask_b32_e32 v130, v130, v132, vcc
	v_mul_f32_e32 v132, 0xc1000000, v131
	v_add_f32_e32 v125, 1.0, v125
	v_exp_f32_e32 v127, v127
	v_mul_f32_e32 v132, v95, v132
	v_rcp_f32_e32 v125, v125
	v_add_f32_e32 v120, v84, v120
	v_cndmask_b32_e32 v131, v131, v132, vcc
	v_add_f32_e32 v126, 1.0, v126
	v_mul_f32_e32 v120, 0xbfb8aa3b, v120
	ds_write_b128 v153, v[128:131] offset:64
	v_mul_f32_e32 v128, 0xc1000000, v124
	v_rcp_f32_e32 v126, v126
	v_exp_f32_e32 v120, v120
	v_add_f32_e32 v121, v85, v121
	v_mul_f32_e32 v128, v92, v128
	v_add_f32_e32 v127, 1.0, v127
	v_mul_f32_e32 v121, 0xbfb8aa3b, v121
	v_cndmask_b32_e32 v124, v124, v128, vcc
	v_mul_f32_e32 v128, 0xc1000000, v125
	v_rcp_f32_e32 v127, v127
	v_exp_f32_e32 v121, v121
	v_add_f32_e32 v122, v86, v122
	v_mul_f32_e32 v128, v93, v128
	v_mul_f32_e32 v122, 0xbfb8aa3b, v122
	v_cndmask_b32_e32 v125, v125, v128, vcc
	v_mul_f32_e32 v128, 0xc1000000, v126
	v_add_f32_e32 v120, 1.0, v120
	v_exp_f32_e32 v122, v122
	v_add_f32_e32 v123, v87, v123
	v_mul_f32_e32 v128, v94, v128
	v_rcp_f32_e32 v120, v120
	v_mul_f32_e32 v123, 0xbfb8aa3b, v123
	v_cndmask_b32_e32 v126, v126, v128, vcc
	v_mul_f32_e32 v128, 0xc1000000, v127
	v_add_f32_e32 v121, 1.0, v121
	v_exp_f32_e32 v123, v123
	v_mul_f32_e32 v128, v95, v128
	v_rcp_f32_e32 v121, v121
	v_add_f32_e32 v116, v84, v116
	v_cndmask_b32_e32 v127, v127, v128, vcc
	v_add_f32_e32 v122, 1.0, v122
	v_mul_f32_e32 v116, 0xbfb8aa3b, v116
	ds_write_b128 v153, v[124:127] offset:4160
	v_mul_f32_e32 v124, 0xc1000000, v120
	v_rcp_f32_e32 v122, v122
	v_exp_f32_e32 v116, v116
	v_add_f32_e32 v117, v85, v117
	v_mul_f32_e32 v124, v92, v124
	v_add_f32_e32 v123, 1.0, v123
	v_mul_f32_e32 v117, 0xbfb8aa3b, v117
	v_cndmask_b32_e32 v120, v120, v124, vcc
	v_mul_f32_e32 v124, 0xc1000000, v121
	v_rcp_f32_e32 v123, v123
	v_exp_f32_e32 v117, v117
	v_add_f32_e32 v118, v86, v118
	v_mul_f32_e32 v124, v93, v124
	v_mul_f32_e32 v118, 0xbfb8aa3b, v118
	v_cndmask_b32_e32 v121, v121, v124, vcc
	v_mul_f32_e32 v124, 0xc1000000, v122
	v_add_f32_e32 v116, 1.0, v116
	v_exp_f32_e32 v118, v118
	v_add_f32_e32 v119, v87, v119
	v_mul_f32_e32 v124, v94, v124
	v_rcp_f32_e32 v116, v116
	v_mul_f32_e32 v119, 0xbfb8aa3b, v119
	v_cndmask_b32_e32 v122, v122, v124, vcc
	v_mul_f32_e32 v124, 0xc1000000, v123
	v_add_f32_e32 v117, 1.0, v117
	v_exp_f32_e32 v119, v119
	v_mul_f32_e32 v124, v95, v124
	v_rcp_f32_e32 v117, v117
	v_cndmask_b32_e32 v123, v123, v124, vcc
	v_add_f32_e32 v118, 1.0, v118
	ds_write_b128 v153, v[120:123] offset:8256
	v_mul_f32_e32 v120, 0xc1000000, v116
	v_rcp_f32_e32 v118, v118
	v_mul_f32_e32 v120, v92, v120
	v_add_f32_e32 v119, 1.0, v119
	v_cndmask_b32_e32 v116, v116, v120, vcc
	v_mul_f32_e32 v120, 0xc1000000, v117
	v_rcp_f32_e32 v119, v119
	v_mul_f32_e32 v120, v93, v120
	v_cndmask_b32_e32 v117, v117, v120, vcc
	v_mul_f32_e32 v120, 0xc1000000, v118
	v_mul_f32_e32 v120, v94, v120
	v_cndmask_b32_e32 v118, v118, v120, vcc
	v_mul_f32_e32 v120, 0xc1000000, v119
	v_mul_f32_e32 v120, v95, v120
	v_cndmask_b32_e32 v119, v119, v120, vcc
	v_lshlrev_b32_e32 v133, 2, v152
	ds_write_b128 v153, v[116:119] offset:12352
	v_and_b32_e32 v116, 60, v133
	v_lshlrev_b32_e32 v132, 2, v116
	v_lshlrev_b32_e32 v116, 4, v152
	v_and_b32_e32 v117, 0xffffc000, v116
	v_add_u32_e32 v117, 0, v117
	v_and_b32_e32 v116, 0x3f00, v116
	v_add3_u32 v135, v117, v116, v132
	s_waitcnt lgkmcnt(0)
	s_barrier
	ds_read_b128 v[128:131], v135 offset:25600
	ds_read_b128 v[120:123], v135 offset:58368
	v_add_u32_e32 v134, 0, v132
	v_add_u32_e32 v136, v134, v116
	ds_read_b128 v[124:127], v136
	s_waitcnt lgkmcnt(2)
	v_mul_f32_e32 v116, 0x3fb8aa3b, v128
	v_exp_f32_e32 v116, v116
	v_add_f32_e32 v117, v128, v128
	v_cmp_nlt_f32_e32 vcc, s79, v117
	s_and_saveexec_b64 s[6:7], vcc
	s_xor_b64 s[6:7], exec, s[6:7]
	v_fma_f32 v128, -v116, v116, 1.0
	s_andn2_saveexec_b64 s[6:7], s[6:7]
	v_fmamk_f32 v118, v117, 0x3c088889, v148
	v_fmaak_f32 v118, v117, v118, 0x3e2aaaab
	v_fma_f32 v118, v117, v118, 0.5
	v_fma_f32 v118, v117, v118, 1.0
	v_mul_f32_e64 v128, v118, -v117
	s_or_b64 exec, exec, s[6:7]
	v_mul_f32_e32 v117, 0x3fb8aa3b, v129
	v_exp_f32_e32 v117, v117
	v_add_f32_e32 v118, v129, v129
	v_cmp_nlt_f32_e32 vcc, s79, v118
	s_and_saveexec_b64 s[6:7], vcc
	s_xor_b64 s[6:7], exec, s[6:7]
	v_fma_f32 v129, -v117, v117, 1.0
	s_andn2_saveexec_b64 s[6:7], s[6:7]
	v_fmamk_f32 v119, v118, 0x3c088889, v148
	v_fmaak_f32 v119, v118, v119, 0x3e2aaaab
	v_fma_f32 v119, v118, v119, 0.5
	v_fma_f32 v119, v118, v119, 1.0
	v_mul_f32_e64 v129, v119, -v118
	s_or_b64 exec, exec, s[6:7]
	v_mul_f32_e32 v118, 0x3fb8aa3b, v130
	v_exp_f32_e32 v118, v118
	v_add_f32_e32 v119, v130, v130
	v_cmp_nlt_f32_e32 vcc, s79, v119
	s_and_saveexec_b64 s[6:7], vcc
	s_xor_b64 s[6:7], exec, s[6:7]
	v_fma_f32 v130, -v118, v118, 1.0
	s_andn2_saveexec_b64 s[6:7], s[6:7]
	v_fmamk_f32 v130, v119, 0x3c088889, v148
	v_fmaak_f32 v130, v119, v130, 0x3e2aaaab
	v_fma_f32 v130, v119, v130, 0.5
	v_fma_f32 v130, v119, v130, 1.0
	v_mul_f32_e64 v130, v130, -v119
	s_or_b64 exec, exec, s[6:7]
	v_mul_f32_e32 v119, 0x3fb8aa3b, v131
	v_exp_f32_e32 v119, v119
	v_add_f32_e32 v137, v131, v131
	v_cmp_nlt_f32_e32 vcc, s79, v137
	s_and_saveexec_b64 s[6:7], vcc
	s_xor_b64 s[6:7], exec, s[6:7]
	v_fma_f32 v131, -v119, v119, 1.0
	s_andn2_saveexec_b64 s[6:7], s[6:7]
	v_fmamk_f32 v131, v137, 0x3c088889, v148
	v_fmaak_f32 v131, v137, v131, 0x3e2aaaab
	v_fma_f32 v131, v137, v131, 0.5
	v_fma_f32 v131, v137, v131, 1.0
	v_mul_f32_e64 v131, v131, -v137
	s_or_b64 exec, exec, s[6:7]
	v_max_f32_e32 v128, v128, v128
	v_max_f32_e32 v128, 0, v128
	v_sqrt_f32_e32 v128, v128
	v_max_f32_e32 v129, v129, v129
	v_max_f32_e32 v129, 0, v129
	v_sqrt_f32_e32 v129, v129
	s_waitcnt lgkmcnt(1)
	v_mul_f32_e32 v120, v120, v128
	s_waitcnt lgkmcnt(0)
	v_mul_f32_e32 v120, v124, v120
	v_max_f32_e32 v124, v130, v130
	v_max_f32_e32 v128, v131, v131
	v_max_f32_e32 v124, 0, v124
	v_max_f32_e32 v128, 0, v128
	v_sqrt_f32_e32 v124, v124
	v_sqrt_f32_e32 v128, v128
	v_mul_f32_e32 v121, v121, v129
	v_mul_f32_e32 v121, v125, v121
	v_mul_f32_e32 v122, v122, v124
	v_mul_f32_e32 v123, v123, v128
	v_mul_f32_e32 v122, v126, v122
	v_mul_f32_e32 v123, v127, v123
	ds_write_b128 v135, v[116:119] offset:25600
	ds_write_b128 v135, v[120:123] offset:58368
	v_add_u32_e32 v116, 0x800, v133
	v_and_b32_e32 v117, 0x3ffff000, v116
	v_and_b32_e32 v116, 0xfc0, v116
	v_lshl_add_u32 v117, v117, 2, 0
	v_lshlrev_b32_e32 v116, 2, v116
	v_add3_u32 v137, v117, v116, v132
	ds_read_b128 v[128:131], v137 offset:25600
	ds_read_b128 v[120:123], v137 offset:58368
	v_add_u32_e32 v116, v134, v116
	ds_read_b128 v[124:127], v116
	s_waitcnt lgkmcnt(2)
	v_mul_f32_e32 v116, 0x3fb8aa3b, v128
	v_exp_f32_e32 v116, v116
	v_add_f32_e32 v117, v128, v128
	v_cmp_nlt_f32_e32 vcc, s79, v117
	s_and_saveexec_b64 s[6:7], vcc
	s_xor_b64 s[6:7], exec, s[6:7]
	v_fma_f32 v128, -v116, v116, 1.0
	s_andn2_saveexec_b64 s[6:7], s[6:7]
	v_fmamk_f32 v118, v117, 0x3c088889, v148
	v_fmaak_f32 v118, v117, v118, 0x3e2aaaab
	v_fma_f32 v118, v117, v118, 0.5
	v_fma_f32 v118, v117, v118, 1.0
	v_mul_f32_e64 v128, v118, -v117
	s_or_b64 exec, exec, s[6:7]
	v_mul_f32_e32 v117, 0x3fb8aa3b, v129
	v_exp_f32_e32 v117, v117
	v_add_f32_e32 v118, v129, v129
	v_cmp_nlt_f32_e32 vcc, s79, v118
	s_and_saveexec_b64 s[6:7], vcc
	s_xor_b64 s[6:7], exec, s[6:7]
	v_fma_f32 v129, -v117, v117, 1.0
	s_andn2_saveexec_b64 s[6:7], s[6:7]
	v_fmamk_f32 v119, v118, 0x3c088889, v148
	v_fmaak_f32 v119, v118, v119, 0x3e2aaaab
	v_fma_f32 v119, v118, v119, 0.5
	v_fma_f32 v119, v118, v119, 1.0
	v_mul_f32_e64 v129, v119, -v118
	s_or_b64 exec, exec, s[6:7]
	v_mul_f32_e32 v118, 0x3fb8aa3b, v130
	v_exp_f32_e32 v118, v118
	v_add_f32_e32 v119, v130, v130
	v_cmp_nlt_f32_e32 vcc, s79, v119
	s_and_saveexec_b64 s[6:7], vcc
	s_xor_b64 s[6:7], exec, s[6:7]
	v_fma_f32 v130, -v118, v118, 1.0
	s_andn2_saveexec_b64 s[6:7], s[6:7]
	v_fmamk_f32 v130, v119, 0x3c088889, v148
	v_fmaak_f32 v130, v119, v130, 0x3e2aaaab
	v_fma_f32 v130, v119, v130, 0.5
	v_fma_f32 v130, v119, v130, 1.0
	v_mul_f32_e64 v130, v130, -v119
	s_or_b64 exec, exec, s[6:7]
	v_mul_f32_e32 v119, 0x3fb8aa3b, v131
	v_exp_f32_e32 v119, v119
	v_add_f32_e32 v138, v131, v131
	v_cmp_nlt_f32_e32 vcc, s79, v138
	s_and_saveexec_b64 s[6:7], vcc
	s_xor_b64 s[6:7], exec, s[6:7]
	v_fma_f32 v131, -v119, v119, 1.0
	s_andn2_saveexec_b64 s[6:7], s[6:7]
	v_fmamk_f32 v131, v138, 0x3c088889, v148
	v_fmaak_f32 v131, v138, v131, 0x3e2aaaab
	v_fma_f32 v131, v138, v131, 0.5
	v_fma_f32 v131, v138, v131, 1.0
	v_mul_f32_e64 v131, v131, -v138
	s_or_b64 exec, exec, s[6:7]
	v_max_f32_e32 v128, v128, v128
	v_max_f32_e32 v128, 0, v128
	v_sqrt_f32_e32 v128, v128
	v_max_f32_e32 v129, v129, v129
	v_max_f32_e32 v129, 0, v129
	v_sqrt_f32_e32 v129, v129
	s_waitcnt lgkmcnt(1)
	v_mul_f32_e32 v120, v120, v128
	s_waitcnt lgkmcnt(0)
	v_mul_f32_e32 v120, v124, v120
	v_max_f32_e32 v124, v130, v130
	v_max_f32_e32 v128, v131, v131
	v_max_f32_e32 v124, 0, v124
	v_max_f32_e32 v128, 0, v128
	v_sqrt_f32_e32 v124, v124
	v_sqrt_f32_e32 v128, v128
	v_mul_f32_e32 v121, v121, v129
	v_mul_f32_e32 v121, v125, v121
	v_mul_f32_e32 v122, v122, v124
	v_mul_f32_e32 v123, v123, v128
	v_mul_f32_e32 v122, v126, v122
	v_mul_f32_e32 v123, v127, v123
	ds_write_b128 v137, v[116:119] offset:25600
	ds_write_b128 v137, v[120:123] offset:58368
	ds_read_b128 v[128:131], v135 offset:41984
	v_add_u32_e32 v137, 0xe400, v135
	ds_read_b128 v[120:123], v137 offset:16384
	ds_read_b128 v[124:127], v136
	s_waitcnt lgkmcnt(2)
	v_mul_f32_e32 v116, 0x3fb8aa3b, v128
	v_exp_f32_e32 v116, v116
	v_add_f32_e32 v117, v128, v128
	v_cmp_nlt_f32_e32 vcc, s79, v117
	s_and_saveexec_b64 s[6:7], vcc
	s_xor_b64 s[6:7], exec, s[6:7]
	v_fma_f32 v128, -v116, v116, 1.0
	s_andn2_saveexec_b64 s[6:7], s[6:7]
	v_fmamk_f32 v118, v117, 0x3c088889, v148
	v_fmaak_f32 v118, v117, v118, 0x3e2aaaab
	v_fma_f32 v118, v117, v118, 0.5
	v_fma_f32 v118, v117, v118, 1.0
	v_mul_f32_e64 v128, v118, -v117
	s_or_b64 exec, exec, s[6:7]
	v_mul_f32_e32 v117, 0x3fb8aa3b, v129
	v_exp_f32_e32 v117, v117
	v_add_f32_e32 v118, v129, v129
	v_cmp_nlt_f32_e32 vcc, s79, v118
	s_and_saveexec_b64 s[6:7], vcc
	s_xor_b64 s[6:7], exec, s[6:7]
	v_fma_f32 v129, -v117, v117, 1.0
	s_andn2_saveexec_b64 s[6:7], s[6:7]
	v_fmamk_f32 v119, v118, 0x3c088889, v148
	v_fmaak_f32 v119, v118, v119, 0x3e2aaaab
	v_fma_f32 v119, v118, v119, 0.5
	v_fma_f32 v119, v118, v119, 1.0
	v_mul_f32_e64 v129, v119, -v118
	s_or_b64 exec, exec, s[6:7]
	v_mul_f32_e32 v118, 0x3fb8aa3b, v130
	v_exp_f32_e32 v118, v118
	v_add_f32_e32 v119, v130, v130
	v_cmp_nlt_f32_e32 vcc, s79, v119
	s_and_saveexec_b64 s[6:7], vcc
	s_xor_b64 s[6:7], exec, s[6:7]
	v_fma_f32 v130, -v118, v118, 1.0
	s_andn2_saveexec_b64 s[6:7], s[6:7]
	v_fmamk_f32 v130, v119, 0x3c088889, v148
	v_fmaak_f32 v130, v119, v130, 0x3e2aaaab
	v_fma_f32 v130, v119, v130, 0.5
	v_fma_f32 v130, v119, v130, 1.0
	v_mul_f32_e64 v130, v130, -v119
	s_or_b64 exec, exec, s[6:7]
	v_mul_f32_e32 v119, 0x3fb8aa3b, v131
	v_exp_f32_e32 v119, v119
	v_add_f32_e32 v136, v131, v131
	v_cmp_nlt_f32_e32 vcc, s79, v136
	s_and_saveexec_b64 s[6:7], vcc
	s_xor_b64 s[6:7], exec, s[6:7]
	v_fma_f32 v131, -v119, v119, 1.0
	s_andn2_saveexec_b64 s[6:7], s[6:7]
	v_fmamk_f32 v131, v136, 0x3c088889, v148
	v_fmaak_f32 v131, v136, v131, 0x3e2aaaab
	v_fma_f32 v131, v136, v131, 0.5
	v_fma_f32 v131, v136, v131, 1.0
	v_mul_f32_e64 v131, v131, -v136
	s_or_b64 exec, exec, s[6:7]
	v_max_f32_e32 v128, v128, v128
	v_max_f32_e32 v128, 0, v128
	v_sqrt_f32_e32 v128, v128
	v_max_f32_e32 v129, v129, v129
	v_max_f32_e32 v129, 0, v129
	v_sqrt_f32_e32 v129, v129
	s_waitcnt lgkmcnt(1)
	v_mul_f32_e32 v120, v120, v128
	s_waitcnt lgkmcnt(0)
	v_mul_f32_e32 v120, v124, v120
	v_max_f32_e32 v124, v130, v130
	v_max_f32_e32 v128, v131, v131
	v_max_f32_e32 v124, 0, v124
	v_max_f32_e32 v128, 0, v128
	v_sqrt_f32_e32 v124, v124
	v_sqrt_f32_e32 v128, v128
	v_mul_f32_e32 v121, v121, v129
	v_mul_f32_e32 v121, v125, v121
	v_mul_f32_e32 v122, v122, v124
	v_mul_f32_e32 v123, v123, v128
	v_mul_f32_e32 v122, v126, v122
	v_mul_f32_e32 v123, v127, v123
	ds_write_b128 v135, v[116:119] offset:41984
	ds_write_b128 v137, v[120:123] offset:16384
	v_add_u32_e32 v116, 0x1800, v133
	v_and_b32_e32 v117, 0x3ffff000, v116
	v_and_b32_e32 v116, 0xfc0, v116
	v_lshl_add_u32 v117, v117, 2, 0
	v_lshlrev_b32_e32 v116, 2, v116
	v_add3_u32 v132, v117, v116, v132
	ds_read_b128 v[128:131], v132 offset:25600
	ds_read_b128 v[120:123], v132 offset:58368
	v_add_u32_e32 v116, v134, v116
	ds_read_b128 v[124:127], v116
	s_waitcnt lgkmcnt(2)
	v_mul_f32_e32 v116, 0x3fb8aa3b, v128
	v_exp_f32_e32 v116, v116
	v_add_f32_e32 v117, v128, v128
	v_cmp_nlt_f32_e32 vcc, s79, v117
	s_and_saveexec_b64 s[6:7], vcc
	s_xor_b64 s[6:7], exec, s[6:7]
	v_fma_f32 v128, -v116, v116, 1.0
	s_andn2_saveexec_b64 s[6:7], s[6:7]
	v_fmamk_f32 v118, v117, 0x3c088889, v148
	v_fmaak_f32 v118, v117, v118, 0x3e2aaaab
	v_fma_f32 v118, v117, v118, 0.5
	v_fma_f32 v118, v117, v118, 1.0
	v_mul_f32_e64 v128, v118, -v117
	s_or_b64 exec, exec, s[6:7]
	v_mul_f32_e32 v117, 0x3fb8aa3b, v129
	v_exp_f32_e32 v117, v117
	v_add_f32_e32 v118, v129, v129
	v_cmp_nlt_f32_e32 vcc, s79, v118
	s_and_saveexec_b64 s[6:7], vcc
	s_xor_b64 s[6:7], exec, s[6:7]
	v_fma_f32 v129, -v117, v117, 1.0
	s_andn2_saveexec_b64 s[6:7], s[6:7]
	v_fmamk_f32 v119, v118, 0x3c088889, v148
	v_fmaak_f32 v119, v118, v119, 0x3e2aaaab
	v_fma_f32 v119, v118, v119, 0.5
	v_fma_f32 v119, v118, v119, 1.0
	v_mul_f32_e64 v129, v119, -v118
	s_or_b64 exec, exec, s[6:7]
	v_mul_f32_e32 v118, 0x3fb8aa3b, v130
	v_exp_f32_e32 v118, v118
	v_add_f32_e32 v119, v130, v130
	v_cmp_nlt_f32_e32 vcc, s79, v119
	s_and_saveexec_b64 s[6:7], vcc
	s_xor_b64 s[6:7], exec, s[6:7]
	v_fma_f32 v130, -v118, v118, 1.0
	s_andn2_saveexec_b64 s[6:7], s[6:7]
	v_fmamk_f32 v130, v119, 0x3c088889, v148
	v_fmaak_f32 v130, v119, v130, 0x3e2aaaab
	v_fma_f32 v130, v119, v130, 0.5
	v_fma_f32 v130, v119, v130, 1.0
	v_mul_f32_e64 v130, v130, -v119
	s_or_b64 exec, exec, s[6:7]
	v_mul_f32_e32 v119, 0x3fb8aa3b, v131
	v_exp_f32_e32 v119, v119
	v_add_f32_e32 v133, v131, v131
	v_cmp_nlt_f32_e32 vcc, s79, v133
	s_and_saveexec_b64 s[6:7], vcc
	s_xor_b64 s[6:7], exec, s[6:7]
	v_fma_f32 v131, -v119, v119, 1.0
	s_andn2_saveexec_b64 s[6:7], s[6:7]
	v_fmamk_f32 v131, v133, 0x3c088889, v148
	v_fmaak_f32 v131, v133, v131, 0x3e2aaaab
	v_fma_f32 v131, v133, v131, 0.5
	v_fma_f32 v131, v133, v131, 1.0
	v_mul_f32_e64 v131, v131, -v133
	s_or_b64 exec, exec, s[6:7]
	v_max_f32_e32 v128, v128, v128
	v_max_f32_e32 v128, 0, v128
	v_sqrt_f32_e32 v128, v128
	v_max_f32_e32 v129, v129, v129
	v_max_f32_e32 v129, 0, v129
	v_sqrt_f32_e32 v129, v129
	s_waitcnt lgkmcnt(1)
	v_mul_f32_e32 v120, v120, v128
	v_max_f32_e32 v128, v130, v130
	s_waitcnt lgkmcnt(0)
	v_mul_f32_e32 v120, v124, v120
	v_max_f32_e32 v124, v131, v131
	v_max_f32_e32 v128, 0, v128
	v_max_f32_e32 v124, 0, v124
	v_sqrt_f32_e32 v128, v128
	v_sqrt_f32_e32 v124, v124
	v_ashrrev_i32_e32 v156, 7, v152
	v_mul_f32_e32 v121, v121, v129
	v_mul_f32_e32 v122, v122, v128
	v_and_b32_e32 v172, 0x7f, v152
	v_mul_f32_e32 v123, v123, v124
	v_lshlrev_b32_e32 v146, 4, v156
	v_mul_f32_e32 v121, v125, v121
	v_mul_f32_e32 v122, v126, v122
	v_bfe_u32 v153, v152, 6, 1
	v_mul_f32_e32 v123, v127, v123
	ds_write_b128 v132, v[116:119] offset:25600
	ds_write_b128 v132, v[120:123] offset:58368
	v_and_b32_e32 v154, 63, v152
	v_sub_u32_e32 v116, 63, v146
	v_cmp_gt_u32_e32 vcc, 64, v172
	v_or_b32_e32 v118, 1, v146
	v_lshl_or_b32 v147, v153, 12, v154
	v_cndmask_b32_e32 v155, v116, v146, vcc
	v_sub_u32_e32 v119, 63, v118
	v_or_b32_e32 v120, 2, v146
	v_lshl_add_u32 v116, v155, 6, v147
	v_cndmask_b32_e32 v157, v119, v118, vcc
	v_sub_u32_e32 v121, 63, v120
	v_or_b32_e32 v122, 3, v146
	v_lshl_add_u32 v116, v116, 2, 0
	v_lshl_add_u32 v118, v157, 6, v147
	v_cndmask_b32_e32 v158, v121, v120, vcc
	v_sub_u32_e32 v123, 63, v122
	v_or_b32_e32 v124, 4, v146
	s_waitcnt lgkmcnt(0)
	s_barrier
	ds_read2st64_b32 v[116:117], v116 offset0:100 offset1:228
	v_lshl_add_u32 v118, v118, 2, 0
	v_lshl_add_u32 v120, v158, 6, v147
	v_cndmask_b32_e32 v159, v123, v122, vcc
	v_sub_u32_e32 v125, 63, v124
	v_or_b32_e32 v126, 5, v146
	ds_read2st64_b32 v[118:119], v118 offset0:100 offset1:228
	v_lshl_add_u32 v120, v120, 2, 0
	v_lshl_add_u32 v122, v159, 6, v147
	v_cndmask_b32_e32 v160, v125, v124, vcc
	v_sub_u32_e32 v127, 63, v126
	v_or_b32_e32 v128, 6, v146
	ds_read2st64_b32 v[120:121], v120 offset0:100 offset1:228
	v_lshl_add_u32 v122, v122, 2, 0
	v_lshl_add_u32 v124, v160, 6, v147
	v_cndmask_b32_e32 v161, v127, v126, vcc
	v_sub_u32_e32 v129, 63, v128
	v_or_b32_e32 v130, 7, v146
	ds_read2st64_b32 v[122:123], v122 offset0:100 offset1:228
	v_lshl_add_u32 v124, v124, 2, 0
	v_lshl_add_u32 v126, v161, 6, v147
	v_cndmask_b32_e32 v162, v129, v128, vcc
	v_sub_u32_e32 v131, 63, v130
	v_or_b32_e32 v132, 8, v146
	ds_read2st64_b32 v[124:125], v124 offset0:100 offset1:228
	v_lshl_add_u32 v126, v126, 2, 0
	v_lshl_add_u32 v128, v162, 6, v147
	v_cndmask_b32_e32 v163, v131, v130, vcc
	v_sub_u32_e32 v133, 63, v132
	v_or_b32_e32 v134, 9, v146
	ds_read2st64_b32 v[126:127], v126 offset0:100 offset1:228
	v_lshl_add_u32 v128, v128, 2, 0
	v_lshl_add_u32 v130, v163, 6, v147
	v_cndmask_b32_e32 v164, v133, v132, vcc
	v_sub_u32_e32 v135, 63, v134
	v_or_b32_e32 v136, 10, v146
	s_waitcnt lgkmcnt(5)
	v_fma_f32 v173, 0, v116, v117
	ds_read2st64_b32 v[128:129], v128 offset0:100 offset1:228
	v_lshl_add_u32 v130, v130, 2, 0
	v_lshl_add_u32 v132, v164, 6, v147
	v_cndmask_b32_e32 v165, v135, v134, vcc
	v_sub_u32_e32 v137, 63, v136
	v_or_b32_e32 v138, 11, v146
	s_waitcnt lgkmcnt(5)
	v_fma_f32 v173, v173, v118, v119
	ds_read2st64_b32 v[130:131], v130 offset0:100 offset1:228
	v_lshl_add_u32 v132, v132, 2, 0
	v_lshl_add_u32 v134, v165, 6, v147
	v_cndmask_b32_e32 v166, v137, v136, vcc
	v_sub_u32_e32 v139, 63, v138
	v_or_b32_e32 v140, 12, v146
	v_mul_f32_e32 v174, v116, v118
	s_waitcnt lgkmcnt(5)
	v_fma_f32 v173, v173, v120, v121
	ds_read2st64_b32 v[132:133], v132 offset0:100 offset1:228
	v_lshl_add_u32 v134, v134, 2, 0
	v_lshl_add_u32 v136, v166, 6, v147
	v_cndmask_b32_e32 v167, v139, v138, vcc
	v_sub_u32_e32 v141, 63, v140
	v_or_b32_e32 v142, 13, v146
	v_mul_f32_e32 v174, v174, v120
	s_waitcnt lgkmcnt(5)
	v_fma_f32 v173, v173, v122, v123
	ds_read2st64_b32 v[134:135], v134 offset0:100 offset1:228
	v_lshl_add_u32 v136, v136, 2, 0
	v_lshl_add_u32 v138, v167, 6, v147
	v_cndmask_b32_e32 v168, v141, v140, vcc
	v_sub_u32_e32 v143, 63, v142
	v_or_b32_e32 v144, 14, v146
	v_mul_f32_e32 v174, v174, v122
	s_waitcnt lgkmcnt(5)
	v_fma_f32 v173, v173, v124, v125
	ds_read2st64_b32 v[136:137], v136 offset0:100 offset1:228
	v_lshl_add_u32 v138, v138, 2, 0
	v_lshl_add_u32 v140, v168, 6, v147
	v_cndmask_b32_e32 v169, v143, v142, vcc
	v_sub_u32_e32 v145, 63, v144
	v_or_b32_e32 v146, 15, v146
	v_mul_f32_e32 v174, v174, v124
	s_waitcnt lgkmcnt(5)
	v_fma_f32 v173, v173, v126, v127
	ds_read2st64_b32 v[138:139], v138 offset0:100 offset1:228
	v_lshl_add_u32 v140, v140, 2, 0
	v_lshl_add_u32 v142, v169, 6, v147
	v_cndmask_b32_e32 v170, v145, v144, vcc
	v_sub_u32_e32 v171, 63, v146
	v_mul_f32_e32 v174, v174, v126
	s_waitcnt lgkmcnt(5)
	v_fma_f32 v173, v173, v128, v129
	ds_read2st64_b32 v[140:141], v140 offset0:100 offset1:228
	v_lshl_add_u32 v142, v142, 2, 0
	v_lshl_add_u32 v144, v170, 6, v147
	v_cndmask_b32_e32 v171, v171, v146, vcc
	v_mul_f32_e32 v174, v174, v128
	s_waitcnt lgkmcnt(5)
	v_fma_f32 v173, v173, v130, v131
	ds_read2st64_b32 v[142:143], v142 offset0:100 offset1:228
	v_lshl_add_u32 v144, v144, 2, 0
	v_lshl_add_u32 v146, v171, 6, v147
	v_mul_f32_e32 v174, v174, v130
	s_waitcnt lgkmcnt(5)
	v_fma_f32 v173, v173, v132, v133
	ds_read2st64_b32 v[144:145], v144 offset0:100 offset1:228
	v_lshl_add_u32 v146, v146, 2, 0
	v_mul_f32_e32 v174, v174, v132
	s_waitcnt lgkmcnt(5)
	v_fma_f32 v173, v173, v134, v135
	ds_read2st64_b32 v[146:147], v146 offset0:100 offset1:228
	v_mul_f32_e32 v174, v174, v134
	s_waitcnt lgkmcnt(5)
	v_fma_f32 v173, v173, v136, v137
	v_mul_f32_e32 v174, v174, v136
	s_waitcnt lgkmcnt(4)
	v_fma_f32 v173, v173, v138, v139
	v_mul_f32_e32 v174, v174, v138
	s_waitcnt lgkmcnt(3)
	v_fma_f32 v173, v173, v140, v141
	v_mul_f32_e32 v174, v174, v140
	s_waitcnt lgkmcnt(2)
	v_fma_f32 v173, v173, v142, v143
	v_mul_f32_e32 v174, v174, v142
	s_waitcnt lgkmcnt(1)
	v_fma_f32 v173, v173, v144, v145
	v_lshl_add_u32 v152, v152, 2, 0
	v_mul_f32_e32 v174, v174, v144
	s_waitcnt lgkmcnt(0)
	v_fma_f32 v173, v173, v146, v147
	v_add_u32_e32 v175, 0x16400, v152
	v_add_u32_e32 v152, 0x16c00, v152
	v_mul_f32_e32 v174, v174, v146
	ds_write_b32 v152, v173
	v_cmp_lt_i32_e32 vcc, 0, v156
	v_lshl_add_u32 v172, v172, 2, 0
	v_mov_b32_e32 v152, v150
	ds_write_b32 v175, v174
	s_waitcnt lgkmcnt(0)
	s_barrier
	s_and_saveexec_b64 s[6:7], vcc
	s_cbranch_execnz .LBB0_774
	s_or_b64 exec, exec, s[6:7]
	v_cmp_lt_i32_e32 vcc, 1, v156
	s_and_saveexec_b64 s[6:7], vcc
	s_cbranch_execnz .LBB0_775
